# combined: + lean epilogue for in-proj L1, residual epilogues with second-half loads hoisted (no atomic deferral), early K/Q issue in dilated attention
# speedup vs baseline: 1.0137x; 1.0007x over previous
.LBB0_454:
	v_lshl_add_u32 v174, s26, 8, v190
	v_lshl_or_b32 v168, s28, 8, v192
	v_ashrrev_i32_e32 v169, 31, v168
	v_ashrrev_i32_e32 v175, 31, v174
	v_lshl_add_u64 v[172:173], v[168:169], 1, s[6:7]
	v_lshlrev_b64 v[112:113], 13, v[174:175]
	v_lshl_add_u64 v[170:171], v[174:175], 3, s[12:13]
	v_lshl_add_u64 v[188:189], v[172:173], 0, v[112:113]
	global_load_dwordx2 v[208:209], v[170:171], off
	global_load_dwordx2 v[232:233], v[170:171], off offset:128
	global_load_dwordx2 v[234:235], v[170:171], off offset:256
	global_load_dwordx2 v[236:237], v[170:171], off offset:384
	global_load_dwordx2 v[238:239], v[170:171], off offset:1024
	global_load_dwordx2 v[240:241], v[170:171], off offset:1152
	global_load_dwordx2 v[242:243], v[170:171], off offset:1280
	global_load_dwordx2 v[244:245], v[170:171], off offset:1408
	global_load_dwordx4 v[200:203], v[188:189], off
	v_or_b32_e32 v184, 16, v174
	v_or_b32_e32 v180, 32, v174
	v_or_b32_e32 v176, 48, v174
	v_ashrrev_i32_e32 v185, 31, v184
	v_ashrrev_i32_e32 v181, 31, v180
	v_ashrrev_i32_e32 v177, 31, v176
	v_lshlrev_b64 v[112:113], 12, v[174:175]
	v_lshlrev_b64 v[114:115], 13, v[184:185]
	v_lshlrev_b64 v[124:125], 13, v[180:181]
	v_lshlrev_b64 v[126:127], 13, v[176:177]
	v_lshl_add_u64 v[112:113], v[112:113], 0, v[168:169]
	v_lshl_add_u64 v[186:187], v[172:173], 0, v[114:115]
	v_lshl_add_u64 v[182:183], v[172:173], 0, v[124:125]
	v_lshl_add_u64 v[178:179], v[172:173], 0, v[126:127]
	v_lshl_add_u64 v[210:211], s[10:11], 0, v[112:113]
	global_load_dwordx4 v[204:207], v[188:189], off offset:256
	global_load_dwordx4 v[148:151], v[186:187], off
	global_load_dwordx4 v[144:147], v[186:187], off offset:256
	global_load_dwordx4 v[140:143], v[182:183], off
	global_load_dwordx4 v[136:139], v[182:183], off offset:256
	global_load_dwordx4 v[124:127], v[178:179], off
	global_load_dwordx4 v[112:115], v[178:179], off offset:256
	s_mov_b64 s[96:97], 0x100000
	v_lshl_add_u64 v[220:221], v[188:189], 0, s[96:97]
	global_load_dwordx4 v[220:223], v[220:221], off
	v_lshl_add_u64 v[224:225], v[188:189], 0, s[96:97]
	global_load_dwordx4 v[224:227], v[224:225], off offset:256
	v_lshl_add_u64 v[228:229], v[186:187], 0, s[96:97]
	global_load_dwordx4 v[228:231], v[228:229], off
	v_lshl_add_u64 v[246:247], v[186:187], 0, s[96:97]
	global_load_dwordx4 v[246:249], v[246:247], off offset:256
	v_lshl_add_u64 v[250:251], v[182:183], 0, s[96:97]
	global_load_dwordx4 v[250:253], v[250:251], off
	v_lshl_add_u64 v[216:217], v[182:183], 0, s[96:97]
	global_load_dwordx4 v[216:219], v[216:217], off offset:256
	s_waitcnt vmcnt(0)
	v_ffbh_u32_e32 v199, v209
	v_min_u32_e32 v199, 32, v199
	v_lshlrev_b64 v[208:209], v199, v[208:209]
	v_min_u32_e32 v208, 1, v208
	v_or_b32_e32 v208, v209, v208
	v_cvt_f32_u32_e32 v208, v208
	v_lshlrev_b32_e32 v212, 16, v200
	v_and_b32_e32 v213, 0xffff0000, v200
	v_lshlrev_b32_e32 v200, 16, v201
	v_and_b32_e32 v201, 0xffff0000, v201
	v_lshlrev_b32_e32 v214, 16, v202
	v_and_b32_e32 v215, 0xffff0000, v202
	v_lshlrev_b32_e32 v202, 16, v203
	v_and_b32_e32 v203, 0xffff0000, v203
	v_pk_add_f32 v[134:135], v[134:135], v[200:201]
	v_pk_add_f32 v[132:133], v[132:133], v[212:213]
	v_pk_add_f32 v[200:201], v[130:131], v[202:203]
	v_pk_add_f32 v[202:203], v[128:129], v[214:215]
	v_sub_u32_e32 v199, 32, v199
	v_cvt_pk_bf16_f32 v128, v132, v133
	v_cvt_pk_bf16_f32 v129, v134, v135
	v_cvt_pk_bf16_f32 v130, v202, v203
	v_cvt_pk_bf16_f32 v131, v200, v201
	global_store_dwordx4 v[188:189], v[128:131], off
	v_mul_f32_e32 v212, v133, v133
	v_mul_f32_e32 v213, v135, v135
	v_ldexp_f32 v128, v208, v199
	v_fmamk_f32 v128, v128, 0x2f800000, v196
	v_rsq_f32_e32 v128, v128
	v_mul_f32_e32 v214, v203, v203
	v_fmac_f32_e32 v212, v132, v132
	v_fmac_f32_e32 v213, v134, v134
	v_fmac_f32_e32 v214, v202, v202
	v_add_f32_e32 v129, v212, v213
	v_mul_f32_e32 v199, 0x41ca3ab3, v128
	v_add_f32_e32 v130, v214, v129
	v_mul_f32_e32 v128, v199, v132
	v_mul_f32_e32 v129, v199, v133
	v_mul_f32_e32 v131, v199, v134
	v_mul_f32_e32 v132, v199, v135
	v_mul_f32_e32 v134, v199, v203
	v_mul_f32_e32 v133, v199, v202
	v_mul_f32_e32 v135, v199, v200
	v_mul_f32_e32 v202, v199, v201
	v_med3_f32 v128, v128, s52, v198
	v_med3_f32 v129, v129, s52, v198
	v_med3_f32 v132, v132, s52, v198
	v_med3_f32 v134, v134, s52, v198
	v_med3_f32 v131, v131, s52, v198
	v_med3_f32 v133, v133, s52, v198
	v_med3_f32 v135, v135, s52, v198
	v_med3_f32 v202, v202, s52, v198
	v_rndne_f32_e32 v128, v128
	v_rndne_f32_e32 v129, v129
	v_rndne_f32_e32 v132, v132
	v_rndne_f32_e32 v134, v134
	v_rndne_f32_e32 v131, v131
	v_rndne_f32_e32 v133, v133
	v_rndne_f32_e32 v135, v135
	v_rndne_f32_e32 v202, v202
	v_cvt_i32_f32_e32 v128, v128
	v_cvt_i32_f32_e32 v129, v129
	v_cvt_i32_f32_e32 v132, v132
	v_cvt_i32_f32_e32 v134, v134
	v_cvt_i32_f32_sdwa v131, v131 dst_sel:WORD_1 dst_unused:UNUSED_PAD src0_sel:DWORD
	v_cvt_i32_f32_e32 v133, v133
	v_cvt_i32_f32_sdwa v135, v135 dst_sel:WORD_1 dst_unused:UNUSED_PAD src0_sel:DWORD
	v_cvt_i32_f32_e32 v202, v202
	v_lshlrev_b32_e32 v129, 8, v129
	v_perm_b32 v128, v132, v128, s53
	v_lshlrev_b32_e32 v132, 8, v134
	v_and_b32_e32 v131, 0xff0000, v131
	v_and_b32_e32 v134, 0xff0000, v135
	v_perm_b32 v133, v202, v133, s53
	v_and_b32_e32 v129, 0xff00, v129
	v_and_b32_e32 v132, 0xff00, v132
	v_or3_b32 v128, v128, v129, v131
	v_or3_b32 v129, v133, v132, v134
	global_store_dwordx2 v[210:211], v[128:129], off
	v_mul_f32_e32 v128, v201, v201
	v_fmac_f32_e32 v128, v200, v200
	v_add_f32_e32 v200, v128, v130
	v_lshlrev_b32_e32 v128, 16, v204
	v_and_b32_e32 v129, 0xffff0000, v204
	v_lshlrev_b32_e32 v130, 16, v205
	v_and_b32_e32 v131, 0xffff0000, v205
	v_lshlrev_b32_e32 v132, 16, v206
	v_and_b32_e32 v133, 0xffff0000, v206
	v_lshlrev_b32_e32 v134, 16, v207
	v_and_b32_e32 v135, 0xffff0000, v207
	v_pk_add_f32 v[122:123], v[122:123], v[130:131]
	v_pk_add_f32 v[120:121], v[120:121], v[128:129]
	v_pk_add_f32 v[130:131], v[116:117], v[132:133]
	v_cvt_pk_bf16_f32 v116, v120, v121
	v_cvt_pk_bf16_f32 v117, v122, v123
	v_pk_add_f32 v[128:129], v[118:119], v[134:135]
	v_cvt_pk_bf16_f32 v118, v130, v131
	s_nop 0
	v_cvt_pk_bf16_f32 v119, v128, v129
	global_store_dwordx4 v[188:189], v[116:119], off offset:256
	s_nop 1
	v_mul_f32_e32 v117, v199, v121
	v_mul_f32_e32 v116, v199, v120
	v_mul_f32_e32 v118, v199, v122
	v_mul_f32_e32 v119, v199, v123
	v_med3_f32 v117, v117, s52, v198
	v_med3_f32 v116, v116, s52, v198
	v_rndne_f32_e32 v117, v117
	v_med3_f32 v118, v118, s52, v198
	v_med3_f32 v119, v119, s52, v198
	v_rndne_f32_e32 v116, v116
	v_cvt_i32_f32_e32 v117, v117
	v_rndne_f32_e32 v118, v118
	v_rndne_f32_e32 v119, v119
	v_cvt_i32_f32_e32 v116, v116
	v_cvt_i32_f32_sdwa v118, v118 dst_sel:WORD_1 dst_unused:UNUSED_PAD src0_sel:DWORD
	v_cvt_i32_f32_e32 v119, v119
	v_lshlrev_b32_e32 v117, 8, v117
	v_and_b32_e32 v117, 0xff00, v117
	v_and_b32_e32 v118, 0xff0000, v118
	v_perm_b32 v116, v119, v116, s53
	v_or3_b32 v132, v116, v117, v118
	v_mul_f32_e32 v117, v199, v131
	v_med3_f32 v117, v117, s52, v198
	v_rndne_f32_e32 v117, v117
	v_cvt_i32_f32_e32 v117, v117
	v_mul_f32_e32 v116, v199, v130
	v_med3_f32 v116, v116, s52, v198
	v_rndne_f32_e32 v116, v116
	v_mul_f32_e32 v118, v199, v128
	v_cvt_i32_f32_e32 v133, v116
	v_lshlrev_b32_e32 v116, 8, v117
	v_and_b32_e32 v134, 0xff00, v116
	v_med3_f32 v116, v118, s52, v198
	v_rndne_f32_e32 v117, v116
	v_mul_f32_e32 v116, v121, v121
	v_mul_f32_e32 v118, v123, v123
	v_fmac_f32_e32 v116, v120, v120
	v_fmac_f32_e32 v118, v122, v122
	v_add_f32_e32 v116, v116, v118
	v_mul_f32_e32 v118, v131, v131
	v_fmac_f32_e32 v118, v130, v130
	v_add_f32_e32 v116, v118, v116
	v_mul_f32_e32 v118, v129, v129
	v_fmac_f32_e32 v118, v128, v128
	v_add_f32_e32 v116, v118, v116
	v_and_b32_e32 v120, 64, v197
	v_add_f32_e32 v118, v200, v116
	v_xor_b32_e32 v116, 16, v197
	v_add_u32_e32 v120, 64, v120
	v_cmp_lt_i32_e32 vcc, v116, v120
	v_mul_f32_e32 v119, v199, v129
	v_cvt_i32_f32_sdwa v122, v117 dst_sel:WORD_1 dst_unused:UNUSED_PAD src0_sel:DWORD
	v_cndmask_b32_e32 v116, v197, v116, vcc
	v_lshlrev_b32_e32 v116, 2, v116
	ds_bpermute_b32 v121, v116, v118
	v_med3_f32 v117, v119, s52, v198
	v_rndne_f32_e32 v117, v117
	v_cvt_i32_f32_e32 v123, v117
	v_xor_b32_e32 v117, 32, v197
	v_cmp_lt_i32_e32 vcc, v117, v120
	s_waitcnt lgkmcnt(0)
	v_add_f32_e32 v118, v118, v121
	v_and_b32_e32 v120, 0xff0000, v122
	v_cndmask_b32_e32 v117, v197, v117, vcc
	v_lshlrev_b32_e32 v117, 2, v117
	ds_bpermute_b32 v119, v117, v118
	v_perm_b32 v121, v123, v133, s53
	v_or3_b32 v133, v121, v134, v120
	global_store_dwordx2 v[210:211], v[132:133], off offset:128
	s_and_saveexec_b64 s[26:27], s[2:3]
	s_cbranch_execz .LBB0_456
	s_waitcnt lgkmcnt(0)
	v_add_f32_e32 v118, v118, v119
	v_fma_f32 v118, v118, s54, 0.5
	v_trunc_f32_e32 v118, v118
	v_mul_f32_e32 v119, 0x2f800000, v118
	v_floor_f32_e32 v119, v119
	v_fmac_f32_e32 v118, 0xcf800000, v119
	v_cvt_u32_f32_e32 v118, v118
	v_cvt_u32_f32_e32 v119, v119
	v_lshl_add_u64 v[120:121], v[174:175], 3, s[8:9]
	global_atomic_add_x2 v[120:121], v[118:119], off
.LBB0_456:
	s_or_b64 exec, exec, s[26:27]
	s_waitcnt lgkmcnt(0)
	v_lshl_add_u64 v[118:119], v[184:185], 3, s[12:13]
	v_mov_b32_e32 v118, v232
	v_mov_b32_e32 v119, v233
	v_lshlrev_b32_e32 v122, 16, v148
	v_and_b32_e32 v123, 0xffff0000, v148
	v_lshlrev_b32_e32 v128, 16, v149
	v_and_b32_e32 v129, 0xffff0000, v149
	v_lshlrev_b32_e32 v148, 16, v146
	v_and_b32_e32 v149, 0xffff0000, v146
	v_lshlrev_b32_e32 v130, 16, v150
	v_and_b32_e32 v131, 0xffff0000, v150
	v_lshlrev_b32_e32 v132, 16, v151
	v_and_b32_e32 v133, 0xffff0000, v151
	v_lshlrev_b32_e32 v146, 16, v147
	v_and_b32_e32 v147, 0xffff0000, v147
	v_pk_add_f32 v[110:111], v[110:111], v[128:129]
	v_pk_add_f32 v[108:109], v[108:109], v[122:123]
	v_pk_add_f32 v[128:129], v[96:97], v[148:149]
	v_cvt_pk_bf16_f32 v96, v108, v109
	v_pk_add_f32 v[106:107], v[106:107], v[132:133]
	v_pk_add_f32 v[104:105], v[104:105], v[130:131]
	v_pk_add_f32 v[122:123], v[98:99], v[146:147]
	v_cvt_pk_bf16_f32 v97, v110, v111
	v_cvt_pk_bf16_f32 v98, v104, v105
	v_cvt_pk_bf16_f32 v99, v106, v107
	global_store_dwordx4 v[186:187], v[96:99], off
	v_mul_f32_e32 v130, v109, v109
	v_mul_f32_e32 v131, v111, v111
	v_mul_f32_e32 v132, v105, v105
	v_fmac_f32_e32 v130, v108, v108
	v_fmac_f32_e32 v131, v110, v110
	v_mul_f32_e32 v133, v107, v107
	v_fmac_f32_e32 v132, v104, v104
	v_fmac_f32_e32 v133, v106, v106
	v_lshlrev_b64 v[120:121], 12, v[184:185]
	v_lshlrev_b32_e32 v134, 16, v144
	v_and_b32_e32 v135, 0xffff0000, v144
	v_lshl_add_u64 v[120:121], v[120:121], 0, v[168:169]
	v_lshlrev_b32_e32 v144, 16, v145
	v_and_b32_e32 v145, 0xffff0000, v145
	v_pk_add_f32 v[100:101], v[100:101], v[134:135]
	v_lshl_add_u64 v[120:121], s[10:11], 0, v[120:121]
	v_pk_add_f32 v[102:103], v[102:103], v[144:145]
	v_ffbh_u32_e32 v96, v119
	v_min_u32_e32 v98, 32, v96
	v_lshlrev_b64 v[96:97], v98, v[118:119]
	v_min_u32_e32 v96, 1, v96
	v_or_b32_e32 v96, v97, v96
	v_cvt_f32_u32_e32 v96, v96
	v_sub_u32_e32 v97, 32, v98
	v_ldexp_f32 v96, v96, v97
	v_fmamk_f32 v96, v96, 0x2f800000, v196
	v_rsq_f32_e32 v96, v96
	v_add_f32_e32 v97, v130, v131
	v_add_f32_e32 v97, v132, v97
	v_add_f32_e32 v118, v133, v97
	v_mul_f32_e32 v119, 0x41ca3ab3, v96
	v_mul_f32_e32 v96, v108, v119
	v_mul_f32_e32 v97, v109, v119
	v_mul_f32_e32 v99, v111, v119
	v_mul_f32_e32 v105, v105, v119
	v_mul_f32_e32 v98, v110, v119
	v_mul_f32_e32 v104, v104, v119
	v_mul_f32_e32 v106, v106, v119
	v_mul_f32_e32 v107, v107, v119
	v_med3_f32 v96, v96, s52, v198
	v_med3_f32 v97, v97, s52, v198
	v_med3_f32 v99, v99, s52, v198
	v_med3_f32 v105, v105, s52, v198
	v_med3_f32 v98, v98, s52, v198
	v_med3_f32 v104, v104, s52, v198
	v_med3_f32 v106, v106, s52, v198
	v_med3_f32 v107, v107, s52, v198
	v_rndne_f32_e32 v96, v96
	v_rndne_f32_e32 v97, v97
	v_rndne_f32_e32 v99, v99
	v_rndne_f32_e32 v105, v105
	v_rndne_f32_e32 v98, v98
	v_rndne_f32_e32 v104, v104
	v_rndne_f32_e32 v106, v106
	v_rndne_f32_e32 v107, v107
	v_cvt_i32_f32_e32 v96, v96
	v_cvt_i32_f32_e32 v97, v97
	v_cvt_i32_f32_e32 v99, v99
	v_cvt_i32_f32_e32 v105, v105
	v_cvt_i32_f32_sdwa v98, v98 dst_sel:WORD_1 dst_unused:UNUSED_PAD src0_sel:DWORD
	v_cvt_i32_f32_e32 v104, v104
	v_cvt_i32_f32_sdwa v106, v106 dst_sel:WORD_1 dst_unused:UNUSED_PAD src0_sel:DWORD
	v_cvt_i32_f32_e32 v107, v107
	v_lshlrev_b32_e32 v97, 8, v97
	v_perm_b32 v96, v99, v96, s53
	v_lshlrev_b32_e32 v99, 8, v105
	v_and_b32_e32 v98, 0xff0000, v98
	v_and_b32_e32 v105, 0xff0000, v106
	v_perm_b32 v104, v107, v104, s53
	v_and_b32_e32 v97, 0xff00, v97
	v_and_b32_e32 v99, 0xff00, v99
	v_or3_b32 v96, v96, v97, v98
	v_or3_b32 v97, v104, v99, v105
	v_mul_f32_e32 v109, v101, v119
	global_store_dwordx2 v[120:121], v[96:97], off
	v_cvt_pk_bf16_f32 v96, v100, v101
	v_cvt_pk_bf16_f32 v97, v102, v103
	v_mul_f32_e32 v108, v100, v119
	v_mul_f32_e32 v110, v102, v119
	v_mul_f32_e32 v111, v103, v119
	v_cvt_pk_bf16_f32 v98, v128, v129
	v_cvt_pk_bf16_f32 v99, v122, v123
	global_store_dwordx4 v[186:187], v[96:99], off offset:256
	v_med3_f32 v108, v108, s52, v198
	v_mul_f32_e32 v104, v123, v119
	v_med3_f32 v97, v109, s52, v198
	v_rndne_f32_e32 v97, v97
	v_med3_f32 v98, v110, s52, v198
	v_med3_f32 v99, v111, s52, v198
	v_rndne_f32_e32 v96, v108
	v_cvt_i32_f32_e32 v97, v97
	v_rndne_f32_e32 v98, v98
	v_rndne_f32_e32 v99, v99
	v_cvt_i32_f32_e32 v96, v96
	v_cvt_i32_f32_sdwa v98, v98 dst_sel:WORD_1 dst_unused:UNUSED_PAD src0_sel:DWORD
	v_cvt_i32_f32_e32 v99, v99
	v_lshlrev_b32_e32 v97, 8, v97
	v_and_b32_e32 v97, 0xff00, v97
	v_and_b32_e32 v98, 0xff0000, v98
	v_perm_b32 v96, v99, v96, s53
	v_or3_b32 v98, v96, v97, v98
	v_mul_f32_e32 v97, v129, v119
	v_med3_f32 v97, v97, s52, v198
	v_rndne_f32_e32 v97, v97
	v_cvt_i32_f32_e32 v97, v97
	v_mul_f32_e32 v96, v128, v119
	v_med3_f32 v96, v96, s52, v198
	v_rndne_f32_e32 v96, v96
	v_mul_f32_e32 v99, v122, v119
	v_cvt_i32_f32_e32 v105, v96
	v_lshlrev_b32_e32 v96, 8, v97
	v_and_b32_e32 v106, 0xff00, v96
	v_med3_f32 v96, v99, s52, v198
	v_mul_f32_e32 v97, v101, v101
	v_mul_f32_e32 v99, v103, v103
	v_fmac_f32_e32 v97, v100, v100
	v_fmac_f32_e32 v99, v102, v102
	v_add_f32_e32 v97, v97, v99
	v_mul_f32_e32 v99, v129, v129
	v_fmac_f32_e32 v99, v128, v128
	v_add_f32_e32 v97, v99, v97
	v_mul_f32_e32 v99, v123, v123
	v_fmac_f32_e32 v99, v122, v122
	v_add_f32_e32 v97, v99, v97
	v_add_f32_e32 v97, v118, v97
	ds_bpermute_b32 v99, v116, v97
	v_rndne_f32_e32 v96, v96
	v_cvt_i32_f32_sdwa v100, v96 dst_sel:WORD_1 dst_unused:UNUSED_PAD src0_sel:DWORD
	v_med3_f32 v96, v104, s52, v198
	v_rndne_f32_e32 v96, v96
	v_cvt_i32_f32_e32 v101, v96
	s_waitcnt lgkmcnt(0)
	v_add_f32_e32 v96, v97, v99
	ds_bpermute_b32 v97, v117, v96
	v_and_b32_e32 v99, 0xff0000, v100
	v_perm_b32 v100, v101, v105, s53
	v_or3_b32 v99, v100, v106, v99
	global_store_dwordx2 v[120:121], v[98:99], off offset:128
	s_and_saveexec_b64 s[26:27], s[2:3]
	s_cbranch_execz .LBB0_458
	s_waitcnt lgkmcnt(0)
	v_add_f32_e32 v96, v96, v97
	v_fma_f32 v96, v96, s54, 0.5
	v_trunc_f32_e32 v96, v96
	v_mul_f32_e32 v97, 0x2f800000, v96
	v_floor_f32_e32 v97, v97
	v_fmac_f32_e32 v96, 0xcf800000, v97
	v_cvt_u32_f32_e32 v96, v96
	v_cvt_u32_f32_e32 v97, v97
	v_lshl_add_u64 v[98:99], v[184:185], 3, s[8:9]
	global_atomic_add_x2 v[98:99], v[96:97], off
.LBB0_458:
	s_or_b64 exec, exec, s[26:27]
	s_waitcnt lgkmcnt(0)
	v_lshl_add_u64 v[96:97], v[180:181], 3, s[12:13]
	v_mov_b32_e32 v96, v234
	v_mov_b32_e32 v97, v235
	v_lshlrev_b32_e32 v100, 16, v140
	v_and_b32_e32 v101, 0xffff0000, v140
	v_lshlrev_b32_e32 v102, 16, v141
	v_and_b32_e32 v103, 0xffff0000, v141
	v_lshlrev_b32_e32 v118, 16, v138
	v_and_b32_e32 v119, 0xffff0000, v138
	v_lshlrev_b32_e32 v104, 16, v142
	v_and_b32_e32 v105, 0xffff0000, v142
	v_lshlrev_b32_e32 v106, 16, v143
	v_and_b32_e32 v107, 0xffff0000, v143
	v_lshlrev_b32_e32 v120, 16, v139
	v_and_b32_e32 v121, 0xffff0000, v139
	v_pk_add_f32 v[94:95], v[94:95], v[102:103]
	v_pk_add_f32 v[92:93], v[92:93], v[100:101]
	v_pk_add_f32 v[102:103], v[80:81], v[118:119]
	v_cvt_pk_bf16_f32 v80, v92, v93
	v_pk_add_f32 v[90:91], v[90:91], v[106:107]
	v_pk_add_f32 v[88:89], v[88:89], v[104:105]
	v_pk_add_f32 v[100:101], v[82:83], v[120:121]
	v_cvt_pk_bf16_f32 v81, v94, v95
	v_cvt_pk_bf16_f32 v82, v88, v89
	v_cvt_pk_bf16_f32 v83, v90, v91
	global_store_dwordx4 v[182:183], v[80:83], off
	v_mul_f32_e32 v104, v93, v93
	v_mul_f32_e32 v105, v95, v95
	v_mul_f32_e32 v106, v89, v89
	v_fmac_f32_e32 v104, v92, v92
	v_fmac_f32_e32 v105, v94, v94
	v_mul_f32_e32 v107, v91, v91
	v_fmac_f32_e32 v106, v88, v88
	v_fmac_f32_e32 v107, v90, v90
	v_lshlrev_b64 v[98:99], 12, v[180:181]
	v_lshlrev_b32_e32 v108, 16, v136
	v_and_b32_e32 v109, 0xffff0000, v136
	v_lshl_add_u64 v[98:99], v[98:99], 0, v[168:169]
	v_lshlrev_b32_e32 v110, 16, v137
	v_and_b32_e32 v111, 0xffff0000, v137
	v_pk_add_f32 v[84:85], v[84:85], v[108:109]
	v_lshl_add_u64 v[98:99], s[10:11], 0, v[98:99]
	v_pk_add_f32 v[86:87], v[86:87], v[110:111]
	v_ffbh_u32_e32 v80, v97
	v_min_u32_e32 v82, 32, v80
	v_lshlrev_b64 v[80:81], v82, v[96:97]
	v_min_u32_e32 v80, 1, v80
	v_or_b32_e32 v80, v81, v80
	v_cvt_f32_u32_e32 v80, v80
	v_sub_u32_e32 v81, 32, v82
	v_ldexp_f32 v80, v80, v81
	v_fmamk_f32 v80, v80, 0x2f800000, v196
	v_rsq_f32_e32 v80, v80
	v_add_f32_e32 v81, v104, v105
	v_add_f32_e32 v81, v106, v81
	v_add_f32_e32 v96, v107, v81
	v_mul_f32_e32 v97, 0x41ca3ab3, v80
	v_mul_f32_e32 v80, v92, v97
	v_mul_f32_e32 v81, v93, v97
	v_mul_f32_e32 v83, v95, v97
	v_mul_f32_e32 v89, v89, v97
	v_mul_f32_e32 v82, v94, v97
	v_mul_f32_e32 v88, v88, v97
	v_mul_f32_e32 v90, v90, v97
	v_mul_f32_e32 v91, v91, v97
	v_med3_f32 v80, v80, s52, v198
	v_med3_f32 v81, v81, s52, v198
	v_med3_f32 v83, v83, s52, v198
	v_med3_f32 v89, v89, s52, v198
	v_med3_f32 v82, v82, s52, v198
	v_med3_f32 v88, v88, s52, v198
	v_med3_f32 v90, v90, s52, v198
	v_med3_f32 v91, v91, s52, v198
	v_rndne_f32_e32 v80, v80
	v_rndne_f32_e32 v81, v81
	v_rndne_f32_e32 v83, v83
	v_rndne_f32_e32 v89, v89
	v_rndne_f32_e32 v82, v82
	v_rndne_f32_e32 v88, v88
	v_rndne_f32_e32 v90, v90
	v_rndne_f32_e32 v91, v91
	v_cvt_i32_f32_e32 v80, v80
	v_cvt_i32_f32_e32 v81, v81
	v_cvt_i32_f32_e32 v83, v83
	v_cvt_i32_f32_e32 v89, v89
	v_cvt_i32_f32_sdwa v82, v82 dst_sel:WORD_1 dst_unused:UNUSED_PAD src0_sel:DWORD
	v_cvt_i32_f32_e32 v88, v88
	v_cvt_i32_f32_sdwa v90, v90 dst_sel:WORD_1 dst_unused:UNUSED_PAD src0_sel:DWORD
	v_cvt_i32_f32_e32 v91, v91
	v_lshlrev_b32_e32 v81, 8, v81
	v_perm_b32 v80, v83, v80, s53
	v_lshlrev_b32_e32 v83, 8, v89
	v_and_b32_e32 v82, 0xff0000, v82
	v_and_b32_e32 v89, 0xff0000, v90
	v_perm_b32 v88, v91, v88, s53
	v_and_b32_e32 v81, 0xff00, v81
	v_and_b32_e32 v83, 0xff00, v83
	v_or3_b32 v80, v80, v81, v82
	v_or3_b32 v81, v88, v83, v89
	v_mul_f32_e32 v93, v85, v97
	global_store_dwordx2 v[98:99], v[80:81], off
	v_cvt_pk_bf16_f32 v80, v84, v85
	v_cvt_pk_bf16_f32 v81, v86, v87
	v_mul_f32_e32 v92, v84, v97
	v_mul_f32_e32 v94, v86, v97
	v_mul_f32_e32 v95, v87, v97
	v_cvt_pk_bf16_f32 v82, v102, v103
	v_cvt_pk_bf16_f32 v83, v100, v101
	global_store_dwordx4 v[182:183], v[80:83], off offset:256
	v_med3_f32 v92, v92, s52, v198
	v_mul_f32_e32 v88, v101, v97
	v_med3_f32 v81, v93, s52, v198
	v_rndne_f32_e32 v81, v81
	v_med3_f32 v82, v94, s52, v198
	v_med3_f32 v83, v95, s52, v198
	v_rndne_f32_e32 v80, v92
	v_cvt_i32_f32_e32 v81, v81
	v_rndne_f32_e32 v82, v82
	v_rndne_f32_e32 v83, v83
	v_cvt_i32_f32_e32 v80, v80
	v_cvt_i32_f32_sdwa v82, v82 dst_sel:WORD_1 dst_unused:UNUSED_PAD src0_sel:DWORD
	v_cvt_i32_f32_e32 v83, v83
	v_lshlrev_b32_e32 v81, 8, v81
	v_and_b32_e32 v81, 0xff00, v81
	v_and_b32_e32 v82, 0xff0000, v82
	v_perm_b32 v80, v83, v80, s53
	v_or3_b32 v82, v80, v81, v82
	v_mul_f32_e32 v81, v103, v97
	v_med3_f32 v81, v81, s52, v198
	v_rndne_f32_e32 v81, v81
	v_cvt_i32_f32_e32 v81, v81
	v_mul_f32_e32 v80, v102, v97
	v_med3_f32 v80, v80, s52, v198
	v_rndne_f32_e32 v80, v80
	v_mul_f32_e32 v83, v100, v97
	v_cvt_i32_f32_e32 v89, v80
	v_lshlrev_b32_e32 v80, 8, v81
	v_and_b32_e32 v90, 0xff00, v80
	v_med3_f32 v80, v83, s52, v198
	v_mul_f32_e32 v81, v85, v85
	v_mul_f32_e32 v83, v87, v87
	v_fmac_f32_e32 v81, v84, v84
	v_fmac_f32_e32 v83, v86, v86
	v_add_f32_e32 v81, v81, v83
	v_mul_f32_e32 v83, v103, v103
	v_fmac_f32_e32 v83, v102, v102
	v_add_f32_e32 v81, v83, v81
	v_mul_f32_e32 v83, v101, v101
	v_fmac_f32_e32 v83, v100, v100
	v_add_f32_e32 v81, v83, v81
	v_add_f32_e32 v81, v96, v81
	ds_bpermute_b32 v83, v116, v81
	v_rndne_f32_e32 v80, v80
	v_cvt_i32_f32_sdwa v84, v80 dst_sel:WORD_1 dst_unused:UNUSED_PAD src0_sel:DWORD
	v_med3_f32 v80, v88, s52, v198
	v_rndne_f32_e32 v80, v80
	v_cvt_i32_f32_e32 v85, v80
	s_waitcnt lgkmcnt(0)
	v_add_f32_e32 v80, v81, v83
	ds_bpermute_b32 v81, v117, v80
	v_and_b32_e32 v83, 0xff0000, v84
	v_perm_b32 v84, v85, v89, s53
	v_or3_b32 v83, v84, v90, v83
	global_store_dwordx2 v[98:99], v[82:83], off offset:128
	s_and_saveexec_b64 s[26:27], s[2:3]
	s_cbranch_execz .LBB0_460
	s_waitcnt lgkmcnt(0)
	v_add_f32_e32 v80, v80, v81
	v_fma_f32 v80, v80, s54, 0.5
	v_trunc_f32_e32 v80, v80
	v_mul_f32_e32 v81, 0x2f800000, v80
	v_floor_f32_e32 v81, v81
	v_fmac_f32_e32 v80, 0xcf800000, v81
	v_cvt_u32_f32_e32 v80, v80
	v_cvt_u32_f32_e32 v81, v81
	v_lshl_add_u64 v[82:83], v[180:181], 3, s[8:9]
	global_atomic_add_x2 v[82:83], v[80:81], off
.LBB0_460:
	s_or_b64 exec, exec, s[26:27]
	s_waitcnt lgkmcnt(0)
	v_lshl_add_u64 v[80:81], v[176:177], 3, s[12:13]
	v_mov_b32_e32 v80, v236
	v_mov_b32_e32 v81, v237
	v_lshlrev_b32_e32 v84, 16, v124
	v_and_b32_e32 v85, 0xffff0000, v124
	v_lshlrev_b32_e32 v86, 16, v125
	v_and_b32_e32 v87, 0xffff0000, v125
	v_lshlrev_b32_e32 v96, 16, v114
	v_and_b32_e32 v97, 0xffff0000, v114
	v_lshlrev_b32_e32 v88, 16, v126
	v_and_b32_e32 v89, 0xffff0000, v126
	v_lshlrev_b32_e32 v90, 16, v127
	v_and_b32_e32 v91, 0xffff0000, v127
	v_lshlrev_b32_e32 v98, 16, v115
	v_and_b32_e32 v99, 0xffff0000, v115
	v_pk_add_f32 v[78:79], v[78:79], v[86:87]
	v_pk_add_f32 v[76:77], v[76:77], v[84:85]
	v_pk_add_f32 v[86:87], v[64:65], v[96:97]
	v_cvt_pk_bf16_f32 v64, v76, v77
	v_pk_add_f32 v[74:75], v[74:75], v[90:91]
	v_pk_add_f32 v[72:73], v[72:73], v[88:89]
	v_pk_add_f32 v[84:85], v[66:67], v[98:99]
	v_cvt_pk_bf16_f32 v65, v78, v79
	v_cvt_pk_bf16_f32 v66, v72, v73
	v_cvt_pk_bf16_f32 v67, v74, v75
	global_store_dwordx4 v[178:179], v[64:67], off
	v_mul_f32_e32 v88, v77, v77
	v_mul_f32_e32 v89, v79, v79
	v_mul_f32_e32 v90, v73, v73
	v_fmac_f32_e32 v88, v76, v76
	v_fmac_f32_e32 v89, v78, v78
	v_mul_f32_e32 v91, v75, v75
	v_fmac_f32_e32 v90, v72, v72
	v_fmac_f32_e32 v91, v74, v74
	v_lshlrev_b64 v[82:83], 12, v[176:177]
	v_lshlrev_b32_e32 v92, 16, v112
	v_and_b32_e32 v93, 0xffff0000, v112
	v_lshl_add_u64 v[82:83], v[82:83], 0, v[168:169]
	v_lshlrev_b32_e32 v94, 16, v113
	v_and_b32_e32 v95, 0xffff0000, v113
	v_pk_add_f32 v[68:69], v[68:69], v[92:93]
	v_lshl_add_u64 v[82:83], s[10:11], 0, v[82:83]
	v_pk_add_f32 v[70:71], v[70:71], v[94:95]
	v_ffbh_u32_e32 v64, v81
	v_min_u32_e32 v66, 32, v64
	v_lshlrev_b64 v[64:65], v66, v[80:81]
	v_min_u32_e32 v64, 1, v64
	v_or_b32_e32 v64, v65, v64
	v_cvt_f32_u32_e32 v64, v64
	v_sub_u32_e32 v65, 32, v66
	v_ldexp_f32 v64, v64, v65
	v_fmamk_f32 v64, v64, 0x2f800000, v196
	v_rsq_f32_e32 v64, v64
	v_add_f32_e32 v65, v88, v89
	v_add_f32_e32 v65, v90, v65
	v_add_f32_e32 v80, v91, v65
	v_mul_f32_e32 v81, 0x41ca3ab3, v64
	v_mul_f32_e32 v64, v76, v81
	v_mul_f32_e32 v65, v77, v81
	v_mul_f32_e32 v67, v79, v81
	v_mul_f32_e32 v73, v73, v81
	v_mul_f32_e32 v66, v78, v81
	v_mul_f32_e32 v72, v72, v81
	v_mul_f32_e32 v74, v74, v81
	v_mul_f32_e32 v75, v75, v81
	v_med3_f32 v64, v64, s52, v198
	v_med3_f32 v65, v65, s52, v198
	v_med3_f32 v67, v67, s52, v198
	v_med3_f32 v73, v73, s52, v198
	v_med3_f32 v66, v66, s52, v198
	v_med3_f32 v72, v72, s52, v198
	v_med3_f32 v74, v74, s52, v198
	v_med3_f32 v75, v75, s52, v198
	v_rndne_f32_e32 v64, v64
	v_rndne_f32_e32 v65, v65
	v_rndne_f32_e32 v67, v67
	v_rndne_f32_e32 v73, v73
	v_rndne_f32_e32 v66, v66
	v_rndne_f32_e32 v72, v72
	v_rndne_f32_e32 v74, v74
	v_rndne_f32_e32 v75, v75
	v_cvt_i32_f32_e32 v64, v64
	v_cvt_i32_f32_e32 v65, v65
	v_cvt_i32_f32_e32 v67, v67
	v_cvt_i32_f32_e32 v73, v73
	v_cvt_i32_f32_sdwa v66, v66 dst_sel:WORD_1 dst_unused:UNUSED_PAD src0_sel:DWORD
	v_cvt_i32_f32_e32 v72, v72
	v_cvt_i32_f32_sdwa v74, v74 dst_sel:WORD_1 dst_unused:UNUSED_PAD src0_sel:DWORD
	v_cvt_i32_f32_e32 v75, v75
	v_lshlrev_b32_e32 v65, 8, v65
	v_perm_b32 v64, v67, v64, s53
	v_lshlrev_b32_e32 v67, 8, v73
	v_and_b32_e32 v66, 0xff0000, v66
	v_and_b32_e32 v73, 0xff0000, v74
	v_perm_b32 v72, v75, v72, s53
	v_and_b32_e32 v65, 0xff00, v65
	v_and_b32_e32 v67, 0xff00, v67
	v_or3_b32 v64, v64, v65, v66
	v_or3_b32 v65, v72, v67, v73
	v_mul_f32_e32 v77, v69, v81
	global_store_dwordx2 v[82:83], v[64:65], off
	v_cvt_pk_bf16_f32 v64, v68, v69
	v_cvt_pk_bf16_f32 v65, v70, v71
	v_mul_f32_e32 v76, v68, v81
	v_mul_f32_e32 v78, v70, v81
	v_mul_f32_e32 v79, v71, v81
	v_cvt_pk_bf16_f32 v66, v86, v87
	v_cvt_pk_bf16_f32 v67, v84, v85
	global_store_dwordx4 v[178:179], v[64:67], off offset:256
	v_med3_f32 v76, v76, s52, v198
	v_mul_f32_e32 v72, v85, v81
	v_med3_f32 v65, v77, s52, v198
	v_rndne_f32_e32 v65, v65
	v_med3_f32 v66, v78, s52, v198
	v_med3_f32 v67, v79, s52, v198
	v_rndne_f32_e32 v64, v76
	v_cvt_i32_f32_e32 v65, v65
	v_rndne_f32_e32 v66, v66
	v_rndne_f32_e32 v67, v67
	v_cvt_i32_f32_e32 v64, v64
	v_cvt_i32_f32_sdwa v66, v66 dst_sel:WORD_1 dst_unused:UNUSED_PAD src0_sel:DWORD
	v_cvt_i32_f32_e32 v67, v67
	v_lshlrev_b32_e32 v65, 8, v65
	v_and_b32_e32 v65, 0xff00, v65
	v_and_b32_e32 v66, 0xff0000, v66
	v_perm_b32 v64, v67, v64, s53
	v_or3_b32 v66, v64, v65, v66
	v_mul_f32_e32 v65, v87, v81
	v_med3_f32 v65, v65, s52, v198
	v_rndne_f32_e32 v65, v65
	v_cvt_i32_f32_e32 v65, v65
	v_mul_f32_e32 v64, v86, v81
	v_med3_f32 v64, v64, s52, v198
	v_rndne_f32_e32 v64, v64
	v_mul_f32_e32 v67, v84, v81
	v_cvt_i32_f32_e32 v73, v64
	v_lshlrev_b32_e32 v64, 8, v65
	v_and_b32_e32 v74, 0xff00, v64
	v_med3_f32 v64, v67, s52, v198
	v_mul_f32_e32 v65, v69, v69
	v_mul_f32_e32 v67, v71, v71
	v_fmac_f32_e32 v65, v68, v68
	v_fmac_f32_e32 v67, v70, v70
	v_add_f32_e32 v65, v65, v67
	v_mul_f32_e32 v67, v87, v87
	v_fmac_f32_e32 v67, v86, v86
	v_add_f32_e32 v65, v67, v65
	v_mul_f32_e32 v67, v85, v85
	v_fmac_f32_e32 v67, v84, v84
	v_add_f32_e32 v65, v67, v65
	v_add_f32_e32 v65, v80, v65
	ds_bpermute_b32 v67, v116, v65
	v_rndne_f32_e32 v64, v64
	v_cvt_i32_f32_sdwa v68, v64 dst_sel:WORD_1 dst_unused:UNUSED_PAD src0_sel:DWORD
	v_med3_f32 v64, v72, s52, v198
	v_rndne_f32_e32 v64, v64
	v_cvt_i32_f32_e32 v69, v64
	s_waitcnt lgkmcnt(0)
	v_add_f32_e32 v64, v65, v67
	ds_bpermute_b32 v65, v117, v64
	v_and_b32_e32 v67, 0xff0000, v68
	v_perm_b32 v68, v69, v73, s53
	v_or3_b32 v67, v68, v74, v67
	global_store_dwordx2 v[82:83], v[66:67], off offset:128
	s_and_saveexec_b64 s[26:27], s[2:3]
	s_cbranch_execz .LBB0_462
	s_waitcnt lgkmcnt(0)
	v_add_f32_e32 v64, v64, v65
	v_fma_f32 v64, v64, s54, 0.5
	v_trunc_f32_e32 v64, v64
	v_mul_f32_e32 v65, 0x2f800000, v64
	v_floor_f32_e32 v65, v65
	v_fmac_f32_e32 v64, 0xcf800000, v65
	v_cvt_u32_f32_e32 v64, v64
	v_cvt_u32_f32_e32 v65, v65
	v_lshl_add_u64 v[66:67], v[176:177], 3, s[8:9]
	global_atomic_add_x2 v[66:67], v[64:65], off
.LBB0_462:
	s_or_b64 exec, exec, s[26:27]
	v_add_u32_e32 v100, 0x80, v174
	v_ashrrev_i32_e32 v101, 31, v100
	s_waitcnt lgkmcnt(0)
	v_lshlrev_b64 v[64:65], 13, v[100:101]
	v_lshl_add_u64 v[102:103], v[172:173], 0, v[64:65]
	v_mov_b32_e32 v112, v238
	v_mov_b32_e32 v113, v239
	v_mov_b32_e32 v104, v220
	v_mov_b32_e32 v105, v221
	v_mov_b32_e32 v106, v222
	v_mov_b32_e32 v107, v223
	v_add_u32_e32 v96, 0x90, v174
	v_add_u32_e32 v92, 0xa0, v174
	v_add_u32_e32 v88, 0xb0, v174
	v_ashrrev_i32_e32 v97, 31, v96
	v_ashrrev_i32_e32 v93, 31, v92
	v_ashrrev_i32_e32 v89, 31, v88
	v_lshlrev_b64 v[64:65], 13, v[96:97]
	v_lshlrev_b64 v[66:67], 13, v[92:93]
	v_lshlrev_b64 v[68:69], 13, v[88:89]
	v_lshlrev_b64 v[70:71], 12, v[100:101]
	v_lshl_add_u64 v[98:99], v[172:173], 0, v[64:65]
	v_lshl_add_u64 v[94:95], v[172:173], 0, v[66:67]
	v_lshl_add_u64 v[90:91], v[172:173], 0, v[68:69]
	v_lshl_add_u64 v[114:115], v[70:71], 0, v[168:169]
	v_mov_b32_e32 v108, v224
	v_mov_b32_e32 v109, v225
	v_mov_b32_e32 v110, v226
	v_mov_b32_e32 v111, v227
	v_mov_b32_e32 v84, v228
	v_mov_b32_e32 v85, v229
	v_mov_b32_e32 v86, v230
	v_mov_b32_e32 v87, v231
	v_mov_b32_e32 v80, v246
	v_mov_b32_e32 v81, v247
	v_mov_b32_e32 v82, v248
	v_mov_b32_e32 v83, v249
	v_mov_b32_e32 v76, v250
	v_mov_b32_e32 v77, v251
	v_mov_b32_e32 v78, v252
	v_mov_b32_e32 v79, v253
	v_mov_b32_e32 v72, v216
	v_mov_b32_e32 v73, v217
	v_mov_b32_e32 v74, v218
	v_mov_b32_e32 v75, v219
	global_load_dwordx4 v[68:71], v[90:91], off
	global_load_dwordx4 v[64:67], v[90:91], off offset:256
	v_lshl_add_u64 v[114:115], s[10:11], 0, v[114:115]
	v_ffbh_u32_e32 v122, v113
	v_min_u32_e32 v122, 32, v122
	v_lshlrev_b32_e32 v118, 16, v104
	v_and_b32_e32 v119, 0xffff0000, v104
	v_lshlrev_b32_e32 v104, 16, v105
	v_and_b32_e32 v105, 0xffff0000, v105
	v_lshlrev_b32_e32 v120, 16, v106
	v_and_b32_e32 v121, 0xffff0000, v106
	v_lshlrev_b32_e32 v106, 16, v107
	v_and_b32_e32 v107, 0xffff0000, v107
	v_lshlrev_b64 v[112:113], v122, v[112:113]
	v_pk_add_f32 v[62:63], v[62:63], v[104:105]
	v_pk_add_f32 v[60:61], v[60:61], v[118:119]
	v_pk_add_f32 v[104:105], v[58:59], v[106:107]
	v_pk_add_f32 v[106:107], v[56:57], v[120:121]
	v_cvt_pk_bf16_f32 v56, v60, v61
	v_min_u32_e32 v112, 1, v112
	v_cvt_pk_bf16_f32 v57, v62, v63
	v_cvt_pk_bf16_f32 v58, v106, v107
	v_cvt_pk_bf16_f32 v59, v104, v105
	global_store_dwordx4 v[102:103], v[56:59], off
	v_sub_u32_e32 v118, 32, v122
	v_mul_f32_e32 v119, v61, v61
	v_or_b32_e32 v56, v113, v112
	v_cvt_f32_u32_e32 v56, v56
	v_mul_f32_e32 v120, v63, v63
	v_mul_f32_e32 v121, v107, v107
	v_fmac_f32_e32 v119, v60, v60
	v_ldexp_f32 v56, v56, v118
	v_fmamk_f32 v56, v56, 0x2f800000, v196
	v_rsq_f32_e32 v56, v56
	v_fmac_f32_e32 v120, v62, v62
	v_mul_f32_e32 v122, v105, v105
	v_fmac_f32_e32 v121, v106, v106
	v_add_f32_e32 v57, v119, v120
	v_fmac_f32_e32 v122, v104, v104
	v_add_f32_e32 v57, v121, v57
	v_mul_f32_e32 v113, 0x41ca3ab3, v56
	v_add_f32_e32 v112, v122, v57
	v_mul_f32_e32 v56, v113, v60
	v_mul_f32_e32 v57, v113, v61
	v_mul_f32_e32 v59, v113, v63
	v_mul_f32_e32 v61, v113, v107
	v_mul_f32_e32 v58, v113, v62
	v_mul_f32_e32 v60, v113, v106
	v_mul_f32_e32 v62, v113, v104
	v_mul_f32_e32 v63, v113, v105
	v_med3_f32 v56, v56, s52, v198
	v_med3_f32 v57, v57, s52, v198
	v_med3_f32 v59, v59, s52, v198
	v_med3_f32 v61, v61, s52, v198
	v_med3_f32 v58, v58, s52, v198
	v_med3_f32 v60, v60, s52, v198
	v_med3_f32 v62, v62, s52, v198
	v_med3_f32 v63, v63, s52, v198
	v_rndne_f32_e32 v56, v56
	v_rndne_f32_e32 v57, v57
	v_rndne_f32_e32 v59, v59
	v_rndne_f32_e32 v61, v61
	v_rndne_f32_e32 v58, v58
	v_rndne_f32_e32 v60, v60
	v_rndne_f32_e32 v62, v62
	v_rndne_f32_e32 v63, v63
	v_cvt_i32_f32_e32 v56, v56
	v_cvt_i32_f32_e32 v57, v57
	v_cvt_i32_f32_e32 v59, v59
	v_cvt_i32_f32_e32 v61, v61
	v_cvt_i32_f32_sdwa v58, v58 dst_sel:WORD_1 dst_unused:UNUSED_PAD src0_sel:DWORD
	v_cvt_i32_f32_e32 v60, v60
	v_cvt_i32_f32_sdwa v62, v62 dst_sel:WORD_1 dst_unused:UNUSED_PAD src0_sel:DWORD
	v_cvt_i32_f32_e32 v63, v63
	v_lshlrev_b32_e32 v57, 8, v57
	v_perm_b32 v56, v59, v56, s53
	v_lshlrev_b32_e32 v59, 8, v61
	v_and_b32_e32 v58, 0xff0000, v58
	v_and_b32_e32 v61, 0xff0000, v62
	v_perm_b32 v60, v63, v60, s53
	v_and_b32_e32 v57, 0xff00, v57
	v_and_b32_e32 v59, 0xff00, v59
	v_or3_b32 v56, v56, v57, v58
	v_or3_b32 v57, v60, v59, v61
	global_store_dwordx2 v[114:115], v[56:57], off
	v_lshlrev_b32_e32 v56, 16, v108
	v_and_b32_e32 v57, 0xffff0000, v108
	v_lshlrev_b32_e32 v58, 16, v109
	v_and_b32_e32 v59, 0xffff0000, v109
	v_lshlrev_b32_e32 v60, 16, v110
	v_and_b32_e32 v61, 0xffff0000, v110
	v_lshlrev_b32_e32 v62, 16, v111
	v_and_b32_e32 v63, 0xffff0000, v111
	v_pk_add_f32 v[54:55], v[54:55], v[58:59]
	v_pk_add_f32 v[52:53], v[52:53], v[56:57]
	v_pk_add_f32 v[58:59], v[48:49], v[60:61]
	v_cvt_pk_bf16_f32 v48, v52, v53
	v_cvt_pk_bf16_f32 v49, v54, v55
	v_pk_add_f32 v[56:57], v[50:51], v[62:63]
	v_cvt_pk_bf16_f32 v50, v58, v59
	s_nop 0
	v_cvt_pk_bf16_f32 v51, v56, v57
	global_store_dwordx4 v[102:103], v[48:51], off offset:256
	v_mul_f32_e32 v60, v113, v57
	s_nop 0
	v_mul_f32_e32 v49, v113, v53
	v_mul_f32_e32 v48, v113, v52
	v_mul_f32_e32 v50, v113, v54
	v_mul_f32_e32 v51, v113, v55
	v_med3_f32 v49, v49, s52, v198
	v_med3_f32 v48, v48, s52, v198
	v_rndne_f32_e32 v49, v49
	v_med3_f32 v50, v50, s52, v198
	v_med3_f32 v51, v51, s52, v198
	v_rndne_f32_e32 v48, v48
	v_cvt_i32_f32_e32 v49, v49
	v_rndne_f32_e32 v50, v50
	v_rndne_f32_e32 v51, v51
	v_cvt_i32_f32_e32 v48, v48
	v_cvt_i32_f32_sdwa v50, v50 dst_sel:WORD_1 dst_unused:UNUSED_PAD src0_sel:DWORD
	v_cvt_i32_f32_e32 v51, v51
	v_lshlrev_b32_e32 v49, 8, v49
	v_and_b32_e32 v49, 0xff00, v49
	v_and_b32_e32 v50, 0xff0000, v50
	v_perm_b32 v48, v51, v48, s53
	v_or3_b32 v50, v48, v49, v50
	v_mul_f32_e32 v49, v113, v59
	v_med3_f32 v49, v49, s52, v198
	v_rndne_f32_e32 v49, v49
	v_cvt_i32_f32_e32 v49, v49
	v_mul_f32_e32 v48, v113, v58
	v_med3_f32 v48, v48, s52, v198
	v_rndne_f32_e32 v48, v48
	v_mul_f32_e32 v51, v113, v56
	v_cvt_i32_f32_e32 v61, v48
	v_lshlrev_b32_e32 v48, 8, v49
	v_and_b32_e32 v62, 0xff00, v48
	v_med3_f32 v48, v51, s52, v198
	v_mul_f32_e32 v49, v53, v53
	v_mul_f32_e32 v51, v55, v55
	v_fmac_f32_e32 v49, v52, v52
	v_fmac_f32_e32 v51, v54, v54
	v_add_f32_e32 v49, v49, v51
	v_mul_f32_e32 v51, v59, v59
	v_fmac_f32_e32 v51, v58, v58
	v_add_f32_e32 v49, v51, v49
	v_mul_f32_e32 v51, v57, v57
	v_fmac_f32_e32 v51, v56, v56
	v_add_f32_e32 v49, v51, v49
	v_add_f32_e32 v49, v112, v49
	ds_bpermute_b32 v51, v116, v49
	v_rndne_f32_e32 v48, v48
	v_cvt_i32_f32_sdwa v52, v48 dst_sel:WORD_1 dst_unused:UNUSED_PAD src0_sel:DWORD
	v_med3_f32 v48, v60, s52, v198
	v_rndne_f32_e32 v48, v48
	v_cvt_i32_f32_e32 v53, v48
	s_waitcnt lgkmcnt(0)
	v_add_f32_e32 v48, v49, v51
	ds_bpermute_b32 v49, v117, v48
	v_and_b32_e32 v51, 0xff0000, v52
	v_perm_b32 v52, v53, v61, s53
	v_or3_b32 v51, v52, v62, v51
	global_store_dwordx2 v[114:115], v[50:51], off offset:128
	s_and_saveexec_b64 s[26:27], s[2:3]
	s_cbranch_execz .LBB0_464
	s_waitcnt lgkmcnt(0)
	v_add_f32_e32 v48, v48, v49
	v_fma_f32 v48, v48, s54, 0.5
	v_trunc_f32_e32 v48, v48
	v_mul_f32_e32 v49, 0x2f800000, v48
	v_floor_f32_e32 v49, v49
	v_fmac_f32_e32 v48, 0xcf800000, v49
	v_cvt_u32_f32_e32 v48, v48
	v_cvt_u32_f32_e32 v49, v49
	v_lshl_add_u64 v[50:51], v[100:101], 3, s[8:9]
	global_atomic_add_x2 v[50:51], v[48:49], off
.LBB0_464:
	s_or_b64 exec, exec, s[26:27]
	s_waitcnt lgkmcnt(0)
	v_mov_b32_e32 v48, v240
	v_mov_b32_e32 v49, v241
	v_lshlrev_b32_e32 v52, 16, v84
	v_and_b32_e32 v53, 0xffff0000, v84
	v_lshlrev_b32_e32 v54, 16, v85
	v_and_b32_e32 v55, 0xffff0000, v85
	v_lshlrev_b32_e32 v60, 16, v80
	v_and_b32_e32 v61, 0xffff0000, v80
	v_lshlrev_b32_e32 v62, 16, v81
	v_and_b32_e32 v63, 0xffff0000, v81
	v_lshlrev_b32_e32 v80, 16, v82
	v_and_b32_e32 v81, 0xffff0000, v82
	v_lshlrev_b32_e32 v56, 16, v86
	v_and_b32_e32 v57, 0xffff0000, v86
	v_lshlrev_b32_e32 v58, 16, v87
	v_and_b32_e32 v59, 0xffff0000, v87
	v_lshlrev_b32_e32 v82, 16, v83
	v_and_b32_e32 v83, 0xffff0000, v83
	v_pk_add_f32 v[46:47], v[46:47], v[54:55]
	v_pk_add_f32 v[44:45], v[44:45], v[52:53]
	v_pk_add_f32 v[54:55], v[32:33], v[80:81]
	v_cvt_pk_bf16_f32 v32, v44, v45
	v_pk_add_f32 v[42:43], v[42:43], v[58:59]
	v_pk_add_f32 v[40:41], v[40:41], v[56:57]
	v_pk_add_f32 v[52:53], v[34:35], v[82:83]
	v_cvt_pk_bf16_f32 v33, v46, v47
	v_cvt_pk_bf16_f32 v34, v40, v41
	v_cvt_pk_bf16_f32 v35, v42, v43
	global_store_dwordx4 v[98:99], v[32:35], off
	v_mul_f32_e32 v56, v45, v45
	v_mul_f32_e32 v57, v47, v47
	v_mul_f32_e32 v58, v41, v41
	v_fmac_f32_e32 v56, v44, v44
	v_fmac_f32_e32 v57, v46, v46
	v_mul_f32_e32 v59, v43, v43
	v_fmac_f32_e32 v58, v40, v40
	v_fmac_f32_e32 v59, v42, v42
	v_lshlrev_b64 v[50:51], 12, v[96:97]
	v_lshl_add_u64 v[50:51], v[50:51], 0, v[168:169]
	v_pk_add_f32 v[36:37], v[36:37], v[60:61]
	v_lshl_add_u64 v[50:51], s[10:11], 0, v[50:51]
	v_pk_add_f32 v[38:39], v[38:39], v[62:63]
	s_waitcnt vmcnt(6)
	v_ffbh_u32_e32 v32, v49
	v_min_u32_e32 v34, 32, v32
	v_lshlrev_b64 v[32:33], v34, v[48:49]
	v_min_u32_e32 v32, 1, v32
	v_or_b32_e32 v32, v33, v32
	v_cvt_f32_u32_e32 v32, v32
	v_sub_u32_e32 v33, 32, v34
	v_ldexp_f32 v32, v32, v33
	v_fmamk_f32 v32, v32, 0x2f800000, v196
	v_rsq_f32_e32 v32, v32
	v_add_f32_e32 v33, v56, v57
	v_add_f32_e32 v33, v58, v33
	v_add_f32_e32 v48, v59, v33
	v_mul_f32_e32 v49, 0x41ca3ab3, v32
	v_mul_f32_e32 v32, v44, v49
	v_mul_f32_e32 v33, v45, v49
	v_mul_f32_e32 v35, v47, v49
	v_mul_f32_e32 v41, v41, v49
	v_mul_f32_e32 v34, v46, v49
	v_mul_f32_e32 v40, v40, v49
	v_mul_f32_e32 v42, v42, v49
	v_mul_f32_e32 v43, v43, v49
	v_med3_f32 v32, v32, s52, v198
	v_med3_f32 v33, v33, s52, v198
	v_med3_f32 v35, v35, s52, v198
	v_med3_f32 v41, v41, s52, v198
	v_med3_f32 v34, v34, s52, v198
	v_med3_f32 v40, v40, s52, v198
	v_med3_f32 v42, v42, s52, v198
	v_med3_f32 v43, v43, s52, v198
	v_rndne_f32_e32 v32, v32
	v_rndne_f32_e32 v33, v33
	v_rndne_f32_e32 v35, v35
	v_rndne_f32_e32 v41, v41
	v_rndne_f32_e32 v34, v34
	v_rndne_f32_e32 v40, v40
	v_rndne_f32_e32 v42, v42
	v_rndne_f32_e32 v43, v43
	v_cvt_i32_f32_e32 v32, v32
	v_cvt_i32_f32_e32 v33, v33
	v_cvt_i32_f32_e32 v35, v35
	v_cvt_i32_f32_e32 v41, v41
	v_cvt_i32_f32_sdwa v34, v34 dst_sel:WORD_1 dst_unused:UNUSED_PAD src0_sel:DWORD
	v_cvt_i32_f32_e32 v40, v40
	v_cvt_i32_f32_sdwa v42, v42 dst_sel:WORD_1 dst_unused:UNUSED_PAD src0_sel:DWORD
	v_cvt_i32_f32_e32 v43, v43
	v_lshlrev_b32_e32 v33, 8, v33
	v_perm_b32 v32, v35, v32, s53
	v_lshlrev_b32_e32 v35, 8, v41
	v_and_b32_e32 v34, 0xff0000, v34
	v_and_b32_e32 v41, 0xff0000, v42
	v_perm_b32 v40, v43, v40, s53
	v_and_b32_e32 v33, 0xff00, v33
	v_and_b32_e32 v35, 0xff00, v35
	v_or3_b32 v32, v32, v33, v34
	v_or3_b32 v33, v40, v35, v41
	v_mul_f32_e32 v45, v37, v49
	global_store_dwordx2 v[50:51], v[32:33], off
	v_cvt_pk_bf16_f32 v32, v36, v37
	v_cvt_pk_bf16_f32 v33, v38, v39
	v_mul_f32_e32 v44, v36, v49
	v_mul_f32_e32 v46, v38, v49
	v_mul_f32_e32 v47, v39, v49
	v_cvt_pk_bf16_f32 v34, v54, v55
	v_cvt_pk_bf16_f32 v35, v52, v53
	global_store_dwordx4 v[98:99], v[32:35], off offset:256
	v_med3_f32 v44, v44, s52, v198
	v_mul_f32_e32 v40, v53, v49
	v_med3_f32 v33, v45, s52, v198
	v_rndne_f32_e32 v33, v33
	v_med3_f32 v34, v46, s52, v198
	v_med3_f32 v35, v47, s52, v198
	v_rndne_f32_e32 v32, v44
	v_cvt_i32_f32_e32 v33, v33
	v_rndne_f32_e32 v34, v34
	v_rndne_f32_e32 v35, v35
	v_cvt_i32_f32_e32 v32, v32
	v_cvt_i32_f32_sdwa v34, v34 dst_sel:WORD_1 dst_unused:UNUSED_PAD src0_sel:DWORD
	v_cvt_i32_f32_e32 v35, v35
	v_lshlrev_b32_e32 v33, 8, v33
	v_and_b32_e32 v33, 0xff00, v33
	v_and_b32_e32 v34, 0xff0000, v34
	v_perm_b32 v32, v35, v32, s53
	v_or3_b32 v34, v32, v33, v34
	v_mul_f32_e32 v33, v55, v49
	v_med3_f32 v33, v33, s52, v198
	v_rndne_f32_e32 v33, v33
	v_cvt_i32_f32_e32 v33, v33
	v_mul_f32_e32 v32, v54, v49
	v_med3_f32 v32, v32, s52, v198
	v_rndne_f32_e32 v32, v32
	v_mul_f32_e32 v35, v52, v49
	v_cvt_i32_f32_e32 v41, v32
	v_lshlrev_b32_e32 v32, 8, v33
	v_and_b32_e32 v42, 0xff00, v32
	v_med3_f32 v32, v35, s52, v198
	v_mul_f32_e32 v33, v37, v37
	v_mul_f32_e32 v35, v39, v39
	v_fmac_f32_e32 v33, v36, v36
	v_fmac_f32_e32 v35, v38, v38
	v_add_f32_e32 v33, v33, v35
	v_mul_f32_e32 v35, v55, v55
	v_fmac_f32_e32 v35, v54, v54
	v_add_f32_e32 v33, v35, v33
	v_mul_f32_e32 v35, v53, v53
	v_fmac_f32_e32 v35, v52, v52
	v_add_f32_e32 v33, v35, v33
	v_add_f32_e32 v33, v48, v33
	ds_bpermute_b32 v35, v116, v33
	v_rndne_f32_e32 v32, v32
	v_cvt_i32_f32_sdwa v36, v32 dst_sel:WORD_1 dst_unused:UNUSED_PAD src0_sel:DWORD
	v_med3_f32 v32, v40, s52, v198
	v_rndne_f32_e32 v32, v32
	v_cvt_i32_f32_e32 v37, v32
	s_waitcnt lgkmcnt(0)
	v_add_f32_e32 v32, v33, v35
	ds_bpermute_b32 v33, v117, v32
	v_and_b32_e32 v35, 0xff0000, v36
	v_perm_b32 v36, v37, v41, s53
	v_or3_b32 v35, v36, v42, v35
	global_store_dwordx2 v[50:51], v[34:35], off offset:128
	s_and_saveexec_b64 s[26:27], s[2:3]
	s_cbranch_execz .LBB0_466
	s_waitcnt lgkmcnt(0)
	v_add_f32_e32 v32, v32, v33
	v_fma_f32 v32, v32, s54, 0.5
	v_trunc_f32_e32 v32, v32
	v_mul_f32_e32 v33, 0x2f800000, v32
	v_floor_f32_e32 v33, v33
	v_fmac_f32_e32 v32, 0xcf800000, v33
	v_cvt_u32_f32_e32 v32, v32
	v_cvt_u32_f32_e32 v33, v33
	v_lshl_add_u64 v[34:35], v[96:97], 3, s[8:9]
	global_atomic_add_x2 v[34:35], v[32:33], off
.LBB0_466:
	s_or_b64 exec, exec, s[26:27]
	s_waitcnt lgkmcnt(0)
	v_mov_b32_e32 v32, v242
	v_mov_b32_e32 v33, v243
	v_lshlrev_b32_e32 v36, 16, v76
	v_and_b32_e32 v37, 0xffff0000, v76
	v_lshlrev_b32_e32 v38, 16, v77
	v_and_b32_e32 v39, 0xffff0000, v77
	v_lshlrev_b32_e32 v48, 16, v74
	v_and_b32_e32 v49, 0xffff0000, v74
	v_lshlrev_b32_e32 v40, 16, v78
	v_and_b32_e32 v41, 0xffff0000, v78
	v_lshlrev_b32_e32 v42, 16, v79
	v_and_b32_e32 v43, 0xffff0000, v79
	v_lshlrev_b32_e32 v50, 16, v75
	v_and_b32_e32 v51, 0xffff0000, v75
	v_pk_add_f32 v[30:31], v[30:31], v[38:39]
	v_pk_add_f32 v[28:29], v[28:29], v[36:37]
	v_pk_add_f32 v[38:39], v[16:17], v[48:49]
	v_cvt_pk_bf16_f32 v16, v28, v29
	v_pk_add_f32 v[26:27], v[26:27], v[42:43]
	v_pk_add_f32 v[24:25], v[24:25], v[40:41]
	v_pk_add_f32 v[36:37], v[18:19], v[50:51]
	v_cvt_pk_bf16_f32 v17, v30, v31
	v_cvt_pk_bf16_f32 v18, v24, v25
	v_cvt_pk_bf16_f32 v19, v26, v27
	global_store_dwordx4 v[94:95], v[16:19], off
	v_mul_f32_e32 v40, v29, v29
	v_mul_f32_e32 v41, v31, v31
	v_mul_f32_e32 v42, v25, v25
	v_fmac_f32_e32 v40, v28, v28
	v_fmac_f32_e32 v41, v30, v30
	v_mul_f32_e32 v43, v27, v27
	v_fmac_f32_e32 v42, v24, v24
	v_fmac_f32_e32 v43, v26, v26
	v_lshlrev_b64 v[34:35], 12, v[92:93]
	v_lshlrev_b32_e32 v44, 16, v72
	v_and_b32_e32 v45, 0xffff0000, v72
	v_lshl_add_u64 v[34:35], v[34:35], 0, v[168:169]
	v_lshlrev_b32_e32 v46, 16, v73
	v_and_b32_e32 v47, 0xffff0000, v73
	v_pk_add_f32 v[20:21], v[20:21], v[44:45]
	v_lshl_add_u64 v[34:35], s[10:11], 0, v[34:35]
	v_pk_add_f32 v[22:23], v[22:23], v[46:47]
	s_waitcnt vmcnt(11)
	v_ffbh_u32_e32 v16, v33
	v_min_u32_e32 v18, 32, v16
	v_lshlrev_b64 v[16:17], v18, v[32:33]
	v_min_u32_e32 v16, 1, v16
	v_or_b32_e32 v16, v17, v16
	v_cvt_f32_u32_e32 v16, v16
	v_sub_u32_e32 v17, 32, v18
	v_ldexp_f32 v16, v16, v17
	v_fmamk_f32 v16, v16, 0x2f800000, v196
	v_rsq_f32_e32 v16, v16
	v_add_f32_e32 v17, v40, v41
	v_add_f32_e32 v17, v42, v17
	v_add_f32_e32 v32, v43, v17
	v_mul_f32_e32 v33, 0x41ca3ab3, v16
	v_mul_f32_e32 v16, v28, v33
	v_mul_f32_e32 v17, v29, v33
	v_mul_f32_e32 v19, v31, v33
	v_mul_f32_e32 v25, v25, v33
	v_mul_f32_e32 v18, v30, v33
	v_mul_f32_e32 v24, v24, v33
	v_mul_f32_e32 v26, v26, v33
	v_mul_f32_e32 v27, v27, v33
	v_med3_f32 v16, v16, s52, v198
	v_med3_f32 v17, v17, s52, v198
	v_med3_f32 v19, v19, s52, v198
	v_med3_f32 v25, v25, s52, v198
	v_med3_f32 v18, v18, s52, v198
	v_med3_f32 v24, v24, s52, v198
	v_med3_f32 v26, v26, s52, v198
	v_med3_f32 v27, v27, s52, v198
	v_rndne_f32_e32 v16, v16
	v_rndne_f32_e32 v17, v17
	v_rndne_f32_e32 v19, v19
	v_rndne_f32_e32 v25, v25
	v_rndne_f32_e32 v18, v18
	v_rndne_f32_e32 v24, v24
	v_rndne_f32_e32 v26, v26
	v_rndne_f32_e32 v27, v27
	v_cvt_i32_f32_e32 v16, v16
	v_cvt_i32_f32_e32 v17, v17
	v_cvt_i32_f32_e32 v19, v19
	v_cvt_i32_f32_e32 v25, v25
	v_cvt_i32_f32_sdwa v18, v18 dst_sel:WORD_1 dst_unused:UNUSED_PAD src0_sel:DWORD
	v_cvt_i32_f32_e32 v24, v24
	v_cvt_i32_f32_sdwa v26, v26 dst_sel:WORD_1 dst_unused:UNUSED_PAD src0_sel:DWORD
	v_cvt_i32_f32_e32 v27, v27
	v_lshlrev_b32_e32 v17, 8, v17
	v_perm_b32 v16, v19, v16, s53
	v_lshlrev_b32_e32 v19, 8, v25
	v_and_b32_e32 v18, 0xff0000, v18
	v_and_b32_e32 v25, 0xff0000, v26
	v_perm_b32 v24, v27, v24, s53
	v_and_b32_e32 v17, 0xff00, v17
	v_and_b32_e32 v19, 0xff00, v19
	v_or3_b32 v16, v16, v17, v18
	v_or3_b32 v17, v24, v19, v25
	v_mul_f32_e32 v29, v21, v33
	global_store_dwordx2 v[34:35], v[16:17], off
	v_cvt_pk_bf16_f32 v16, v20, v21
	v_cvt_pk_bf16_f32 v17, v22, v23
	v_mul_f32_e32 v28, v20, v33
	v_mul_f32_e32 v30, v22, v33
	v_mul_f32_e32 v31, v23, v33
	v_cvt_pk_bf16_f32 v18, v38, v39
	v_cvt_pk_bf16_f32 v19, v36, v37
	global_store_dwordx4 v[94:95], v[16:19], off offset:256
	v_med3_f32 v28, v28, s52, v198
	v_mul_f32_e32 v24, v37, v33
	v_med3_f32 v17, v29, s52, v198
	v_rndne_f32_e32 v17, v17
	v_med3_f32 v18, v30, s52, v198
	v_med3_f32 v19, v31, s52, v198
	v_rndne_f32_e32 v16, v28
	v_cvt_i32_f32_e32 v17, v17
	v_rndne_f32_e32 v18, v18
	v_rndne_f32_e32 v19, v19
	v_cvt_i32_f32_e32 v16, v16
	v_cvt_i32_f32_sdwa v18, v18 dst_sel:WORD_1 dst_unused:UNUSED_PAD src0_sel:DWORD
	v_cvt_i32_f32_e32 v19, v19
	v_lshlrev_b32_e32 v17, 8, v17
	v_and_b32_e32 v17, 0xff00, v17
	v_and_b32_e32 v18, 0xff0000, v18
	v_perm_b32 v16, v19, v16, s53
	v_or3_b32 v18, v16, v17, v18
	v_mul_f32_e32 v17, v39, v33
	v_med3_f32 v17, v17, s52, v198
	v_rndne_f32_e32 v17, v17
	v_cvt_i32_f32_e32 v17, v17
	v_mul_f32_e32 v16, v38, v33
	v_med3_f32 v16, v16, s52, v198
	v_rndne_f32_e32 v16, v16
	v_mul_f32_e32 v19, v36, v33
	v_cvt_i32_f32_e32 v25, v16
	v_lshlrev_b32_e32 v16, 8, v17
	v_and_b32_e32 v26, 0xff00, v16
	v_med3_f32 v16, v19, s52, v198
	v_mul_f32_e32 v17, v21, v21
	v_mul_f32_e32 v19, v23, v23
	v_fmac_f32_e32 v17, v20, v20
	v_fmac_f32_e32 v19, v22, v22
	v_add_f32_e32 v17, v17, v19
	v_mul_f32_e32 v19, v39, v39
	v_fmac_f32_e32 v19, v38, v38
	v_add_f32_e32 v17, v19, v17
	v_mul_f32_e32 v19, v37, v37
	v_fmac_f32_e32 v19, v36, v36
	v_add_f32_e32 v17, v19, v17
	v_add_f32_e32 v17, v32, v17
	ds_bpermute_b32 v19, v116, v17
	v_rndne_f32_e32 v16, v16
	v_cvt_i32_f32_sdwa v20, v16 dst_sel:WORD_1 dst_unused:UNUSED_PAD src0_sel:DWORD
	v_med3_f32 v16, v24, s52, v198
	v_rndne_f32_e32 v16, v16
	v_cvt_i32_f32_e32 v21, v16
	s_waitcnt lgkmcnt(0)
	v_add_f32_e32 v16, v17, v19
	ds_bpermute_b32 v17, v117, v16
	v_and_b32_e32 v19, 0xff0000, v20
	v_perm_b32 v20, v21, v25, s53
	v_or3_b32 v19, v20, v26, v19
	global_store_dwordx2 v[34:35], v[18:19], off offset:128
	s_and_saveexec_b64 s[26:27], s[2:3]
	s_cbranch_execz .LBB0_468
	s_waitcnt lgkmcnt(0)
	v_add_f32_e32 v16, v16, v17
	v_fma_f32 v16, v16, s54, 0.5
	v_trunc_f32_e32 v16, v16
	v_mul_f32_e32 v17, 0x2f800000, v16
	v_floor_f32_e32 v17, v17
	v_fmac_f32_e32 v16, 0xcf800000, v17
	v_cvt_u32_f32_e32 v16, v16
	v_cvt_u32_f32_e32 v17, v17
	v_lshl_add_u64 v[18:19], v[92:93], 3, s[8:9]
	global_atomic_add_x2 v[18:19], v[16:17], off
.LBB0_468:
	s_or_b64 exec, exec, s[26:27]
	s_waitcnt lgkmcnt(0)
	v_mov_b32_e32 v16, v244
	v_mov_b32_e32 v17, v245
	v_lshlrev_b32_e32 v20, 16, v68
	v_and_b32_e32 v21, 0xffff0000, v68
	v_lshlrev_b32_e32 v22, 16, v69
	v_and_b32_e32 v23, 0xffff0000, v69
	v_lshlrev_b32_e32 v32, 16, v66
	v_and_b32_e32 v33, 0xffff0000, v66
	v_lshlrev_b32_e32 v24, 16, v70
	v_and_b32_e32 v25, 0xffff0000, v70
	v_lshlrev_b32_e32 v26, 16, v71
	v_and_b32_e32 v27, 0xffff0000, v71
	v_lshlrev_b32_e32 v34, 16, v67
	v_and_b32_e32 v35, 0xffff0000, v67
	v_pk_add_f32 v[14:15], v[14:15], v[22:23]
	v_pk_add_f32 v[12:13], v[12:13], v[20:21]
	v_pk_add_f32 v[22:23], v[0:1], v[32:33]
	v_cvt_pk_bf16_f32 v0, v12, v13
	v_pk_add_f32 v[10:11], v[10:11], v[26:27]
	v_pk_add_f32 v[8:9], v[8:9], v[24:25]
	v_pk_add_f32 v[20:21], v[2:3], v[34:35]
	v_cvt_pk_bf16_f32 v1, v14, v15
	v_cvt_pk_bf16_f32 v2, v8, v9
	v_cvt_pk_bf16_f32 v3, v10, v11
	global_store_dwordx4 v[90:91], v[0:3], off
	v_mul_f32_e32 v24, v13, v13
	v_mul_f32_e32 v25, v15, v15
	v_mul_f32_e32 v26, v9, v9
	v_fmac_f32_e32 v24, v12, v12
	v_fmac_f32_e32 v25, v14, v14
	v_mul_f32_e32 v27, v11, v11
	v_fmac_f32_e32 v26, v8, v8
	v_fmac_f32_e32 v27, v10, v10
	v_lshlrev_b64 v[18:19], 12, v[88:89]
	v_lshlrev_b32_e32 v28, 16, v64
	v_and_b32_e32 v29, 0xffff0000, v64
	v_lshl_add_u64 v[18:19], v[18:19], 0, v[168:169]
	v_lshlrev_b32_e32 v30, 16, v65
	v_and_b32_e32 v31, 0xffff0000, v65
	v_pk_add_f32 v[4:5], v[4:5], v[28:29]
	v_lshl_add_u64 v[18:19], s[10:11], 0, v[18:19]
	v_pk_add_f32 v[6:7], v[6:7], v[30:31]
	s_waitcnt vmcnt(16)
	v_ffbh_u32_e32 v0, v17
	v_min_u32_e32 v2, 32, v0
	v_lshlrev_b64 v[0:1], v2, v[16:17]
	v_min_u32_e32 v0, 1, v0
	v_or_b32_e32 v0, v1, v0
	v_cvt_f32_u32_e32 v0, v0
	v_sub_u32_e32 v1, 32, v2
	v_ldexp_f32 v0, v0, v1
	v_fmamk_f32 v0, v0, 0x2f800000, v196
	v_rsq_f32_e32 v0, v0
	v_add_f32_e32 v1, v24, v25
	v_add_f32_e32 v1, v26, v1
	v_add_f32_e32 v16, v27, v1
	v_mul_f32_e32 v17, 0x41ca3ab3, v0
	v_mul_f32_e32 v0, v12, v17
	v_mul_f32_e32 v1, v13, v17
	v_mul_f32_e32 v3, v15, v17
	v_mul_f32_e32 v9, v9, v17
	v_mul_f32_e32 v2, v14, v17
	v_mul_f32_e32 v8, v8, v17
	v_mul_f32_e32 v10, v10, v17
	v_mul_f32_e32 v11, v11, v17
	v_med3_f32 v0, v0, s52, v198
	v_med3_f32 v1, v1, s52, v198
	v_med3_f32 v3, v3, s52, v198
	v_med3_f32 v9, v9, s52, v198
	v_med3_f32 v2, v2, s52, v198
	v_med3_f32 v8, v8, s52, v198
	v_med3_f32 v10, v10, s52, v198
	v_med3_f32 v11, v11, s52, v198
	v_rndne_f32_e32 v0, v0
	v_rndne_f32_e32 v1, v1
	v_rndne_f32_e32 v3, v3
	v_rndne_f32_e32 v9, v9
	v_rndne_f32_e32 v2, v2
	v_rndne_f32_e32 v8, v8
	v_rndne_f32_e32 v10, v10
	v_rndne_f32_e32 v11, v11
	v_cvt_i32_f32_e32 v0, v0
	v_cvt_i32_f32_e32 v1, v1
	v_cvt_i32_f32_e32 v3, v3
	v_cvt_i32_f32_e32 v9, v9
	v_cvt_i32_f32_sdwa v2, v2 dst_sel:WORD_1 dst_unused:UNUSED_PAD src0_sel:DWORD
	v_cvt_i32_f32_e32 v8, v8
	v_cvt_i32_f32_sdwa v10, v10 dst_sel:WORD_1 dst_unused:UNUSED_PAD src0_sel:DWORD
	v_cvt_i32_f32_e32 v11, v11
	v_lshlrev_b32_e32 v1, 8, v1
	v_perm_b32 v0, v3, v0, s53
	v_lshlrev_b32_e32 v3, 8, v9
	v_and_b32_e32 v2, 0xff0000, v2
	v_and_b32_e32 v9, 0xff0000, v10
	v_perm_b32 v8, v11, v8, s53
	v_and_b32_e32 v1, 0xff00, v1
	v_and_b32_e32 v3, 0xff00, v3
	v_or3_b32 v0, v0, v1, v2
	v_or3_b32 v1, v8, v3, v9
	v_mul_f32_e32 v13, v5, v17
	global_store_dwordx2 v[18:19], v[0:1], off
	v_cvt_pk_bf16_f32 v0, v4, v5
	v_cvt_pk_bf16_f32 v1, v6, v7
	v_mul_f32_e32 v12, v4, v17
	v_mul_f32_e32 v14, v6, v17
	v_mul_f32_e32 v15, v7, v17
	v_cvt_pk_bf16_f32 v2, v22, v23
	v_cvt_pk_bf16_f32 v3, v20, v21
	global_store_dwordx4 v[90:91], v[0:3], off offset:256
	v_med3_f32 v12, v12, s52, v198
	v_mul_f32_e32 v8, v21, v17
	v_med3_f32 v1, v13, s52, v198
	v_rndne_f32_e32 v1, v1
	v_med3_f32 v2, v14, s52, v198
	v_med3_f32 v3, v15, s52, v198
	v_rndne_f32_e32 v0, v12
	v_cvt_i32_f32_e32 v1, v1
	v_rndne_f32_e32 v2, v2
	v_rndne_f32_e32 v3, v3
	v_cvt_i32_f32_e32 v0, v0
	v_cvt_i32_f32_sdwa v2, v2 dst_sel:WORD_1 dst_unused:UNUSED_PAD src0_sel:DWORD
	v_cvt_i32_f32_e32 v3, v3
	v_lshlrev_b32_e32 v1, 8, v1
	v_and_b32_e32 v1, 0xff00, v1
	v_and_b32_e32 v2, 0xff0000, v2
	v_perm_b32 v0, v3, v0, s53
	v_or3_b32 v2, v0, v1, v2
	v_mul_f32_e32 v1, v23, v17
	v_med3_f32 v1, v1, s52, v198
	v_rndne_f32_e32 v1, v1
	v_cvt_i32_f32_e32 v1, v1
	v_mul_f32_e32 v0, v22, v17
	v_med3_f32 v0, v0, s52, v198
	v_rndne_f32_e32 v0, v0
	v_mul_f32_e32 v3, v20, v17
	v_cvt_i32_f32_e32 v9, v0
	v_lshlrev_b32_e32 v0, 8, v1
	v_and_b32_e32 v10, 0xff00, v0
	v_med3_f32 v0, v3, s52, v198
	v_mul_f32_e32 v1, v5, v5
	v_mul_f32_e32 v3, v7, v7
	v_fmac_f32_e32 v1, v4, v4
	v_fmac_f32_e32 v3, v6, v6
	v_add_f32_e32 v1, v1, v3
	v_mul_f32_e32 v3, v23, v23
	v_fmac_f32_e32 v3, v22, v22
	v_add_f32_e32 v1, v3, v1
	v_mul_f32_e32 v3, v21, v21
	v_fmac_f32_e32 v3, v20, v20
	v_add_f32_e32 v1, v3, v1
	v_add_f32_e32 v1, v16, v1
	ds_bpermute_b32 v3, v116, v1
	v_rndne_f32_e32 v0, v0
	v_cvt_i32_f32_sdwa v4, v0 dst_sel:WORD_1 dst_unused:UNUSED_PAD src0_sel:DWORD
	v_med3_f32 v0, v8, s52, v198
	v_rndne_f32_e32 v0, v0
	v_cvt_i32_f32_e32 v5, v0
	s_waitcnt lgkmcnt(0)
	v_add_f32_e32 v0, v1, v3
	ds_bpermute_b32 v1, v117, v0
	v_and_b32_e32 v3, 0xff0000, v4
	v_perm_b32 v4, v5, v9, s53
	v_or3_b32 v3, v4, v10, v3
	global_store_dwordx2 v[18:19], v[2:3], off offset:128
	s_and_saveexec_b64 s[26:27], s[2:3]
	s_cbranch_execz .LBB0_470
	s_waitcnt lgkmcnt(0)
	v_add_f32_e32 v0, v0, v1
	v_fma_f32 v0, v0, s54, 0.5
	v_trunc_f32_e32 v0, v0
	v_mul_f32_e32 v1, 0x2f800000, v0
	v_floor_f32_e32 v1, v1
	v_fmac_f32_e32 v0, 0xcf800000, v1
	v_cvt_u32_f32_e32 v0, v0
	v_cvt_u32_f32_e32 v1, v1
	v_lshl_add_u64 v[2:3], v[88:89], 3, s[8:9]
	global_atomic_add_x2 v[2:3], v[0:1], off

.LBB0_638:
	v_lshl_add_u32 v174, s26, 8, v190
	v_lshl_or_b32 v168, s28, 8, v192
	v_ashrrev_i32_e32 v169, 31, v168
	v_ashrrev_i32_e32 v175, 31, v174
	v_lshl_add_u64 v[172:173], v[168:169], 1, s[6:7]
	v_lshlrev_b64 v[112:113], 13, v[174:175]
	v_lshl_add_u64 v[170:171], v[174:175], 3, s[8:9]
	v_lshl_add_u64 v[188:189], v[172:173], 0, v[112:113]
	global_load_dwordx2 v[208:209], v[170:171], off
	global_load_dwordx2 v[232:233], v[170:171], off offset:128
	global_load_dwordx2 v[234:235], v[170:171], off offset:256
	global_load_dwordx2 v[236:237], v[170:171], off offset:384
	global_load_dwordx2 v[238:239], v[170:171], off offset:1024
	global_load_dwordx2 v[240:241], v[170:171], off offset:1152
	global_load_dwordx2 v[242:243], v[170:171], off offset:1280
	global_load_dwordx2 v[244:245], v[170:171], off offset:1408
	global_load_dwordx4 v[200:203], v[188:189], off
	v_or_b32_e32 v184, 16, v174
	v_or_b32_e32 v180, 32, v174
	v_or_b32_e32 v176, 48, v174
	v_ashrrev_i32_e32 v185, 31, v184
	v_ashrrev_i32_e32 v181, 31, v180
	v_ashrrev_i32_e32 v177, 31, v176
	v_lshlrev_b64 v[112:113], 12, v[174:175]
	v_lshlrev_b64 v[114:115], 13, v[184:185]
	v_lshlrev_b64 v[124:125], 13, v[180:181]
	v_lshlrev_b64 v[126:127], 13, v[176:177]
	v_lshl_add_u64 v[112:113], v[112:113], 0, v[168:169]
	v_lshl_add_u64 v[186:187], v[172:173], 0, v[114:115]
	v_lshl_add_u64 v[182:183], v[172:173], 0, v[124:125]
	v_lshl_add_u64 v[178:179], v[172:173], 0, v[126:127]
	v_lshl_add_u64 v[210:211], s[12:13], 0, v[112:113]
	global_load_dwordx4 v[204:207], v[188:189], off offset:256
	global_load_dwordx4 v[148:151], v[186:187], off
	global_load_dwordx4 v[144:147], v[186:187], off offset:256
	global_load_dwordx4 v[140:143], v[182:183], off
	global_load_dwordx4 v[136:139], v[182:183], off offset:256
	global_load_dwordx4 v[124:127], v[178:179], off
	global_load_dwordx4 v[112:115], v[178:179], off offset:256
	s_mov_b64 s[96:97], 0x100000
	v_lshl_add_u64 v[220:221], v[188:189], 0, s[96:97]
	global_load_dwordx4 v[220:223], v[220:221], off
	v_lshl_add_u64 v[224:225], v[188:189], 0, s[96:97]
	global_load_dwordx4 v[224:227], v[224:225], off offset:256
	v_lshl_add_u64 v[228:229], v[186:187], 0, s[96:97]
	global_load_dwordx4 v[228:231], v[228:229], off
	v_lshl_add_u64 v[246:247], v[186:187], 0, s[96:97]
	global_load_dwordx4 v[246:249], v[246:247], off offset:256
	v_lshl_add_u64 v[250:251], v[182:183], 0, s[96:97]
	global_load_dwordx4 v[250:253], v[250:251], off
	v_lshl_add_u64 v[216:217], v[182:183], 0, s[96:97]
	global_load_dwordx4 v[216:219], v[216:217], off offset:256
	s_waitcnt vmcnt(0)
	v_ffbh_u32_e32 v199, v209
	v_min_u32_e32 v199, 32, v199
	v_lshlrev_b64 v[208:209], v199, v[208:209]
	v_min_u32_e32 v208, 1, v208
	v_or_b32_e32 v208, v209, v208
	v_cvt_f32_u32_e32 v208, v208
	v_lshlrev_b32_e32 v212, 16, v200
	v_and_b32_e32 v213, 0xffff0000, v200
	v_lshlrev_b32_e32 v200, 16, v201
	v_and_b32_e32 v201, 0xffff0000, v201
	v_lshlrev_b32_e32 v214, 16, v202
	v_and_b32_e32 v215, 0xffff0000, v202
	v_lshlrev_b32_e32 v202, 16, v203
	v_and_b32_e32 v203, 0xffff0000, v203
	v_pk_add_f32 v[134:135], v[134:135], v[200:201]
	v_pk_add_f32 v[132:133], v[132:133], v[212:213]
	v_pk_add_f32 v[200:201], v[130:131], v[202:203]
	v_pk_add_f32 v[202:203], v[128:129], v[214:215]
	v_sub_u32_e32 v199, 32, v199
	v_cvt_pk_bf16_f32 v128, v132, v133
	v_cvt_pk_bf16_f32 v129, v134, v135
	v_cvt_pk_bf16_f32 v130, v202, v203
	v_cvt_pk_bf16_f32 v131, v200, v201
	global_store_dwordx4 v[188:189], v[128:131], off
	v_mul_f32_e32 v212, v133, v133
	v_mul_f32_e32 v213, v135, v135
	v_ldexp_f32 v128, v208, v199
	v_fmamk_f32 v128, v128, 0x2f800000, v196
	v_rsq_f32_e32 v128, v128
	v_mul_f32_e32 v214, v203, v203
	v_fmac_f32_e32 v212, v132, v132
	v_fmac_f32_e32 v213, v134, v134
	v_fmac_f32_e32 v214, v202, v202
	v_add_f32_e32 v129, v212, v213
	v_mul_f32_e32 v199, 0x41b56db7, v128
	v_add_f32_e32 v130, v214, v129
	v_mul_f32_e32 v128, v199, v132
	v_mul_f32_e32 v129, v199, v133
	v_mul_f32_e32 v131, v199, v134
	v_mul_f32_e32 v132, v199, v135
	v_mul_f32_e32 v134, v199, v203
	v_mul_f32_e32 v133, v199, v202
	v_mul_f32_e32 v135, v199, v200
	v_mul_f32_e32 v202, v199, v201
	v_med3_f32 v128, v128, s52, v198
	v_med3_f32 v129, v129, s52, v198
	v_med3_f32 v132, v132, s52, v198
	v_med3_f32 v134, v134, s52, v198
	v_med3_f32 v131, v131, s52, v198
	v_med3_f32 v133, v133, s52, v198
	v_med3_f32 v135, v135, s52, v198
	v_med3_f32 v202, v202, s52, v198
	v_rndne_f32_e32 v128, v128
	v_rndne_f32_e32 v129, v129
	v_rndne_f32_e32 v132, v132
	v_rndne_f32_e32 v134, v134
	v_rndne_f32_e32 v131, v131
	v_rndne_f32_e32 v133, v133
	v_rndne_f32_e32 v135, v135
	v_rndne_f32_e32 v202, v202
	v_cvt_i32_f32_e32 v128, v128
	v_cvt_i32_f32_e32 v129, v129
	v_cvt_i32_f32_e32 v132, v132
	v_cvt_i32_f32_e32 v134, v134
	v_cvt_i32_f32_sdwa v131, v131 dst_sel:WORD_1 dst_unused:UNUSED_PAD src0_sel:DWORD
	v_cvt_i32_f32_e32 v133, v133
	v_cvt_i32_f32_sdwa v135, v135 dst_sel:WORD_1 dst_unused:UNUSED_PAD src0_sel:DWORD
	v_cvt_i32_f32_e32 v202, v202
	v_lshlrev_b32_e32 v129, 8, v129
	v_perm_b32 v128, v132, v128, s53
	v_lshlrev_b32_e32 v132, 8, v134
	v_and_b32_e32 v131, 0xff0000, v131
	v_and_b32_e32 v134, 0xff0000, v135
	v_perm_b32 v133, v202, v133, s53
	v_and_b32_e32 v129, 0xff00, v129
	v_and_b32_e32 v132, 0xff00, v132
	v_or3_b32 v128, v128, v129, v131
	v_or3_b32 v129, v133, v132, v134
	global_store_dwordx2 v[210:211], v[128:129], off
	v_mul_f32_e32 v128, v201, v201
	v_fmac_f32_e32 v128, v200, v200
	v_add_f32_e32 v200, v128, v130
	v_lshlrev_b32_e32 v128, 16, v204
	v_and_b32_e32 v129, 0xffff0000, v204
	v_lshlrev_b32_e32 v130, 16, v205
	v_and_b32_e32 v131, 0xffff0000, v205
	v_lshlrev_b32_e32 v132, 16, v206
	v_and_b32_e32 v133, 0xffff0000, v206
	v_lshlrev_b32_e32 v134, 16, v207
	v_and_b32_e32 v135, 0xffff0000, v207
	v_pk_add_f32 v[122:123], v[122:123], v[130:131]
	v_pk_add_f32 v[120:121], v[120:121], v[128:129]
	v_pk_add_f32 v[130:131], v[116:117], v[132:133]
	v_cvt_pk_bf16_f32 v116, v120, v121
	v_cvt_pk_bf16_f32 v117, v122, v123
	v_pk_add_f32 v[128:129], v[118:119], v[134:135]
	v_cvt_pk_bf16_f32 v118, v130, v131
	s_nop 0
	v_cvt_pk_bf16_f32 v119, v128, v129
	global_store_dwordx4 v[188:189], v[116:119], off offset:256
	s_nop 1
	v_mul_f32_e32 v117, v199, v121
	v_mul_f32_e32 v116, v199, v120
	v_mul_f32_e32 v118, v199, v122
	v_mul_f32_e32 v119, v199, v123
	v_med3_f32 v117, v117, s52, v198
	v_med3_f32 v116, v116, s52, v198
	v_rndne_f32_e32 v117, v117
	v_med3_f32 v118, v118, s52, v198
	v_med3_f32 v119, v119, s52, v198
	v_rndne_f32_e32 v116, v116
	v_cvt_i32_f32_e32 v117, v117
	v_rndne_f32_e32 v118, v118
	v_rndne_f32_e32 v119, v119
	v_cvt_i32_f32_e32 v116, v116
	v_cvt_i32_f32_sdwa v118, v118 dst_sel:WORD_1 dst_unused:UNUSED_PAD src0_sel:DWORD
	v_cvt_i32_f32_e32 v119, v119
	v_lshlrev_b32_e32 v117, 8, v117
	v_and_b32_e32 v117, 0xff00, v117
	v_and_b32_e32 v118, 0xff0000, v118
	v_perm_b32 v116, v119, v116, s53
	v_or3_b32 v132, v116, v117, v118
	v_mul_f32_e32 v117, v199, v131
	v_med3_f32 v117, v117, s52, v198
	v_rndne_f32_e32 v117, v117
	v_cvt_i32_f32_e32 v117, v117
	v_mul_f32_e32 v116, v199, v130
	v_med3_f32 v116, v116, s52, v198
	v_rndne_f32_e32 v116, v116
	v_mul_f32_e32 v118, v199, v128
	v_cvt_i32_f32_e32 v133, v116
	v_lshlrev_b32_e32 v116, 8, v117
	v_and_b32_e32 v134, 0xff00, v116
	v_med3_f32 v116, v118, s52, v198
	v_rndne_f32_e32 v117, v116
	v_mul_f32_e32 v116, v121, v121
	v_mul_f32_e32 v118, v123, v123
	v_fmac_f32_e32 v116, v120, v120
	v_fmac_f32_e32 v118, v122, v122
	v_add_f32_e32 v116, v116, v118
	v_mul_f32_e32 v118, v131, v131
	v_fmac_f32_e32 v118, v130, v130
	v_add_f32_e32 v116, v118, v116
	v_mul_f32_e32 v118, v129, v129
	v_fmac_f32_e32 v118, v128, v128
	v_add_f32_e32 v116, v118, v116
	v_and_b32_e32 v120, 64, v197
	v_add_f32_e32 v118, v200, v116
	v_xor_b32_e32 v116, 16, v197
	v_add_u32_e32 v120, 64, v120
	v_cmp_lt_i32_e32 vcc, v116, v120
	v_mul_f32_e32 v119, v199, v129
	v_cvt_i32_f32_sdwa v122, v117 dst_sel:WORD_1 dst_unused:UNUSED_PAD src0_sel:DWORD
	v_cndmask_b32_e32 v116, v197, v116, vcc
	v_lshlrev_b32_e32 v116, 2, v116
	ds_bpermute_b32 v121, v116, v118
	v_med3_f32 v117, v119, s52, v198
	v_rndne_f32_e32 v117, v117
	v_cvt_i32_f32_e32 v123, v117
	v_xor_b32_e32 v117, 32, v197
	v_cmp_lt_i32_e32 vcc, v117, v120
	s_waitcnt lgkmcnt(0)
	v_add_f32_e32 v118, v118, v121
	v_and_b32_e32 v120, 0xff0000, v122
	v_cndmask_b32_e32 v117, v197, v117, vcc
	v_lshlrev_b32_e32 v117, 2, v117
	ds_bpermute_b32 v119, v117, v118
	v_perm_b32 v121, v123, v133, s53
	v_or3_b32 v133, v121, v134, v120
	global_store_dwordx2 v[210:211], v[132:133], off offset:128
	s_and_saveexec_b64 s[26:27], s[2:3]
	s_cbranch_execz .LBB0_640
	s_waitcnt lgkmcnt(0)
	v_add_f32_e32 v118, v118, v119
	v_fma_f32 v118, v118, s54, 0.5
	v_trunc_f32_e32 v118, v118
	v_mul_f32_e32 v119, 0x2f800000, v118
	v_floor_f32_e32 v119, v119
	v_fmac_f32_e32 v118, 0xcf800000, v119
	v_cvt_u32_f32_e32 v118, v118
	v_cvt_u32_f32_e32 v119, v119
	v_lshl_add_u64 v[120:121], v[174:175], 3, s[10:11]
	global_atomic_add_x2 v[120:121], v[118:119], off
.LBB0_640:
	s_or_b64 exec, exec, s[26:27]
	s_waitcnt lgkmcnt(0)
	v_lshl_add_u64 v[118:119], v[184:185], 3, s[8:9]
	v_mov_b32_e32 v118, v232
	v_mov_b32_e32 v119, v233
	v_lshlrev_b32_e32 v122, 16, v148
	v_and_b32_e32 v123, 0xffff0000, v148
	v_lshlrev_b32_e32 v128, 16, v149
	v_and_b32_e32 v129, 0xffff0000, v149
	v_lshlrev_b32_e32 v148, 16, v146
	v_and_b32_e32 v149, 0xffff0000, v146
	v_lshlrev_b32_e32 v130, 16, v150
	v_and_b32_e32 v131, 0xffff0000, v150
	v_lshlrev_b32_e32 v132, 16, v151
	v_and_b32_e32 v133, 0xffff0000, v151
	v_lshlrev_b32_e32 v146, 16, v147
	v_and_b32_e32 v147, 0xffff0000, v147
	v_pk_add_f32 v[110:111], v[110:111], v[128:129]
	v_pk_add_f32 v[108:109], v[108:109], v[122:123]
	v_pk_add_f32 v[128:129], v[96:97], v[148:149]
	v_cvt_pk_bf16_f32 v96, v108, v109
	v_pk_add_f32 v[106:107], v[106:107], v[132:133]
	v_pk_add_f32 v[104:105], v[104:105], v[130:131]
	v_pk_add_f32 v[122:123], v[98:99], v[146:147]
	v_cvt_pk_bf16_f32 v97, v110, v111
	v_cvt_pk_bf16_f32 v98, v104, v105
	v_cvt_pk_bf16_f32 v99, v106, v107
	global_store_dwordx4 v[186:187], v[96:99], off
	v_mul_f32_e32 v130, v109, v109
	v_mul_f32_e32 v131, v111, v111
	v_mul_f32_e32 v132, v105, v105
	v_fmac_f32_e32 v130, v108, v108
	v_fmac_f32_e32 v131, v110, v110
	v_mul_f32_e32 v133, v107, v107
	v_fmac_f32_e32 v132, v104, v104
	v_fmac_f32_e32 v133, v106, v106
	v_lshlrev_b64 v[120:121], 12, v[184:185]
	v_lshlrev_b32_e32 v134, 16, v144
	v_and_b32_e32 v135, 0xffff0000, v144
	v_lshl_add_u64 v[120:121], v[120:121], 0, v[168:169]
	v_lshlrev_b32_e32 v144, 16, v145
	v_and_b32_e32 v145, 0xffff0000, v145
	v_pk_add_f32 v[100:101], v[100:101], v[134:135]
	v_lshl_add_u64 v[120:121], s[12:13], 0, v[120:121]
	v_pk_add_f32 v[102:103], v[102:103], v[144:145]
	v_ffbh_u32_e32 v96, v119
	v_min_u32_e32 v98, 32, v96
	v_lshlrev_b64 v[96:97], v98, v[118:119]
	v_min_u32_e32 v96, 1, v96
	v_or_b32_e32 v96, v97, v96
	v_cvt_f32_u32_e32 v96, v96
	v_sub_u32_e32 v97, 32, v98
	v_ldexp_f32 v96, v96, v97
	v_fmamk_f32 v96, v96, 0x2f800000, v196
	v_rsq_f32_e32 v96, v96
	v_add_f32_e32 v97, v130, v131
	v_add_f32_e32 v97, v132, v97
	v_add_f32_e32 v118, v133, v97
	v_mul_f32_e32 v119, 0x41b56db7, v96
	v_mul_f32_e32 v96, v108, v119
	v_mul_f32_e32 v97, v109, v119
	v_mul_f32_e32 v99, v111, v119
	v_mul_f32_e32 v105, v105, v119
	v_mul_f32_e32 v98, v110, v119
	v_mul_f32_e32 v104, v104, v119
	v_mul_f32_e32 v106, v106, v119
	v_mul_f32_e32 v107, v107, v119
	v_med3_f32 v96, v96, s52, v198
	v_med3_f32 v97, v97, s52, v198
	v_med3_f32 v99, v99, s52, v198
	v_med3_f32 v105, v105, s52, v198
	v_med3_f32 v98, v98, s52, v198
	v_med3_f32 v104, v104, s52, v198
	v_med3_f32 v106, v106, s52, v198
	v_med3_f32 v107, v107, s52, v198
	v_rndne_f32_e32 v96, v96
	v_rndne_f32_e32 v97, v97
	v_rndne_f32_e32 v99, v99
	v_rndne_f32_e32 v105, v105
	v_rndne_f32_e32 v98, v98
	v_rndne_f32_e32 v104, v104
	v_rndne_f32_e32 v106, v106
	v_rndne_f32_e32 v107, v107
	v_cvt_i32_f32_e32 v96, v96
	v_cvt_i32_f32_e32 v97, v97
	v_cvt_i32_f32_e32 v99, v99
	v_cvt_i32_f32_e32 v105, v105
	v_cvt_i32_f32_sdwa v98, v98 dst_sel:WORD_1 dst_unused:UNUSED_PAD src0_sel:DWORD
	v_cvt_i32_f32_e32 v104, v104
	v_cvt_i32_f32_sdwa v106, v106 dst_sel:WORD_1 dst_unused:UNUSED_PAD src0_sel:DWORD
	v_cvt_i32_f32_e32 v107, v107
	v_lshlrev_b32_e32 v97, 8, v97
	v_perm_b32 v96, v99, v96, s53
	v_lshlrev_b32_e32 v99, 8, v105
	v_and_b32_e32 v98, 0xff0000, v98
	v_and_b32_e32 v105, 0xff0000, v106
	v_perm_b32 v104, v107, v104, s53
	v_and_b32_e32 v97, 0xff00, v97
	v_and_b32_e32 v99, 0xff00, v99
	v_or3_b32 v96, v96, v97, v98
	v_or3_b32 v97, v104, v99, v105
	v_mul_f32_e32 v109, v101, v119
	global_store_dwordx2 v[120:121], v[96:97], off
	v_cvt_pk_bf16_f32 v96, v100, v101
	v_cvt_pk_bf16_f32 v97, v102, v103
	v_mul_f32_e32 v108, v100, v119
	v_mul_f32_e32 v110, v102, v119
	v_mul_f32_e32 v111, v103, v119
	v_cvt_pk_bf16_f32 v98, v128, v129
	v_cvt_pk_bf16_f32 v99, v122, v123
	global_store_dwordx4 v[186:187], v[96:99], off offset:256
	v_med3_f32 v108, v108, s52, v198
	v_mul_f32_e32 v104, v123, v119
	v_med3_f32 v97, v109, s52, v198
	v_rndne_f32_e32 v97, v97
	v_med3_f32 v98, v110, s52, v198
	v_med3_f32 v99, v111, s52, v198
	v_rndne_f32_e32 v96, v108
	v_cvt_i32_f32_e32 v97, v97
	v_rndne_f32_e32 v98, v98
	v_rndne_f32_e32 v99, v99
	v_cvt_i32_f32_e32 v96, v96
	v_cvt_i32_f32_sdwa v98, v98 dst_sel:WORD_1 dst_unused:UNUSED_PAD src0_sel:DWORD
	v_cvt_i32_f32_e32 v99, v99
	v_lshlrev_b32_e32 v97, 8, v97
	v_and_b32_e32 v97, 0xff00, v97
	v_and_b32_e32 v98, 0xff0000, v98
	v_perm_b32 v96, v99, v96, s53
	v_or3_b32 v98, v96, v97, v98
	v_mul_f32_e32 v97, v129, v119
	v_med3_f32 v97, v97, s52, v198
	v_rndne_f32_e32 v97, v97
	v_cvt_i32_f32_e32 v97, v97
	v_mul_f32_e32 v96, v128, v119
	v_med3_f32 v96, v96, s52, v198
	v_rndne_f32_e32 v96, v96
	v_mul_f32_e32 v99, v122, v119
	v_cvt_i32_f32_e32 v105, v96
	v_lshlrev_b32_e32 v96, 8, v97
	v_and_b32_e32 v106, 0xff00, v96
	v_med3_f32 v96, v99, s52, v198
	v_mul_f32_e32 v97, v101, v101
	v_mul_f32_e32 v99, v103, v103
	v_fmac_f32_e32 v97, v100, v100
	v_fmac_f32_e32 v99, v102, v102
	v_add_f32_e32 v97, v97, v99
	v_mul_f32_e32 v99, v129, v129
	v_fmac_f32_e32 v99, v128, v128
	v_add_f32_e32 v97, v99, v97
	v_mul_f32_e32 v99, v123, v123
	v_fmac_f32_e32 v99, v122, v122
	v_add_f32_e32 v97, v99, v97
	v_add_f32_e32 v97, v118, v97
	ds_bpermute_b32 v99, v116, v97
	v_rndne_f32_e32 v96, v96
	v_cvt_i32_f32_sdwa v100, v96 dst_sel:WORD_1 dst_unused:UNUSED_PAD src0_sel:DWORD
	v_med3_f32 v96, v104, s52, v198
	v_rndne_f32_e32 v96, v96
	v_cvt_i32_f32_e32 v101, v96
	s_waitcnt lgkmcnt(0)
	v_add_f32_e32 v96, v97, v99
	ds_bpermute_b32 v97, v117, v96
	v_and_b32_e32 v99, 0xff0000, v100
	v_perm_b32 v100, v101, v105, s53
	v_or3_b32 v99, v100, v106, v99
	global_store_dwordx2 v[120:121], v[98:99], off offset:128
	s_and_saveexec_b64 s[26:27], s[2:3]
	s_cbranch_execz .LBB0_642
	s_waitcnt lgkmcnt(0)
	v_add_f32_e32 v96, v96, v97
	v_fma_f32 v96, v96, s54, 0.5
	v_trunc_f32_e32 v96, v96
	v_mul_f32_e32 v97, 0x2f800000, v96
	v_floor_f32_e32 v97, v97
	v_fmac_f32_e32 v96, 0xcf800000, v97
	v_cvt_u32_f32_e32 v96, v96
	v_cvt_u32_f32_e32 v97, v97
	v_lshl_add_u64 v[98:99], v[184:185], 3, s[10:11]
	global_atomic_add_x2 v[98:99], v[96:97], off
.LBB0_642:
	s_or_b64 exec, exec, s[26:27]
	s_waitcnt lgkmcnt(0)
	v_lshl_add_u64 v[96:97], v[180:181], 3, s[8:9]
	v_mov_b32_e32 v96, v234
	v_mov_b32_e32 v97, v235
	v_lshlrev_b32_e32 v100, 16, v140
	v_and_b32_e32 v101, 0xffff0000, v140
	v_lshlrev_b32_e32 v102, 16, v141
	v_and_b32_e32 v103, 0xffff0000, v141
	v_lshlrev_b32_e32 v118, 16, v138
	v_and_b32_e32 v119, 0xffff0000, v138
	v_lshlrev_b32_e32 v104, 16, v142
	v_and_b32_e32 v105, 0xffff0000, v142
	v_lshlrev_b32_e32 v106, 16, v143
	v_and_b32_e32 v107, 0xffff0000, v143
	v_lshlrev_b32_e32 v120, 16, v139
	v_and_b32_e32 v121, 0xffff0000, v139
	v_pk_add_f32 v[94:95], v[94:95], v[102:103]
	v_pk_add_f32 v[92:93], v[92:93], v[100:101]
	v_pk_add_f32 v[102:103], v[80:81], v[118:119]
	v_cvt_pk_bf16_f32 v80, v92, v93
	v_pk_add_f32 v[90:91], v[90:91], v[106:107]
	v_pk_add_f32 v[88:89], v[88:89], v[104:105]
	v_pk_add_f32 v[100:101], v[82:83], v[120:121]
	v_cvt_pk_bf16_f32 v81, v94, v95
	v_cvt_pk_bf16_f32 v82, v88, v89
	v_cvt_pk_bf16_f32 v83, v90, v91
	global_store_dwordx4 v[182:183], v[80:83], off
	v_mul_f32_e32 v104, v93, v93
	v_mul_f32_e32 v105, v95, v95
	v_mul_f32_e32 v106, v89, v89
	v_fmac_f32_e32 v104, v92, v92
	v_fmac_f32_e32 v105, v94, v94
	v_mul_f32_e32 v107, v91, v91
	v_fmac_f32_e32 v106, v88, v88
	v_fmac_f32_e32 v107, v90, v90
	v_lshlrev_b64 v[98:99], 12, v[180:181]
	v_lshlrev_b32_e32 v108, 16, v136
	v_and_b32_e32 v109, 0xffff0000, v136
	v_lshl_add_u64 v[98:99], v[98:99], 0, v[168:169]
	v_lshlrev_b32_e32 v110, 16, v137
	v_and_b32_e32 v111, 0xffff0000, v137
	v_pk_add_f32 v[84:85], v[84:85], v[108:109]
	v_lshl_add_u64 v[98:99], s[12:13], 0, v[98:99]
	v_pk_add_f32 v[86:87], v[86:87], v[110:111]
	v_ffbh_u32_e32 v80, v97
	v_min_u32_e32 v82, 32, v80
	v_lshlrev_b64 v[80:81], v82, v[96:97]
	v_min_u32_e32 v80, 1, v80
	v_or_b32_e32 v80, v81, v80
	v_cvt_f32_u32_e32 v80, v80
	v_sub_u32_e32 v81, 32, v82
	v_ldexp_f32 v80, v80, v81
	v_fmamk_f32 v80, v80, 0x2f800000, v196
	v_rsq_f32_e32 v80, v80
	v_add_f32_e32 v81, v104, v105
	v_add_f32_e32 v81, v106, v81
	v_add_f32_e32 v96, v107, v81
	v_mul_f32_e32 v97, 0x41b56db7, v80
	v_mul_f32_e32 v80, v92, v97
	v_mul_f32_e32 v81, v93, v97
	v_mul_f32_e32 v83, v95, v97
	v_mul_f32_e32 v89, v89, v97
	v_mul_f32_e32 v82, v94, v97
	v_mul_f32_e32 v88, v88, v97
	v_mul_f32_e32 v90, v90, v97
	v_mul_f32_e32 v91, v91, v97
	v_med3_f32 v80, v80, s52, v198
	v_med3_f32 v81, v81, s52, v198
	v_med3_f32 v83, v83, s52, v198
	v_med3_f32 v89, v89, s52, v198
	v_med3_f32 v82, v82, s52, v198
	v_med3_f32 v88, v88, s52, v198
	v_med3_f32 v90, v90, s52, v198
	v_med3_f32 v91, v91, s52, v198
	v_rndne_f32_e32 v80, v80
	v_rndne_f32_e32 v81, v81
	v_rndne_f32_e32 v83, v83
	v_rndne_f32_e32 v89, v89
	v_rndne_f32_e32 v82, v82
	v_rndne_f32_e32 v88, v88
	v_rndne_f32_e32 v90, v90
	v_rndne_f32_e32 v91, v91
	v_cvt_i32_f32_e32 v80, v80
	v_cvt_i32_f32_e32 v81, v81
	v_cvt_i32_f32_e32 v83, v83
	v_cvt_i32_f32_e32 v89, v89
	v_cvt_i32_f32_sdwa v82, v82 dst_sel:WORD_1 dst_unused:UNUSED_PAD src0_sel:DWORD
	v_cvt_i32_f32_e32 v88, v88
	v_cvt_i32_f32_sdwa v90, v90 dst_sel:WORD_1 dst_unused:UNUSED_PAD src0_sel:DWORD
	v_cvt_i32_f32_e32 v91, v91
	v_lshlrev_b32_e32 v81, 8, v81
	v_perm_b32 v80, v83, v80, s53
	v_lshlrev_b32_e32 v83, 8, v89
	v_and_b32_e32 v82, 0xff0000, v82
	v_and_b32_e32 v89, 0xff0000, v90
	v_perm_b32 v88, v91, v88, s53
	v_and_b32_e32 v81, 0xff00, v81
	v_and_b32_e32 v83, 0xff00, v83
	v_or3_b32 v80, v80, v81, v82
	v_or3_b32 v81, v88, v83, v89
	v_mul_f32_e32 v93, v85, v97
	global_store_dwordx2 v[98:99], v[80:81], off
	v_cvt_pk_bf16_f32 v80, v84, v85
	v_cvt_pk_bf16_f32 v81, v86, v87
	v_mul_f32_e32 v92, v84, v97
	v_mul_f32_e32 v94, v86, v97
	v_mul_f32_e32 v95, v87, v97
	v_cvt_pk_bf16_f32 v82, v102, v103
	v_cvt_pk_bf16_f32 v83, v100, v101
	global_store_dwordx4 v[182:183], v[80:83], off offset:256
	v_med3_f32 v92, v92, s52, v198
	v_mul_f32_e32 v88, v101, v97
	v_med3_f32 v81, v93, s52, v198
	v_rndne_f32_e32 v81, v81
	v_med3_f32 v82, v94, s52, v198
	v_med3_f32 v83, v95, s52, v198
	v_rndne_f32_e32 v80, v92
	v_cvt_i32_f32_e32 v81, v81
	v_rndne_f32_e32 v82, v82
	v_rndne_f32_e32 v83, v83
	v_cvt_i32_f32_e32 v80, v80
	v_cvt_i32_f32_sdwa v82, v82 dst_sel:WORD_1 dst_unused:UNUSED_PAD src0_sel:DWORD
	v_cvt_i32_f32_e32 v83, v83
	v_lshlrev_b32_e32 v81, 8, v81
	v_and_b32_e32 v81, 0xff00, v81
	v_and_b32_e32 v82, 0xff0000, v82
	v_perm_b32 v80, v83, v80, s53
	v_or3_b32 v82, v80, v81, v82
	v_mul_f32_e32 v81, v103, v97
	v_med3_f32 v81, v81, s52, v198
	v_rndne_f32_e32 v81, v81
	v_cvt_i32_f32_e32 v81, v81
	v_mul_f32_e32 v80, v102, v97
	v_med3_f32 v80, v80, s52, v198
	v_rndne_f32_e32 v80, v80
	v_mul_f32_e32 v83, v100, v97
	v_cvt_i32_f32_e32 v89, v80
	v_lshlrev_b32_e32 v80, 8, v81
	v_and_b32_e32 v90, 0xff00, v80
	v_med3_f32 v80, v83, s52, v198
	v_mul_f32_e32 v81, v85, v85
	v_mul_f32_e32 v83, v87, v87
	v_fmac_f32_e32 v81, v84, v84
	v_fmac_f32_e32 v83, v86, v86
	v_add_f32_e32 v81, v81, v83
	v_mul_f32_e32 v83, v103, v103
	v_fmac_f32_e32 v83, v102, v102
	v_add_f32_e32 v81, v83, v81
	v_mul_f32_e32 v83, v101, v101
	v_fmac_f32_e32 v83, v100, v100
	v_add_f32_e32 v81, v83, v81
	v_add_f32_e32 v81, v96, v81
	ds_bpermute_b32 v83, v116, v81
	v_rndne_f32_e32 v80, v80
	v_cvt_i32_f32_sdwa v84, v80 dst_sel:WORD_1 dst_unused:UNUSED_PAD src0_sel:DWORD
	v_med3_f32 v80, v88, s52, v198
	v_rndne_f32_e32 v80, v80
	v_cvt_i32_f32_e32 v85, v80
	s_waitcnt lgkmcnt(0)
	v_add_f32_e32 v80, v81, v83
	ds_bpermute_b32 v81, v117, v80
	v_and_b32_e32 v83, 0xff0000, v84
	v_perm_b32 v84, v85, v89, s53
	v_or3_b32 v83, v84, v90, v83
	global_store_dwordx2 v[98:99], v[82:83], off offset:128
	s_and_saveexec_b64 s[26:27], s[2:3]
	s_cbranch_execz .LBB0_644
	s_waitcnt lgkmcnt(0)
	v_add_f32_e32 v80, v80, v81
	v_fma_f32 v80, v80, s54, 0.5
	v_trunc_f32_e32 v80, v80
	v_mul_f32_e32 v81, 0x2f800000, v80
	v_floor_f32_e32 v81, v81
	v_fmac_f32_e32 v80, 0xcf800000, v81
	v_cvt_u32_f32_e32 v80, v80
	v_cvt_u32_f32_e32 v81, v81
	v_lshl_add_u64 v[82:83], v[180:181], 3, s[10:11]
	global_atomic_add_x2 v[82:83], v[80:81], off
.LBB0_644:
	s_or_b64 exec, exec, s[26:27]
	s_waitcnt lgkmcnt(0)
	v_lshl_add_u64 v[80:81], v[176:177], 3, s[8:9]
	v_mov_b32_e32 v80, v236
	v_mov_b32_e32 v81, v237
	v_lshlrev_b32_e32 v84, 16, v124
	v_and_b32_e32 v85, 0xffff0000, v124
	v_lshlrev_b32_e32 v86, 16, v125
	v_and_b32_e32 v87, 0xffff0000, v125
	v_lshlrev_b32_e32 v96, 16, v114
	v_and_b32_e32 v97, 0xffff0000, v114
	v_lshlrev_b32_e32 v88, 16, v126
	v_and_b32_e32 v89, 0xffff0000, v126
	v_lshlrev_b32_e32 v90, 16, v127
	v_and_b32_e32 v91, 0xffff0000, v127
	v_lshlrev_b32_e32 v98, 16, v115
	v_and_b32_e32 v99, 0xffff0000, v115
	v_pk_add_f32 v[78:79], v[78:79], v[86:87]
	v_pk_add_f32 v[76:77], v[76:77], v[84:85]
	v_pk_add_f32 v[86:87], v[64:65], v[96:97]
	v_cvt_pk_bf16_f32 v64, v76, v77
	v_pk_add_f32 v[74:75], v[74:75], v[90:91]
	v_pk_add_f32 v[72:73], v[72:73], v[88:89]
	v_pk_add_f32 v[84:85], v[66:67], v[98:99]
	v_cvt_pk_bf16_f32 v65, v78, v79
	v_cvt_pk_bf16_f32 v66, v72, v73
	v_cvt_pk_bf16_f32 v67, v74, v75
	global_store_dwordx4 v[178:179], v[64:67], off
	v_mul_f32_e32 v88, v77, v77
	v_mul_f32_e32 v89, v79, v79
	v_mul_f32_e32 v90, v73, v73
	v_fmac_f32_e32 v88, v76, v76
	v_fmac_f32_e32 v89, v78, v78
	v_mul_f32_e32 v91, v75, v75
	v_fmac_f32_e32 v90, v72, v72
	v_fmac_f32_e32 v91, v74, v74
	v_lshlrev_b64 v[82:83], 12, v[176:177]
	v_lshlrev_b32_e32 v92, 16, v112
	v_and_b32_e32 v93, 0xffff0000, v112
	v_lshl_add_u64 v[82:83], v[82:83], 0, v[168:169]
	v_lshlrev_b32_e32 v94, 16, v113
	v_and_b32_e32 v95, 0xffff0000, v113
	v_pk_add_f32 v[68:69], v[68:69], v[92:93]
	v_lshl_add_u64 v[82:83], s[12:13], 0, v[82:83]
	v_pk_add_f32 v[70:71], v[70:71], v[94:95]
	v_ffbh_u32_e32 v64, v81
	v_min_u32_e32 v66, 32, v64
	v_lshlrev_b64 v[64:65], v66, v[80:81]
	v_min_u32_e32 v64, 1, v64
	v_or_b32_e32 v64, v65, v64
	v_cvt_f32_u32_e32 v64, v64
	v_sub_u32_e32 v65, 32, v66
	v_ldexp_f32 v64, v64, v65
	v_fmamk_f32 v64, v64, 0x2f800000, v196
	v_rsq_f32_e32 v64, v64
	v_add_f32_e32 v65, v88, v89
	v_add_f32_e32 v65, v90, v65
	v_add_f32_e32 v80, v91, v65
	v_mul_f32_e32 v81, 0x41b56db7, v64
	v_mul_f32_e32 v64, v76, v81
	v_mul_f32_e32 v65, v77, v81
	v_mul_f32_e32 v67, v79, v81
	v_mul_f32_e32 v73, v73, v81
	v_mul_f32_e32 v66, v78, v81
	v_mul_f32_e32 v72, v72, v81
	v_mul_f32_e32 v74, v74, v81
	v_mul_f32_e32 v75, v75, v81
	v_med3_f32 v64, v64, s52, v198
	v_med3_f32 v65, v65, s52, v198
	v_med3_f32 v67, v67, s52, v198
	v_med3_f32 v73, v73, s52, v198
	v_med3_f32 v66, v66, s52, v198
	v_med3_f32 v72, v72, s52, v198
	v_med3_f32 v74, v74, s52, v198
	v_med3_f32 v75, v75, s52, v198
	v_rndne_f32_e32 v64, v64
	v_rndne_f32_e32 v65, v65
	v_rndne_f32_e32 v67, v67
	v_rndne_f32_e32 v73, v73
	v_rndne_f32_e32 v66, v66
	v_rndne_f32_e32 v72, v72
	v_rndne_f32_e32 v74, v74
	v_rndne_f32_e32 v75, v75
	v_cvt_i32_f32_e32 v64, v64
	v_cvt_i32_f32_e32 v65, v65
	v_cvt_i32_f32_e32 v67, v67
	v_cvt_i32_f32_e32 v73, v73
	v_cvt_i32_f32_sdwa v66, v66 dst_sel:WORD_1 dst_unused:UNUSED_PAD src0_sel:DWORD
	v_cvt_i32_f32_e32 v72, v72
	v_cvt_i32_f32_sdwa v74, v74 dst_sel:WORD_1 dst_unused:UNUSED_PAD src0_sel:DWORD
	v_cvt_i32_f32_e32 v75, v75
	v_lshlrev_b32_e32 v65, 8, v65
	v_perm_b32 v64, v67, v64, s53
	v_lshlrev_b32_e32 v67, 8, v73
	v_and_b32_e32 v66, 0xff0000, v66
	v_and_b32_e32 v73, 0xff0000, v74
	v_perm_b32 v72, v75, v72, s53
	v_and_b32_e32 v65, 0xff00, v65
	v_and_b32_e32 v67, 0xff00, v67
	v_or3_b32 v64, v64, v65, v66
	v_or3_b32 v65, v72, v67, v73
	v_mul_f32_e32 v77, v69, v81
	global_store_dwordx2 v[82:83], v[64:65], off
	v_cvt_pk_bf16_f32 v64, v68, v69
	v_cvt_pk_bf16_f32 v65, v70, v71
	v_mul_f32_e32 v76, v68, v81
	v_mul_f32_e32 v78, v70, v81
	v_mul_f32_e32 v79, v71, v81
	v_cvt_pk_bf16_f32 v66, v86, v87
	v_cvt_pk_bf16_f32 v67, v84, v85
	global_store_dwordx4 v[178:179], v[64:67], off offset:256
	v_med3_f32 v76, v76, s52, v198
	v_mul_f32_e32 v72, v85, v81
	v_med3_f32 v65, v77, s52, v198
	v_rndne_f32_e32 v65, v65
	v_med3_f32 v66, v78, s52, v198
	v_med3_f32 v67, v79, s52, v198
	v_rndne_f32_e32 v64, v76
	v_cvt_i32_f32_e32 v65, v65
	v_rndne_f32_e32 v66, v66
	v_rndne_f32_e32 v67, v67
	v_cvt_i32_f32_e32 v64, v64
	v_cvt_i32_f32_sdwa v66, v66 dst_sel:WORD_1 dst_unused:UNUSED_PAD src0_sel:DWORD
	v_cvt_i32_f32_e32 v67, v67
	v_lshlrev_b32_e32 v65, 8, v65
	v_and_b32_e32 v65, 0xff00, v65
	v_and_b32_e32 v66, 0xff0000, v66
	v_perm_b32 v64, v67, v64, s53
	v_or3_b32 v66, v64, v65, v66
	v_mul_f32_e32 v65, v87, v81
	v_med3_f32 v65, v65, s52, v198
	v_rndne_f32_e32 v65, v65
	v_cvt_i32_f32_e32 v65, v65
	v_mul_f32_e32 v64, v86, v81
	v_med3_f32 v64, v64, s52, v198
	v_rndne_f32_e32 v64, v64
	v_mul_f32_e32 v67, v84, v81
	v_cvt_i32_f32_e32 v73, v64
	v_lshlrev_b32_e32 v64, 8, v65
	v_and_b32_e32 v74, 0xff00, v64
	v_med3_f32 v64, v67, s52, v198
	v_mul_f32_e32 v65, v69, v69
	v_mul_f32_e32 v67, v71, v71
	v_fmac_f32_e32 v65, v68, v68
	v_fmac_f32_e32 v67, v70, v70
	v_add_f32_e32 v65, v65, v67
	v_mul_f32_e32 v67, v87, v87
	v_fmac_f32_e32 v67, v86, v86
	v_add_f32_e32 v65, v67, v65
	v_mul_f32_e32 v67, v85, v85
	v_fmac_f32_e32 v67, v84, v84
	v_add_f32_e32 v65, v67, v65
	v_add_f32_e32 v65, v80, v65
	ds_bpermute_b32 v67, v116, v65
	v_rndne_f32_e32 v64, v64
	v_cvt_i32_f32_sdwa v68, v64 dst_sel:WORD_1 dst_unused:UNUSED_PAD src0_sel:DWORD
	v_med3_f32 v64, v72, s52, v198
	v_rndne_f32_e32 v64, v64
	v_cvt_i32_f32_e32 v69, v64
	s_waitcnt lgkmcnt(0)
	v_add_f32_e32 v64, v65, v67
	ds_bpermute_b32 v65, v117, v64
	v_and_b32_e32 v67, 0xff0000, v68
	v_perm_b32 v68, v69, v73, s53
	v_or3_b32 v67, v68, v74, v67
	global_store_dwordx2 v[82:83], v[66:67], off offset:128
	s_and_saveexec_b64 s[26:27], s[2:3]
	s_cbranch_execz .LBB0_646
	s_waitcnt lgkmcnt(0)
	v_add_f32_e32 v64, v64, v65
	v_fma_f32 v64, v64, s54, 0.5
	v_trunc_f32_e32 v64, v64
	v_mul_f32_e32 v65, 0x2f800000, v64
	v_floor_f32_e32 v65, v65
	v_fmac_f32_e32 v64, 0xcf800000, v65
	v_cvt_u32_f32_e32 v64, v64
	v_cvt_u32_f32_e32 v65, v65
	v_lshl_add_u64 v[66:67], v[176:177], 3, s[10:11]
	global_atomic_add_x2 v[66:67], v[64:65], off
.LBB0_646:
	s_or_b64 exec, exec, s[26:27]
	v_add_u32_e32 v100, 0x80, v174
	v_ashrrev_i32_e32 v101, 31, v100
	s_waitcnt lgkmcnt(0)
	v_lshlrev_b64 v[64:65], 13, v[100:101]
	v_lshl_add_u64 v[102:103], v[172:173], 0, v[64:65]
	v_mov_b32_e32 v112, v238
	v_mov_b32_e32 v113, v239
	v_mov_b32_e32 v104, v220
	v_mov_b32_e32 v105, v221
	v_mov_b32_e32 v106, v222
	v_mov_b32_e32 v107, v223
	v_add_u32_e32 v96, 0x90, v174
	v_add_u32_e32 v92, 0xa0, v174
	v_add_u32_e32 v88, 0xb0, v174
	v_ashrrev_i32_e32 v97, 31, v96
	v_ashrrev_i32_e32 v93, 31, v92
	v_ashrrev_i32_e32 v89, 31, v88
	v_lshlrev_b64 v[64:65], 13, v[96:97]
	v_lshlrev_b64 v[66:67], 13, v[92:93]
	v_lshlrev_b64 v[68:69], 13, v[88:89]
	v_lshlrev_b64 v[70:71], 12, v[100:101]
	v_lshl_add_u64 v[98:99], v[172:173], 0, v[64:65]
	v_lshl_add_u64 v[94:95], v[172:173], 0, v[66:67]
	v_lshl_add_u64 v[90:91], v[172:173], 0, v[68:69]
	v_lshl_add_u64 v[114:115], v[70:71], 0, v[168:169]
	v_mov_b32_e32 v108, v224
	v_mov_b32_e32 v109, v225
	v_mov_b32_e32 v110, v226
	v_mov_b32_e32 v111, v227
	v_mov_b32_e32 v84, v228
	v_mov_b32_e32 v85, v229
	v_mov_b32_e32 v86, v230
	v_mov_b32_e32 v87, v231
	v_mov_b32_e32 v80, v246
	v_mov_b32_e32 v81, v247
	v_mov_b32_e32 v82, v248
	v_mov_b32_e32 v83, v249
	v_mov_b32_e32 v76, v250
	v_mov_b32_e32 v77, v251
	v_mov_b32_e32 v78, v252
	v_mov_b32_e32 v79, v253
	v_mov_b32_e32 v72, v216
	v_mov_b32_e32 v73, v217
	v_mov_b32_e32 v74, v218
	v_mov_b32_e32 v75, v219
	global_load_dwordx4 v[68:71], v[90:91], off
	global_load_dwordx4 v[64:67], v[90:91], off offset:256
	v_lshl_add_u64 v[114:115], s[12:13], 0, v[114:115]
	v_ffbh_u32_e32 v122, v113
	v_min_u32_e32 v122, 32, v122
	v_lshlrev_b32_e32 v118, 16, v104
	v_and_b32_e32 v119, 0xffff0000, v104
	v_lshlrev_b32_e32 v104, 16, v105
	v_and_b32_e32 v105, 0xffff0000, v105
	v_lshlrev_b32_e32 v120, 16, v106
	v_and_b32_e32 v121, 0xffff0000, v106
	v_lshlrev_b32_e32 v106, 16, v107
	v_and_b32_e32 v107, 0xffff0000, v107
	v_lshlrev_b64 v[112:113], v122, v[112:113]
	v_pk_add_f32 v[62:63], v[62:63], v[104:105]
	v_pk_add_f32 v[60:61], v[60:61], v[118:119]
	v_pk_add_f32 v[104:105], v[58:59], v[106:107]
	v_pk_add_f32 v[106:107], v[56:57], v[120:121]
	v_cvt_pk_bf16_f32 v56, v60, v61
	v_min_u32_e32 v112, 1, v112
	v_cvt_pk_bf16_f32 v57, v62, v63
	v_cvt_pk_bf16_f32 v58, v106, v107
	v_cvt_pk_bf16_f32 v59, v104, v105
	global_store_dwordx4 v[102:103], v[56:59], off
	v_sub_u32_e32 v118, 32, v122
	v_mul_f32_e32 v119, v61, v61
	v_or_b32_e32 v56, v113, v112
	v_cvt_f32_u32_e32 v56, v56
	v_mul_f32_e32 v120, v63, v63
	v_mul_f32_e32 v121, v107, v107
	v_fmac_f32_e32 v119, v60, v60
	v_ldexp_f32 v56, v56, v118
	v_fmamk_f32 v56, v56, 0x2f800000, v196
	v_rsq_f32_e32 v56, v56
	v_fmac_f32_e32 v120, v62, v62
	v_mul_f32_e32 v122, v105, v105
	v_fmac_f32_e32 v121, v106, v106
	v_add_f32_e32 v57, v119, v120
	v_fmac_f32_e32 v122, v104, v104
	v_add_f32_e32 v57, v121, v57
	v_mul_f32_e32 v113, 0x41b56db7, v56
	v_add_f32_e32 v112, v122, v57
	v_mul_f32_e32 v56, v113, v60
	v_mul_f32_e32 v57, v113, v61
	v_mul_f32_e32 v59, v113, v63
	v_mul_f32_e32 v61, v113, v107
	v_mul_f32_e32 v58, v113, v62
	v_mul_f32_e32 v60, v113, v106
	v_mul_f32_e32 v62, v113, v104
	v_mul_f32_e32 v63, v113, v105
	v_med3_f32 v56, v56, s52, v198
	v_med3_f32 v57, v57, s52, v198
	v_med3_f32 v59, v59, s52, v198
	v_med3_f32 v61, v61, s52, v198
	v_med3_f32 v58, v58, s52, v198
	v_med3_f32 v60, v60, s52, v198
	v_med3_f32 v62, v62, s52, v198
	v_med3_f32 v63, v63, s52, v198
	v_rndne_f32_e32 v56, v56
	v_rndne_f32_e32 v57, v57
	v_rndne_f32_e32 v59, v59
	v_rndne_f32_e32 v61, v61
	v_rndne_f32_e32 v58, v58
	v_rndne_f32_e32 v60, v60
	v_rndne_f32_e32 v62, v62
	v_rndne_f32_e32 v63, v63
	v_cvt_i32_f32_e32 v56, v56
	v_cvt_i32_f32_e32 v57, v57
	v_cvt_i32_f32_e32 v59, v59
	v_cvt_i32_f32_e32 v61, v61
	v_cvt_i32_f32_sdwa v58, v58 dst_sel:WORD_1 dst_unused:UNUSED_PAD src0_sel:DWORD
	v_cvt_i32_f32_e32 v60, v60
	v_cvt_i32_f32_sdwa v62, v62 dst_sel:WORD_1 dst_unused:UNUSED_PAD src0_sel:DWORD
	v_cvt_i32_f32_e32 v63, v63
	v_lshlrev_b32_e32 v57, 8, v57
	v_perm_b32 v56, v59, v56, s53
	v_lshlrev_b32_e32 v59, 8, v61
	v_and_b32_e32 v58, 0xff0000, v58
	v_and_b32_e32 v61, 0xff0000, v62
	v_perm_b32 v60, v63, v60, s53
	v_and_b32_e32 v57, 0xff00, v57
	v_and_b32_e32 v59, 0xff00, v59
	v_or3_b32 v56, v56, v57, v58
	v_or3_b32 v57, v60, v59, v61
	global_store_dwordx2 v[114:115], v[56:57], off
	v_lshlrev_b32_e32 v56, 16, v108
	v_and_b32_e32 v57, 0xffff0000, v108
	v_lshlrev_b32_e32 v58, 16, v109
	v_and_b32_e32 v59, 0xffff0000, v109
	v_lshlrev_b32_e32 v60, 16, v110
	v_and_b32_e32 v61, 0xffff0000, v110
	v_lshlrev_b32_e32 v62, 16, v111
	v_and_b32_e32 v63, 0xffff0000, v111
	v_pk_add_f32 v[54:55], v[54:55], v[58:59]
	v_pk_add_f32 v[52:53], v[52:53], v[56:57]
	v_pk_add_f32 v[58:59], v[48:49], v[60:61]
	v_cvt_pk_bf16_f32 v48, v52, v53
	v_cvt_pk_bf16_f32 v49, v54, v55
	v_pk_add_f32 v[56:57], v[50:51], v[62:63]
	v_cvt_pk_bf16_f32 v50, v58, v59
	s_nop 0
	v_cvt_pk_bf16_f32 v51, v56, v57
	global_store_dwordx4 v[102:103], v[48:51], off offset:256
	v_mul_f32_e32 v60, v113, v57
	s_nop 0
	v_mul_f32_e32 v49, v113, v53
	v_mul_f32_e32 v48, v113, v52
	v_mul_f32_e32 v50, v113, v54
	v_mul_f32_e32 v51, v113, v55
	v_med3_f32 v49, v49, s52, v198
	v_med3_f32 v48, v48, s52, v198
	v_rndne_f32_e32 v49, v49
	v_med3_f32 v50, v50, s52, v198
	v_med3_f32 v51, v51, s52, v198
	v_rndne_f32_e32 v48, v48
	v_cvt_i32_f32_e32 v49, v49
	v_rndne_f32_e32 v50, v50
	v_rndne_f32_e32 v51, v51
	v_cvt_i32_f32_e32 v48, v48
	v_cvt_i32_f32_sdwa v50, v50 dst_sel:WORD_1 dst_unused:UNUSED_PAD src0_sel:DWORD
	v_cvt_i32_f32_e32 v51, v51
	v_lshlrev_b32_e32 v49, 8, v49
	v_and_b32_e32 v49, 0xff00, v49
	v_and_b32_e32 v50, 0xff0000, v50
	v_perm_b32 v48, v51, v48, s53
	v_or3_b32 v50, v48, v49, v50
	v_mul_f32_e32 v49, v113, v59
	v_med3_f32 v49, v49, s52, v198
	v_rndne_f32_e32 v49, v49
	v_cvt_i32_f32_e32 v49, v49
	v_mul_f32_e32 v48, v113, v58
	v_med3_f32 v48, v48, s52, v198
	v_rndne_f32_e32 v48, v48
	v_mul_f32_e32 v51, v113, v56
	v_cvt_i32_f32_e32 v61, v48
	v_lshlrev_b32_e32 v48, 8, v49
	v_and_b32_e32 v62, 0xff00, v48
	v_med3_f32 v48, v51, s52, v198
	v_mul_f32_e32 v49, v53, v53
	v_mul_f32_e32 v51, v55, v55
	v_fmac_f32_e32 v49, v52, v52
	v_fmac_f32_e32 v51, v54, v54
	v_add_f32_e32 v49, v49, v51
	v_mul_f32_e32 v51, v59, v59
	v_fmac_f32_e32 v51, v58, v58
	v_add_f32_e32 v49, v51, v49
	v_mul_f32_e32 v51, v57, v57
	v_fmac_f32_e32 v51, v56, v56
	v_add_f32_e32 v49, v51, v49
	v_add_f32_e32 v49, v112, v49
	ds_bpermute_b32 v51, v116, v49
	v_rndne_f32_e32 v48, v48
	v_cvt_i32_f32_sdwa v52, v48 dst_sel:WORD_1 dst_unused:UNUSED_PAD src0_sel:DWORD
	v_med3_f32 v48, v60, s52, v198
	v_rndne_f32_e32 v48, v48
	v_cvt_i32_f32_e32 v53, v48
	s_waitcnt lgkmcnt(0)
	v_add_f32_e32 v48, v49, v51
	ds_bpermute_b32 v49, v117, v48
	v_and_b32_e32 v51, 0xff0000, v52
	v_perm_b32 v52, v53, v61, s53
	v_or3_b32 v51, v52, v62, v51
	global_store_dwordx2 v[114:115], v[50:51], off offset:128
	s_and_saveexec_b64 s[26:27], s[2:3]
	s_cbranch_execz .LBB0_648
	s_waitcnt lgkmcnt(0)
	v_add_f32_e32 v48, v48, v49
	v_fma_f32 v48, v48, s54, 0.5
	v_trunc_f32_e32 v48, v48
	v_mul_f32_e32 v49, 0x2f800000, v48
	v_floor_f32_e32 v49, v49
	v_fmac_f32_e32 v48, 0xcf800000, v49
	v_cvt_u32_f32_e32 v48, v48
	v_cvt_u32_f32_e32 v49, v49
	v_lshl_add_u64 v[50:51], v[100:101], 3, s[10:11]
	global_atomic_add_x2 v[50:51], v[48:49], off
.LBB0_648:
	s_or_b64 exec, exec, s[26:27]
	s_waitcnt lgkmcnt(0)
	v_mov_b32_e32 v48, v240
	v_mov_b32_e32 v49, v241
	v_lshlrev_b32_e32 v52, 16, v84
	v_and_b32_e32 v53, 0xffff0000, v84
	v_lshlrev_b32_e32 v54, 16, v85
	v_and_b32_e32 v55, 0xffff0000, v85
	v_lshlrev_b32_e32 v60, 16, v80
	v_and_b32_e32 v61, 0xffff0000, v80
	v_lshlrev_b32_e32 v62, 16, v81
	v_and_b32_e32 v63, 0xffff0000, v81
	v_lshlrev_b32_e32 v80, 16, v82
	v_and_b32_e32 v81, 0xffff0000, v82
	v_lshlrev_b32_e32 v56, 16, v86
	v_and_b32_e32 v57, 0xffff0000, v86
	v_lshlrev_b32_e32 v58, 16, v87
	v_and_b32_e32 v59, 0xffff0000, v87
	v_lshlrev_b32_e32 v82, 16, v83
	v_and_b32_e32 v83, 0xffff0000, v83
	v_pk_add_f32 v[46:47], v[46:47], v[54:55]
	v_pk_add_f32 v[44:45], v[44:45], v[52:53]
	v_pk_add_f32 v[54:55], v[32:33], v[80:81]
	v_cvt_pk_bf16_f32 v32, v44, v45
	v_pk_add_f32 v[42:43], v[42:43], v[58:59]
	v_pk_add_f32 v[40:41], v[40:41], v[56:57]
	v_pk_add_f32 v[52:53], v[34:35], v[82:83]
	v_cvt_pk_bf16_f32 v33, v46, v47
	v_cvt_pk_bf16_f32 v34, v40, v41
	v_cvt_pk_bf16_f32 v35, v42, v43
	global_store_dwordx4 v[98:99], v[32:35], off
	v_mul_f32_e32 v56, v45, v45
	v_mul_f32_e32 v57, v47, v47
	v_mul_f32_e32 v58, v41, v41
	v_fmac_f32_e32 v56, v44, v44
	v_fmac_f32_e32 v57, v46, v46
	v_mul_f32_e32 v59, v43, v43
	v_fmac_f32_e32 v58, v40, v40
	v_fmac_f32_e32 v59, v42, v42
	v_lshlrev_b64 v[50:51], 12, v[96:97]
	v_lshl_add_u64 v[50:51], v[50:51], 0, v[168:169]
	v_pk_add_f32 v[36:37], v[36:37], v[60:61]
	v_lshl_add_u64 v[50:51], s[12:13], 0, v[50:51]
	v_pk_add_f32 v[38:39], v[38:39], v[62:63]
	s_waitcnt vmcnt(6)
	v_ffbh_u32_e32 v32, v49
	v_min_u32_e32 v34, 32, v32
	v_lshlrev_b64 v[32:33], v34, v[48:49]
	v_min_u32_e32 v32, 1, v32
	v_or_b32_e32 v32, v33, v32
	v_cvt_f32_u32_e32 v32, v32
	v_sub_u32_e32 v33, 32, v34
	v_ldexp_f32 v32, v32, v33
	v_fmamk_f32 v32, v32, 0x2f800000, v196
	v_rsq_f32_e32 v32, v32
	v_add_f32_e32 v33, v56, v57
	v_add_f32_e32 v33, v58, v33
	v_add_f32_e32 v48, v59, v33
	v_mul_f32_e32 v49, 0x41b56db7, v32
	v_mul_f32_e32 v32, v44, v49
	v_mul_f32_e32 v33, v45, v49
	v_mul_f32_e32 v35, v47, v49
	v_mul_f32_e32 v41, v41, v49
	v_mul_f32_e32 v34, v46, v49
	v_mul_f32_e32 v40, v40, v49
	v_mul_f32_e32 v42, v42, v49
	v_mul_f32_e32 v43, v43, v49
	v_med3_f32 v32, v32, s52, v198
	v_med3_f32 v33, v33, s52, v198
	v_med3_f32 v35, v35, s52, v198
	v_med3_f32 v41, v41, s52, v198
	v_med3_f32 v34, v34, s52, v198
	v_med3_f32 v40, v40, s52, v198
	v_med3_f32 v42, v42, s52, v198
	v_med3_f32 v43, v43, s52, v198
	v_rndne_f32_e32 v32, v32
	v_rndne_f32_e32 v33, v33
	v_rndne_f32_e32 v35, v35
	v_rndne_f32_e32 v41, v41
	v_rndne_f32_e32 v34, v34
	v_rndne_f32_e32 v40, v40
	v_rndne_f32_e32 v42, v42
	v_rndne_f32_e32 v43, v43
	v_cvt_i32_f32_e32 v32, v32
	v_cvt_i32_f32_e32 v33, v33
	v_cvt_i32_f32_e32 v35, v35
	v_cvt_i32_f32_e32 v41, v41
	v_cvt_i32_f32_sdwa v34, v34 dst_sel:WORD_1 dst_unused:UNUSED_PAD src0_sel:DWORD
	v_cvt_i32_f32_e32 v40, v40
	v_cvt_i32_f32_sdwa v42, v42 dst_sel:WORD_1 dst_unused:UNUSED_PAD src0_sel:DWORD
	v_cvt_i32_f32_e32 v43, v43
	v_lshlrev_b32_e32 v33, 8, v33
	v_perm_b32 v32, v35, v32, s53
	v_lshlrev_b32_e32 v35, 8, v41
	v_and_b32_e32 v34, 0xff0000, v34
	v_and_b32_e32 v41, 0xff0000, v42
	v_perm_b32 v40, v43, v40, s53
	v_and_b32_e32 v33, 0xff00, v33
	v_and_b32_e32 v35, 0xff00, v35
	v_or3_b32 v32, v32, v33, v34
	v_or3_b32 v33, v40, v35, v41
	v_mul_f32_e32 v45, v37, v49
	global_store_dwordx2 v[50:51], v[32:33], off
	v_cvt_pk_bf16_f32 v32, v36, v37
	v_cvt_pk_bf16_f32 v33, v38, v39
	v_mul_f32_e32 v44, v36, v49
	v_mul_f32_e32 v46, v38, v49
	v_mul_f32_e32 v47, v39, v49
	v_cvt_pk_bf16_f32 v34, v54, v55
	v_cvt_pk_bf16_f32 v35, v52, v53
	global_store_dwordx4 v[98:99], v[32:35], off offset:256
	v_med3_f32 v44, v44, s52, v198
	v_mul_f32_e32 v40, v53, v49
	v_med3_f32 v33, v45, s52, v198
	v_rndne_f32_e32 v33, v33
	v_med3_f32 v34, v46, s52, v198
	v_med3_f32 v35, v47, s52, v198
	v_rndne_f32_e32 v32, v44
	v_cvt_i32_f32_e32 v33, v33
	v_rndne_f32_e32 v34, v34
	v_rndne_f32_e32 v35, v35
	v_cvt_i32_f32_e32 v32, v32
	v_cvt_i32_f32_sdwa v34, v34 dst_sel:WORD_1 dst_unused:UNUSED_PAD src0_sel:DWORD
	v_cvt_i32_f32_e32 v35, v35
	v_lshlrev_b32_e32 v33, 8, v33
	v_and_b32_e32 v33, 0xff00, v33
	v_and_b32_e32 v34, 0xff0000, v34
	v_perm_b32 v32, v35, v32, s53
	v_or3_b32 v34, v32, v33, v34
	v_mul_f32_e32 v33, v55, v49
	v_med3_f32 v33, v33, s52, v198
	v_rndne_f32_e32 v33, v33
	v_cvt_i32_f32_e32 v33, v33
	v_mul_f32_e32 v32, v54, v49
	v_med3_f32 v32, v32, s52, v198
	v_rndne_f32_e32 v32, v32
	v_mul_f32_e32 v35, v52, v49
	v_cvt_i32_f32_e32 v41, v32
	v_lshlrev_b32_e32 v32, 8, v33
	v_and_b32_e32 v42, 0xff00, v32
	v_med3_f32 v32, v35, s52, v198
	v_mul_f32_e32 v33, v37, v37
	v_mul_f32_e32 v35, v39, v39
	v_fmac_f32_e32 v33, v36, v36
	v_fmac_f32_e32 v35, v38, v38
	v_add_f32_e32 v33, v33, v35
	v_mul_f32_e32 v35, v55, v55
	v_fmac_f32_e32 v35, v54, v54
	v_add_f32_e32 v33, v35, v33
	v_mul_f32_e32 v35, v53, v53
	v_fmac_f32_e32 v35, v52, v52
	v_add_f32_e32 v33, v35, v33
	v_add_f32_e32 v33, v48, v33
	ds_bpermute_b32 v35, v116, v33
	v_rndne_f32_e32 v32, v32
	v_cvt_i32_f32_sdwa v36, v32 dst_sel:WORD_1 dst_unused:UNUSED_PAD src0_sel:DWORD
	v_med3_f32 v32, v40, s52, v198
	v_rndne_f32_e32 v32, v32
	v_cvt_i32_f32_e32 v37, v32
	s_waitcnt lgkmcnt(0)
	v_add_f32_e32 v32, v33, v35
	ds_bpermute_b32 v33, v117, v32
	v_and_b32_e32 v35, 0xff0000, v36
	v_perm_b32 v36, v37, v41, s53
	v_or3_b32 v35, v36, v42, v35
	global_store_dwordx2 v[50:51], v[34:35], off offset:128
	s_and_saveexec_b64 s[26:27], s[2:3]
	s_cbranch_execz .LBB0_650
	s_waitcnt lgkmcnt(0)
	v_add_f32_e32 v32, v32, v33
	v_fma_f32 v32, v32, s54, 0.5
	v_trunc_f32_e32 v32, v32
	v_mul_f32_e32 v33, 0x2f800000, v32
	v_floor_f32_e32 v33, v33
	v_fmac_f32_e32 v32, 0xcf800000, v33
	v_cvt_u32_f32_e32 v32, v32
	v_cvt_u32_f32_e32 v33, v33
	v_lshl_add_u64 v[34:35], v[96:97], 3, s[10:11]
	global_atomic_add_x2 v[34:35], v[32:33], off
.LBB0_650:
	s_or_b64 exec, exec, s[26:27]
	s_waitcnt lgkmcnt(0)
	v_mov_b32_e32 v32, v242
	v_mov_b32_e32 v33, v243
	v_lshlrev_b32_e32 v36, 16, v76
	v_and_b32_e32 v37, 0xffff0000, v76
	v_lshlrev_b32_e32 v38, 16, v77
	v_and_b32_e32 v39, 0xffff0000, v77
	v_lshlrev_b32_e32 v48, 16, v74
	v_and_b32_e32 v49, 0xffff0000, v74
	v_lshlrev_b32_e32 v40, 16, v78
	v_and_b32_e32 v41, 0xffff0000, v78
	v_lshlrev_b32_e32 v42, 16, v79
	v_and_b32_e32 v43, 0xffff0000, v79
	v_lshlrev_b32_e32 v50, 16, v75
	v_and_b32_e32 v51, 0xffff0000, v75
	v_pk_add_f32 v[30:31], v[30:31], v[38:39]
	v_pk_add_f32 v[28:29], v[28:29], v[36:37]
	v_pk_add_f32 v[38:39], v[16:17], v[48:49]
	v_cvt_pk_bf16_f32 v16, v28, v29
	v_pk_add_f32 v[26:27], v[26:27], v[42:43]
	v_pk_add_f32 v[24:25], v[24:25], v[40:41]
	v_pk_add_f32 v[36:37], v[18:19], v[50:51]
	v_cvt_pk_bf16_f32 v17, v30, v31
	v_cvt_pk_bf16_f32 v18, v24, v25
	v_cvt_pk_bf16_f32 v19, v26, v27
	global_store_dwordx4 v[94:95], v[16:19], off
	v_mul_f32_e32 v40, v29, v29
	v_mul_f32_e32 v41, v31, v31
	v_mul_f32_e32 v42, v25, v25
	v_fmac_f32_e32 v40, v28, v28
	v_fmac_f32_e32 v41, v30, v30
	v_mul_f32_e32 v43, v27, v27
	v_fmac_f32_e32 v42, v24, v24
	v_fmac_f32_e32 v43, v26, v26
	v_lshlrev_b64 v[34:35], 12, v[92:93]
	v_lshlrev_b32_e32 v44, 16, v72
	v_and_b32_e32 v45, 0xffff0000, v72
	v_lshl_add_u64 v[34:35], v[34:35], 0, v[168:169]
	v_lshlrev_b32_e32 v46, 16, v73
	v_and_b32_e32 v47, 0xffff0000, v73
	v_pk_add_f32 v[20:21], v[20:21], v[44:45]
	v_lshl_add_u64 v[34:35], s[12:13], 0, v[34:35]
	v_pk_add_f32 v[22:23], v[22:23], v[46:47]
	s_waitcnt vmcnt(11)
	v_ffbh_u32_e32 v16, v33
	v_min_u32_e32 v18, 32, v16
	v_lshlrev_b64 v[16:17], v18, v[32:33]
	v_min_u32_e32 v16, 1, v16
	v_or_b32_e32 v16, v17, v16
	v_cvt_f32_u32_e32 v16, v16
	v_sub_u32_e32 v17, 32, v18
	v_ldexp_f32 v16, v16, v17
	v_fmamk_f32 v16, v16, 0x2f800000, v196
	v_rsq_f32_e32 v16, v16
	v_add_f32_e32 v17, v40, v41
	v_add_f32_e32 v17, v42, v17
	v_add_f32_e32 v32, v43, v17
	v_mul_f32_e32 v33, 0x41b56db7, v16
	v_mul_f32_e32 v16, v28, v33
	v_mul_f32_e32 v17, v29, v33
	v_mul_f32_e32 v19, v31, v33
	v_mul_f32_e32 v25, v25, v33
	v_mul_f32_e32 v18, v30, v33
	v_mul_f32_e32 v24, v24, v33
	v_mul_f32_e32 v26, v26, v33
	v_mul_f32_e32 v27, v27, v33
	v_med3_f32 v16, v16, s52, v198
	v_med3_f32 v17, v17, s52, v198
	v_med3_f32 v19, v19, s52, v198
	v_med3_f32 v25, v25, s52, v198
	v_med3_f32 v18, v18, s52, v198
	v_med3_f32 v24, v24, s52, v198
	v_med3_f32 v26, v26, s52, v198
	v_med3_f32 v27, v27, s52, v198
	v_rndne_f32_e32 v16, v16
	v_rndne_f32_e32 v17, v17
	v_rndne_f32_e32 v19, v19
	v_rndne_f32_e32 v25, v25
	v_rndne_f32_e32 v18, v18
	v_rndne_f32_e32 v24, v24
	v_rndne_f32_e32 v26, v26
	v_rndne_f32_e32 v27, v27
	v_cvt_i32_f32_e32 v16, v16
	v_cvt_i32_f32_e32 v17, v17
	v_cvt_i32_f32_e32 v19, v19
	v_cvt_i32_f32_e32 v25, v25
	v_cvt_i32_f32_sdwa v18, v18 dst_sel:WORD_1 dst_unused:UNUSED_PAD src0_sel:DWORD
	v_cvt_i32_f32_e32 v24, v24
	v_cvt_i32_f32_sdwa v26, v26 dst_sel:WORD_1 dst_unused:UNUSED_PAD src0_sel:DWORD
	v_cvt_i32_f32_e32 v27, v27
	v_lshlrev_b32_e32 v17, 8, v17
	v_perm_b32 v16, v19, v16, s53
	v_lshlrev_b32_e32 v19, 8, v25
	v_and_b32_e32 v18, 0xff0000, v18
	v_and_b32_e32 v25, 0xff0000, v26
	v_perm_b32 v24, v27, v24, s53
	v_and_b32_e32 v17, 0xff00, v17
	v_and_b32_e32 v19, 0xff00, v19
	v_or3_b32 v16, v16, v17, v18
	v_or3_b32 v17, v24, v19, v25
	v_mul_f32_e32 v29, v21, v33
	global_store_dwordx2 v[34:35], v[16:17], off
	v_cvt_pk_bf16_f32 v16, v20, v21
	v_cvt_pk_bf16_f32 v17, v22, v23
	v_mul_f32_e32 v28, v20, v33
	v_mul_f32_e32 v30, v22, v33
	v_mul_f32_e32 v31, v23, v33
	v_cvt_pk_bf16_f32 v18, v38, v39
	v_cvt_pk_bf16_f32 v19, v36, v37
	global_store_dwordx4 v[94:95], v[16:19], off offset:256
	v_med3_f32 v28, v28, s52, v198
	v_mul_f32_e32 v24, v37, v33
	v_med3_f32 v17, v29, s52, v198
	v_rndne_f32_e32 v17, v17
	v_med3_f32 v18, v30, s52, v198
	v_med3_f32 v19, v31, s52, v198
	v_rndne_f32_e32 v16, v28
	v_cvt_i32_f32_e32 v17, v17
	v_rndne_f32_e32 v18, v18
	v_rndne_f32_e32 v19, v19
	v_cvt_i32_f32_e32 v16, v16
	v_cvt_i32_f32_sdwa v18, v18 dst_sel:WORD_1 dst_unused:UNUSED_PAD src0_sel:DWORD
	v_cvt_i32_f32_e32 v19, v19
	v_lshlrev_b32_e32 v17, 8, v17
	v_and_b32_e32 v17, 0xff00, v17
	v_and_b32_e32 v18, 0xff0000, v18
	v_perm_b32 v16, v19, v16, s53
	v_or3_b32 v18, v16, v17, v18
	v_mul_f32_e32 v17, v39, v33
	v_med3_f32 v17, v17, s52, v198
	v_rndne_f32_e32 v17, v17
	v_cvt_i32_f32_e32 v17, v17
	v_mul_f32_e32 v16, v38, v33
	v_med3_f32 v16, v16, s52, v198
	v_rndne_f32_e32 v16, v16
	v_mul_f32_e32 v19, v36, v33
	v_cvt_i32_f32_e32 v25, v16
	v_lshlrev_b32_e32 v16, 8, v17
	v_and_b32_e32 v26, 0xff00, v16
	v_med3_f32 v16, v19, s52, v198
	v_mul_f32_e32 v17, v21, v21
	v_mul_f32_e32 v19, v23, v23
	v_fmac_f32_e32 v17, v20, v20
	v_fmac_f32_e32 v19, v22, v22
	v_add_f32_e32 v17, v17, v19
	v_mul_f32_e32 v19, v39, v39
	v_fmac_f32_e32 v19, v38, v38
	v_add_f32_e32 v17, v19, v17
	v_mul_f32_e32 v19, v37, v37
	v_fmac_f32_e32 v19, v36, v36
	v_add_f32_e32 v17, v19, v17
	v_add_f32_e32 v17, v32, v17
	ds_bpermute_b32 v19, v116, v17
	v_rndne_f32_e32 v16, v16
	v_cvt_i32_f32_sdwa v20, v16 dst_sel:WORD_1 dst_unused:UNUSED_PAD src0_sel:DWORD
	v_med3_f32 v16, v24, s52, v198
	v_rndne_f32_e32 v16, v16
	v_cvt_i32_f32_e32 v21, v16
	s_waitcnt lgkmcnt(0)
	v_add_f32_e32 v16, v17, v19
	ds_bpermute_b32 v17, v117, v16
	v_and_b32_e32 v19, 0xff0000, v20
	v_perm_b32 v20, v21, v25, s53
	v_or3_b32 v19, v20, v26, v19
	global_store_dwordx2 v[34:35], v[18:19], off offset:128
	s_and_saveexec_b64 s[26:27], s[2:3]
	s_cbranch_execz .LBB0_652
	s_waitcnt lgkmcnt(0)
	v_add_f32_e32 v16, v16, v17
	v_fma_f32 v16, v16, s54, 0.5
	v_trunc_f32_e32 v16, v16
	v_mul_f32_e32 v17, 0x2f800000, v16
	v_floor_f32_e32 v17, v17
	v_fmac_f32_e32 v16, 0xcf800000, v17
	v_cvt_u32_f32_e32 v16, v16
	v_cvt_u32_f32_e32 v17, v17
	v_lshl_add_u64 v[18:19], v[92:93], 3, s[10:11]
	global_atomic_add_x2 v[18:19], v[16:17], off
.LBB0_652:
	s_or_b64 exec, exec, s[26:27]
	s_waitcnt lgkmcnt(0)
	v_mov_b32_e32 v16, v244
	v_mov_b32_e32 v17, v245
	v_lshlrev_b32_e32 v20, 16, v68
	v_and_b32_e32 v21, 0xffff0000, v68
	v_lshlrev_b32_e32 v22, 16, v69
	v_and_b32_e32 v23, 0xffff0000, v69
	v_lshlrev_b32_e32 v32, 16, v66
	v_and_b32_e32 v33, 0xffff0000, v66
	v_lshlrev_b32_e32 v24, 16, v70
	v_and_b32_e32 v25, 0xffff0000, v70
	v_lshlrev_b32_e32 v26, 16, v71
	v_and_b32_e32 v27, 0xffff0000, v71
	v_lshlrev_b32_e32 v34, 16, v67
	v_and_b32_e32 v35, 0xffff0000, v67
	v_pk_add_f32 v[14:15], v[14:15], v[22:23]
	v_pk_add_f32 v[12:13], v[12:13], v[20:21]
	v_pk_add_f32 v[22:23], v[0:1], v[32:33]
	v_cvt_pk_bf16_f32 v0, v12, v13
	v_pk_add_f32 v[10:11], v[10:11], v[26:27]
	v_pk_add_f32 v[8:9], v[8:9], v[24:25]
	v_pk_add_f32 v[20:21], v[2:3], v[34:35]
	v_cvt_pk_bf16_f32 v1, v14, v15
	v_cvt_pk_bf16_f32 v2, v8, v9
	v_cvt_pk_bf16_f32 v3, v10, v11
	global_store_dwordx4 v[90:91], v[0:3], off
	v_mul_f32_e32 v24, v13, v13
	v_mul_f32_e32 v25, v15, v15
	v_mul_f32_e32 v26, v9, v9
	v_fmac_f32_e32 v24, v12, v12
	v_fmac_f32_e32 v25, v14, v14
	v_mul_f32_e32 v27, v11, v11
	v_fmac_f32_e32 v26, v8, v8
	v_fmac_f32_e32 v27, v10, v10
	v_lshlrev_b64 v[18:19], 12, v[88:89]
	v_lshlrev_b32_e32 v28, 16, v64
	v_and_b32_e32 v29, 0xffff0000, v64
	v_lshl_add_u64 v[18:19], v[18:19], 0, v[168:169]
	v_lshlrev_b32_e32 v30, 16, v65
	v_and_b32_e32 v31, 0xffff0000, v65
	v_pk_add_f32 v[4:5], v[4:5], v[28:29]
	v_lshl_add_u64 v[18:19], s[12:13], 0, v[18:19]
	v_pk_add_f32 v[6:7], v[6:7], v[30:31]
	s_waitcnt vmcnt(16)
	v_ffbh_u32_e32 v0, v17
	v_min_u32_e32 v2, 32, v0
	v_lshlrev_b64 v[0:1], v2, v[16:17]
	v_min_u32_e32 v0, 1, v0
	v_or_b32_e32 v0, v1, v0
	v_cvt_f32_u32_e32 v0, v0
	v_sub_u32_e32 v1, 32, v2
	v_ldexp_f32 v0, v0, v1
	v_fmamk_f32 v0, v0, 0x2f800000, v196
	v_rsq_f32_e32 v0, v0
	v_add_f32_e32 v1, v24, v25
	v_add_f32_e32 v1, v26, v1
	v_add_f32_e32 v16, v27, v1
	v_mul_f32_e32 v17, 0x41b56db7, v0
	v_mul_f32_e32 v0, v12, v17
	v_mul_f32_e32 v1, v13, v17
	v_mul_f32_e32 v3, v15, v17
	v_mul_f32_e32 v9, v9, v17
	v_mul_f32_e32 v2, v14, v17
	v_mul_f32_e32 v8, v8, v17
	v_mul_f32_e32 v10, v10, v17
	v_mul_f32_e32 v11, v11, v17
	v_med3_f32 v0, v0, s52, v198
	v_med3_f32 v1, v1, s52, v198
	v_med3_f32 v3, v3, s52, v198
	v_med3_f32 v9, v9, s52, v198
	v_med3_f32 v2, v2, s52, v198
	v_med3_f32 v8, v8, s52, v198
	v_med3_f32 v10, v10, s52, v198
	v_med3_f32 v11, v11, s52, v198
	v_rndne_f32_e32 v0, v0
	v_rndne_f32_e32 v1, v1
	v_rndne_f32_e32 v3, v3
	v_rndne_f32_e32 v9, v9
	v_rndne_f32_e32 v2, v2
	v_rndne_f32_e32 v8, v8
	v_rndne_f32_e32 v10, v10
	v_rndne_f32_e32 v11, v11
	v_cvt_i32_f32_e32 v0, v0
	v_cvt_i32_f32_e32 v1, v1
	v_cvt_i32_f32_e32 v3, v3
	v_cvt_i32_f32_e32 v9, v9
	v_cvt_i32_f32_sdwa v2, v2 dst_sel:WORD_1 dst_unused:UNUSED_PAD src0_sel:DWORD
	v_cvt_i32_f32_e32 v8, v8
	v_cvt_i32_f32_sdwa v10, v10 dst_sel:WORD_1 dst_unused:UNUSED_PAD src0_sel:DWORD
	v_cvt_i32_f32_e32 v11, v11
	v_lshlrev_b32_e32 v1, 8, v1
	v_perm_b32 v0, v3, v0, s53
	v_lshlrev_b32_e32 v3, 8, v9
	v_and_b32_e32 v2, 0xff0000, v2
	v_and_b32_e32 v9, 0xff0000, v10
	v_perm_b32 v8, v11, v8, s53
	v_and_b32_e32 v1, 0xff00, v1
	v_and_b32_e32 v3, 0xff00, v3
	v_or3_b32 v0, v0, v1, v2
	v_or3_b32 v1, v8, v3, v9
	v_mul_f32_e32 v13, v5, v17
	global_store_dwordx2 v[18:19], v[0:1], off
	v_cvt_pk_bf16_f32 v0, v4, v5
	v_cvt_pk_bf16_f32 v1, v6, v7
	v_mul_f32_e32 v12, v4, v17
	v_mul_f32_e32 v14, v6, v17
	v_mul_f32_e32 v15, v7, v17
	v_cvt_pk_bf16_f32 v2, v22, v23
	v_cvt_pk_bf16_f32 v3, v20, v21
	global_store_dwordx4 v[90:91], v[0:3], off offset:256
	v_med3_f32 v12, v12, s52, v198
	v_mul_f32_e32 v8, v21, v17
	v_med3_f32 v1, v13, s52, v198
	v_rndne_f32_e32 v1, v1
	v_med3_f32 v2, v14, s52, v198
	v_med3_f32 v3, v15, s52, v198
	v_rndne_f32_e32 v0, v12
	v_cvt_i32_f32_e32 v1, v1
	v_rndne_f32_e32 v2, v2
	v_rndne_f32_e32 v3, v3
	v_cvt_i32_f32_e32 v0, v0
	v_cvt_i32_f32_sdwa v2, v2 dst_sel:WORD_1 dst_unused:UNUSED_PAD src0_sel:DWORD
	v_cvt_i32_f32_e32 v3, v3
	v_lshlrev_b32_e32 v1, 8, v1
	v_and_b32_e32 v1, 0xff00, v1
	v_and_b32_e32 v2, 0xff0000, v2
	v_perm_b32 v0, v3, v0, s53
	v_or3_b32 v2, v0, v1, v2
	v_mul_f32_e32 v1, v23, v17
	v_med3_f32 v1, v1, s52, v198
	v_rndne_f32_e32 v1, v1
	v_cvt_i32_f32_e32 v1, v1
	v_mul_f32_e32 v0, v22, v17
	v_med3_f32 v0, v0, s52, v198
	v_rndne_f32_e32 v0, v0
	v_mul_f32_e32 v3, v20, v17
	v_cvt_i32_f32_e32 v9, v0
	v_lshlrev_b32_e32 v0, 8, v1
	v_and_b32_e32 v10, 0xff00, v0
	v_med3_f32 v0, v3, s52, v198
	v_mul_f32_e32 v1, v5, v5
	v_mul_f32_e32 v3, v7, v7
	v_fmac_f32_e32 v1, v4, v4
	v_fmac_f32_e32 v3, v6, v6
	v_add_f32_e32 v1, v1, v3
	v_mul_f32_e32 v3, v23, v23
	v_fmac_f32_e32 v3, v22, v22
	v_add_f32_e32 v1, v3, v1
	v_mul_f32_e32 v3, v21, v21
	v_fmac_f32_e32 v3, v20, v20
	v_add_f32_e32 v1, v3, v1
	v_add_f32_e32 v1, v16, v1
	ds_bpermute_b32 v3, v116, v1
	v_rndne_f32_e32 v0, v0
	v_cvt_i32_f32_sdwa v4, v0 dst_sel:WORD_1 dst_unused:UNUSED_PAD src0_sel:DWORD
	v_med3_f32 v0, v8, s52, v198
	v_rndne_f32_e32 v0, v0
	v_cvt_i32_f32_e32 v5, v0
	s_waitcnt lgkmcnt(0)
	v_add_f32_e32 v0, v1, v3
	ds_bpermute_b32 v1, v117, v0
	v_and_b32_e32 v3, 0xff0000, v4
	v_perm_b32 v4, v5, v9, s53
	v_or3_b32 v3, v4, v10, v3
	global_store_dwordx2 v[18:19], v[2:3], off offset:128
	s_and_saveexec_b64 s[26:27], s[2:3]
	s_cbranch_execz .LBB0_654
	s_waitcnt lgkmcnt(0)
	v_add_f32_e32 v0, v0, v1
	v_fma_f32 v0, v0, s54, 0.5
	v_trunc_f32_e32 v0, v0
	v_mul_f32_e32 v1, 0x2f800000, v0
	v_floor_f32_e32 v1, v1
	v_fmac_f32_e32 v0, 0xcf800000, v1
	v_cvt_u32_f32_e32 v0, v0
	v_cvt_u32_f32_e32 v1, v1
	v_lshl_add_u64 v[2:3], v[88:89], 3, s[10:11]
	global_atomic_add_x2 v[2:3], v[0:1], off

.LBB0_715:
	s_mov_b64 s[0:1], s[78:79]
	s_load_dword s0, s[0:1], 0xa8
	s_waitcnt lgkmcnt(0)
	s_cmp_gt_i32 s0, 7
	s_cbranch_scc1 .LBB0_733
	s_mov_b64 s[0:1], s[78:79]
	s_load_dword s0, s[0:1], 0xac
	s_waitcnt lgkmcnt(0)
	s_cmp_lt_i32 s0, 8
	s_cbranch_scc1 .LBB0_733
	s_mov_b32 s95, -1
	s_mov_b64 s[0:1], s[78:79]
	s_mov_b32 s4, -1
	s_cmpk_gt_i32 s87, 0x9ff
	s_cbranch_scc1 .LBB0_733
	s_load_dwordx2 s[2:3], s[0:1], 0xa0
	v_mbcnt_lo_u32_b32 v0, s4, 0
	v_mbcnt_hi_u32_b32 v9, s4, v0
	s_mov_b32 s0, 0xfffe0
	s_movk_i32 s37, 0x141
	s_waitcnt lgkmcnt(0)
	s_add_u32 s30, s2, 0x38400000
	s_addc_u32 s31, s3, 0
	s_add_u32 s33, s2, 0x8a00000
	s_addc_u32 s34, s3, 0
	s_lshl_b32 s35, s81, 10
	v_lshl_add_u32 v0, v9, 4, s35
	v_add_u32_e32 v1, 0x2000, v0
	v_ashrrev_i32_e32 v2, 31, v1
	v_lshrrev_b32_e32 v2, 22, v2
	v_add_u32_e32 v2, v1, v2
	v_ashrrev_i32_e32 v8, 10, v2
	v_mul_i32_i24_e32 v2, 0x400, v8
	v_sub_u32_e32 v1, v1, v2
	v_lshrrev_b32_e32 v2, 4, v1
	v_bitop3_b32 v1, v2, v1, 32 bitop3:0x6c
	v_ashrrev_i32_e32 v2, 31, v1
	v_lshrrev_b32_e32 v2, 26, v2
	v_add_u32_e32 v2, v1, v2
	v_ashrrev_i32_e32 v10, 6, v2
	v_lshlrev_b32_e32 v3, 3, v8
	v_and_b32_e32 v2, 0xffc0, v2
	v_and_b32_e32 v3, -16, v3
	v_sub_u32_e32 v1, v1, v2
	v_add_u32_e32 v3, v10, v3
	v_lshrrev_b16_e32 v2, 7, v1
	v_and_b32_e32 v4, 3, v10
	v_lshrrev_b32_e32 v5, 2, v3
	v_lshlrev_b32_e32 v6, 1, v3
	v_and_b32_e32 v2, 1, v2
	v_and_or_b32 v4, v3, s0, v4
	v_and_b32_e32 v5, 4, v5
	v_and_b32_e32 v6, 24, v6
	v_add_u16_e32 v1, v1, v2
	v_mov_b32_e32 v2, 1
	v_or3_b32 v4, v4, v5, v6
	v_lshlrev_b32_e32 v5, 5, v8
	v_ashrrev_i16_sdwa v1, v2, sext(v1) dst_sel:DWORD dst_unused:UNUSED_PAD src0_sel:DWORD src1_sel:BYTE_0
	v_and_b32_e32 v5, 32, v5
	v_bfe_i32 v11, v1, 0, 16
	v_add_lshl_u32 v1, v5, v11, 1
	v_lshl_add_u32 v128, v4, 12, v1
	v_lshl_add_u32 v130, v3, 12, v1
	v_ashrrev_i32_e32 v1, 31, v0
	v_lshrrev_b32_e32 v1, 22, v1
	v_add_u32_e32 v1, v0, v1
	v_ashrrev_i32_e32 v12, 10, v1
	v_mul_i32_i24_e32 v1, 0x400, v12
	v_sub_u32_e32 v0, v0, v1
	v_lshrrev_b32_e32 v1, 4, v0
	v_bitop3_b32 v0, v1, v0, 32 bitop3:0x6c
	v_ashrrev_i32_e32 v1, 31, v0
	v_lshrrev_b32_e32 v1, 26, v1
	v_add_u32_e32 v1, v0, v1
	v_lshlrev_b32_e32 v3, 3, v12
	v_ashrrev_i32_e32 v13, 6, v1
	v_and_b32_e32 v3, -16, v3
	v_add_u32_e32 v3, v13, v3
	v_and_b32_e32 v4, 3, v13
	s_ashr_i32 s36, s87, 31
	v_and_or_b32 v4, v3, s0, v4
	s_lshr_b32 s0, s36, 29
	s_add_i32 s0, s87, s0
	s_ashr_i32 s1, s0, 3
	s_and_b32 s0, s0, -8
	s_lshr_b32 s19, s92, 8
	s_sub_i32 s0, s87, s0
	s_cmp_lt_i32 s0, 0
	s_cselect_b32 s4, s37, 0x140
	s_mul_i32 s0, s4, s0
	s_add_i32 s0, s0, s1
	s_mul_hi_i32 s1, s0, 0x66666667
	s_lshr_b32 s4, s1, 31
	s_ashr_i32 s1, s1, 7
	s_add_i32 s1, s1, s4
	s_lshl_b32 s4, s1, 3
	s_mulk_i32 s1, 0x140
	s_sub_i32 s0, s0, s1
	s_sext_i32_i16 s1, s0
	s_bfe_u32 s1, s1, 0x3001c
	s_add_i32 s1, s0, s1
	s_sext_i32_i16 s5, s1
	s_and_b32 s1, s1, 0xfff8
	s_sub_i32 s0, s0, s1
	s_sext_i32_i16 s0, s0
	v_lshrrev_b32_e32 v5, 2, v3
	v_lshlrev_b32_e32 v6, 1, v3
	v_and_b32_e32 v1, 0xc0, v1
	s_lshr_b32 s18, s5, 3
	s_add_i32 s0, s4, s0
	v_and_b32_e32 v5, 4, v5
	v_and_b32_e32 v6, 24, v6
	v_sub_u32_e32 v0, v0, v1
	s_ashr_i32 s1, s0, 31
	s_bfe_i64 s[4:5], s[18:19], 0x100000
	v_or3_b32 v4, v4, v5, v6
	v_lshlrev_b32_e32 v5, 5, v12
	v_ashrrev_i16_sdwa v0, v2, sext(v0) dst_sel:DWORD dst_unused:UNUSED_PAD src0_sel:DWORD src1_sel:BYTE_0
	s_lshl_b64 s[6:7], s[0:1], 20
	s_lshl_b64 s[4:5], s[4:5], 20
	v_and_b32_e32 v5, 32, v5
	v_bfe_i32 v14, v0, 0, 16
	s_add_u32 s4, s33, s4
	v_add_lshl_u32 v0, v5, v14, 1
	s_addc_u32 s5, s34, s5
	s_add_i32 s38, s35, 0
	v_lshl_add_u32 v132, v4, 12, v0
	s_add_i32 m0, s38, 0x10000
	v_lshl_add_u32 v134, v3, 12, v0
	global_load_lds_dwordx4 v132, s[4:5]
	s_add_i32 m0, s38, 0x12000
	s_add_u32 s8, s4, 0x80000
	global_load_lds_dwordx4 v128, s[4:5]
	s_addc_u32 s9, s5, 0
	s_add_i32 m0, s38, 0x14000
	v_mov_b32_e32 v133, 0
	global_load_lds_dwordx4 v132, s[8:9]
	s_add_i32 m0, s38, 0x16000
	s_add_u32 s6, s30, s6
	s_addc_u32 s7, s31, s7
	s_add_i32 s39, s38, 0x2000
	global_load_lds_dwordx4 v128, s[8:9]
	s_mov_b32 m0, s38
	s_add_u32 s8, s6, 0x80000
	global_load_lds_dwordx4 v134, s[6:7]
	s_mov_b32 m0, s39
	s_addc_u32 s9, s7, 0
	s_add_i32 s40, s38, 0x4000
	global_load_lds_dwordx4 v130, s[6:7]
	s_mov_b32 m0, s40
	s_add_i32 s41, s38, 0x6000
	global_load_lds_dwordx4 v134, s[8:9]
	s_mov_b32 m0, s41
	v_mov_b32_e32 v129, v133
	global_load_lds_dwordx4 v130, s[8:9]
	v_mov_b32_e32 v135, v133
	v_mov_b32_e32 v131, v133
	s_cmp_eq_u32 s19, 1
	s_mov_b32 s42, 0
	v_lshl_add_u64 v[6:7], s[4:5], 0, v[132:133]
	v_lshl_add_u64 v[4:5], s[4:5], 0, v[128:129]
	v_lshl_add_u64 v[0:1], s[6:7], 0, v[134:135]
	s_cselect_b64 s[8:9], -1, 0
	s_cmp_lg_u32 s19, 1
	v_lshl_add_u64 v[2:3], s[6:7], 0, v[130:131]
	s_cbranch_scc1 .LBB0_720
	s_barrier

.LBB0_729:
	s_cmp_eq_u32 s95, s0
	s_cbranch_scc1 .Llean_p7
	s_mov_b32 s95, s0
	v_lshl_add_u32 v144, s0, 8, v155
	v_ashrrev_i32_e32 v145, 31, v144
	v_lshlrev_b64 v[146:147], 3, v[144:145]
	v_lshl_add_u64 v[148:149], s[14:15], 0, v[146:147]
	global_load_dwordx2 v[168:169], v[148:149], off
	v_lshl_add_u64 v[146:147], s[12:13], 0, v[146:147]
	global_load_dwordx2 v[170:171], v[146:147], off
	global_load_dwordx2 v[172:173], v[148:149], off offset:128
	global_load_dwordx2 v[174:175], v[146:147], off offset:128
	global_load_dwordx2 v[176:177], v[148:149], off offset:256
	global_load_dwordx2 v[178:179], v[146:147], off offset:256
	global_load_dwordx2 v[180:181], v[148:149], off offset:384
	global_load_dwordx2 v[182:183], v[146:147], off offset:384
	global_load_dwordx2 v[152:153], v[148:149], off offset:1024
	global_load_dwordx2 v[150:151], v[146:147], off offset:1024
	v_cvt_f32_i32_e32 v125, v125
	v_cvt_f32_i32_e32 v124, v124
	v_cvt_f32_i32_e32 v127, v127
	v_cvt_f32_i32_e32 v126, v126
	v_cvt_f32_i32_e32 v121, v121
	v_cvt_f32_i32_e32 v123, v123
	v_cvt_f32_i32_e32 v122, v122
	v_cvt_f32_i32_e32 v120, v120
	v_cvt_f32_i32_e32 v117, v117
	v_cvt_f32_i32_e32 v116, v116
	v_cvt_f32_i32_e32 v113, v113
	v_cvt_f32_i32_e32 v115, v115
	v_cvt_f32_i32_e32 v114, v114
	v_cvt_f32_i32_e32 v112, v112
	v_cvt_f32_i32_e32 v119, v119
	v_cvt_f32_i32_e32 v118, v118
	v_cvt_f32_i32_e32 v109, v109
	v_cvt_f32_i32_e32 v108, v108
	v_cvt_f32_i32_e32 v111, v111
	v_cvt_f32_i32_e32 v110, v110
	v_cvt_f32_i32_e32 v105, v105
	v_cvt_f32_i32_e32 v107, v107
	v_cvt_f32_i32_e32 v106, v106
	v_cvt_f32_i32_e32 v104, v104
	v_cvt_f32_i32_e32 v101, v101
	v_cvt_f32_i32_e32 v100, v100
	v_cvt_f32_i32_e32 v97, v97
	v_cvt_f32_i32_e32 v99, v99
	v_cvt_f32_i32_e32 v98, v98
	v_cvt_f32_i32_e32 v96, v96
	v_cvt_f32_i32_e32 v103, v103
	v_cvt_f32_i32_e32 v102, v102
	v_cvt_f32_i32_e32 v93, v93
	v_cvt_f32_i32_e32 v92, v92
	v_cvt_f32_i32_e32 v95, v95
	v_cvt_f32_i32_e32 v94, v94
	v_cvt_f32_i32_e32 v89, v89
	v_cvt_f32_i32_e32 v91, v91
	v_cvt_f32_i32_e32 v90, v90
	v_cvt_f32_i32_e32 v88, v88
	v_cvt_f32_i32_e32 v85, v85
	v_cvt_f32_i32_e32 v84, v84
	v_cvt_f32_i32_e32 v81, v81
	v_cvt_f32_i32_e32 v83, v83
	v_cvt_f32_i32_e32 v82, v82
	v_cvt_f32_i32_e32 v80, v80
	v_cvt_f32_i32_e32 v87, v87
	v_cvt_f32_i32_e32 v86, v86
	v_cvt_f32_i32_e32 v77, v77
	v_cvt_f32_i32_e32 v76, v76
	v_cvt_f32_i32_e32 v79, v79
	v_cvt_f32_i32_e32 v78, v78
	v_cvt_f32_i32_e32 v73, v73
	v_cvt_f32_i32_e32 v75, v75
	v_cvt_f32_i32_e32 v74, v74
	v_cvt_f32_i32_e32 v72, v72
	v_cvt_f32_i32_e32 v69, v69
	v_cvt_f32_i32_e32 v68, v68
	v_cvt_f32_i32_e32 v71, v71
	v_cvt_f32_i32_e32 v70, v70
	v_cvt_f32_i32_e32 v65, v65
	v_cvt_f32_i32_e32 v67, v67
	v_cvt_f32_i32_e32 v66, v66
	v_cvt_f32_i32_e32 v64, v64
	v_cvt_f32_i32_e32 v61, v61
	v_cvt_f32_i32_e32 v60, v60
	v_cvt_f32_i32_e32 v63, v63
	v_cvt_f32_i32_e32 v62, v62
	v_cvt_f32_i32_e32 v57, v57
	v_cvt_f32_i32_e32 v59, v59
	v_cvt_f32_i32_e32 v58, v58
	s_waitcnt vmcnt(0)
	v_ffbh_u32_e32 v154, v171
	v_ffbh_u32_e32 v156, v173
	v_ffbh_u32_e32 v158, v175
	v_ffbh_u32_e32 v160, v177
	v_ffbh_u32_e32 v162, v179
	v_min_u32_e32 v154, 32, v154
	v_ffbh_u32_e32 v145, v169
	v_min_u32_e32 v145, 32, v145
	v_min_u32_e32 v156, 32, v156
	v_min_u32_e32 v158, 32, v158
	v_min_u32_e32 v160, 32, v160
	v_min_u32_e32 v162, 32, v162
	v_lshlrev_b64 v[168:169], v145, v[168:169]
	v_lshlrev_b64 v[170:171], v154, v[170:171]
	v_lshlrev_b64 v[172:173], v156, v[172:173]
	v_lshlrev_b64 v[174:175], v158, v[174:175]
	v_lshlrev_b64 v[176:177], v160, v[176:177]
	v_lshlrev_b64 v[178:179], v162, v[178:179]
	v_min_u32_e32 v164, 1, v168
	v_min_u32_e32 v168, 1, v170
	v_min_u32_e32 v170, 1, v172
	v_min_u32_e32 v172, 1, v174
	v_min_u32_e32 v174, 1, v176
	v_min_u32_e32 v176, 1, v178
	v_or_b32_e32 v168, v171, v168
	v_or_b32_e32 v164, v169, v164
	v_or_b32_e32 v169, v173, v170
	v_or_b32_e32 v170, v175, v172
	v_or_b32_e32 v171, v177, v174
	v_or_b32_e32 v172, v179, v176
	v_cvt_f32_u32_e32 v168, v168
	v_cvt_f32_u32_e32 v170, v170
	v_cvt_f32_u32_e32 v171, v171
	v_cvt_f32_u32_e32 v172, v172
	v_cvt_f32_u32_e32 v164, v164
	v_sub_u32_e32 v154, 32, v154
	v_cvt_f32_u32_e32 v169, v169
	v_sub_u32_e32 v158, 32, v158
	v_sub_u32_e32 v160, 32, v160
	v_sub_u32_e32 v162, 32, v162
	v_ldexp_f32 v154, v168, v154
	v_sub_u32_e32 v145, 32, v145
	v_ldexp_f32 v158, v170, v158
	v_ldexp_f32 v160, v171, v160
	v_ldexp_f32 v162, v172, v162
	v_fmamk_f32 v154, v154, 0x2f800000, v166
	v_sub_u32_e32 v156, 32, v156
	v_ldexp_f32 v145, v164, v145
	v_fmamk_f32 v158, v158, 0x2f800000, v166
	v_fmamk_f32 v160, v160, 0x2f800000, v166
	v_fmamk_f32 v162, v162, 0x2f800000, v166
	v_mul_f32_e32 v164, 0x4f800000, v154
	v_cmp_gt_f32_e32 vcc, s48, v154
	v_ldexp_f32 v156, v169, v156
	v_mul_f32_e32 v168, 0x4f800000, v158
	v_rsq_f32_e32 v169, v160
	v_mul_f32_e32 v160, 0x4f800000, v162
	v_cndmask_b32_e32 v154, v154, v164, vcc
	v_cmp_gt_f32_e64 s[0:1], s48, v158
	v_cmp_gt_f32_e64 s[4:5], s48, v162
	v_fmamk_f32 v145, v145, 0x2f800000, v166
	v_cndmask_b32_e64 v158, v158, v168, s[0:1]
	v_cndmask_b32_e64 v162, v162, v160, s[4:5]
	v_sqrt_f32_e32 v160, v154
	v_sqrt_f32_e32 v164, v158
	v_fmamk_f32 v156, v156, 0x2f800000, v166
	v_rsq_f32_e32 v145, v145
	v_add_u32_e32 v170, -1, v160
	v_add_u32_e32 v172, -1, v164
	v_fma_f32 v174, -v170, v160, v154
	v_add_u32_e32 v171, 1, v160
	v_fma_f32 v176, -v172, v164, v158
	v_cmp_ge_f32_e64 s[6:7], 0, v174
	v_add_u32_e32 v173, 1, v164
	v_fma_f32 v175, -v171, v160, v154
	v_cndmask_b32_e64 v160, v160, v170, s[6:7]
	v_cmp_ge_f32_e64 s[6:7], 0, v176
	v_fma_f32 v177, -v173, v164, v158
	v_rsq_f32_e32 v156, v156
	v_cndmask_b32_e64 v164, v164, v172, s[6:7]
	v_cmp_lt_f32_e64 s[6:7], 0, v175
	v_sqrt_f32_e32 v168, v162
	v_mul_f32_e32 v145, 0x37b6087d, v145
	v_cndmask_b32_e64 v160, v160, v171, s[6:7]
	v_cmp_lt_f32_e64 s[6:7], 0, v177
	v_mul_f32_e32 v170, 0x37800000, v160
	v_cndmask_b32_e32 v160, v160, v170, vcc
	v_cndmask_b32_e64 v164, v164, v173, s[6:7]
	v_mul_f32_e32 v171, 0x37800000, v164
	v_cmp_class_f32_e32 vcc, v154, v167
	v_cndmask_b32_e64 v170, v164, v171, s[0:1]
	v_mul_f32_e32 v156, 0x37b6087d, v156
	v_cndmask_b32_e32 v154, v160, v154, vcc
	v_cmp_class_f32_e32 vcc, v158, v167
	v_mul_f32_e32 v164, v145, v154
	v_add_u32_e32 v154, -1, v168
	v_cndmask_b32_e32 v145, v170, v158, vcc
	v_mul_f32_e32 v160, v156, v145
	v_fma_f32 v156, -v154, v168, v162
	v_cmp_ge_f32_e32 vcc, 0, v156
	v_add_u32_e32 v156, 1, v168
	v_fma_f32 v158, -v156, v168, v162
	v_mul_f32_e32 v145, 0x37b6087d, v169
	v_cndmask_b32_e32 v154, v168, v154, vcc
	v_cmp_lt_f32_e32 vcc, 0, v158
	global_load_dwordx2 v[168:169], v[148:149], off offset:1152
	v_cmp_class_f32_e64 s[0:1], v162, v167
	v_cndmask_b32_e32 v154, v154, v156, vcc
	v_ffbh_u32_e32 v156, v181
	v_min_u32_e32 v156, 32, v156
	v_lshlrev_b64 v[170:171], v156, v[180:181]
	v_min_u32_e32 v158, 1, v170
	v_or_b32_e32 v158, v171, v158
	v_cvt_f32_u32_e32 v158, v158
	v_mul_f32_e32 v170, 0x37800000, v154
	v_cndmask_b32_e64 v154, v154, v170, s[4:5]
	v_sub_u32_e32 v156, 32, v156
	global_load_dwordx2 v[170:171], v[146:147], off offset:1152
	v_ldexp_f32 v156, v158, v156
	v_ffbh_u32_e32 v158, v183
	v_min_u32_e32 v158, 32, v158
	v_lshlrev_b64 v[172:173], v158, v[182:183]
	v_min_u32_e32 v172, 1, v172
	v_or_b32_e32 v172, v173, v172
	v_cvt_f32_u32_e32 v172, v172
	v_sub_u32_e32 v158, 32, v158
	v_fmamk_f32 v156, v156, 0x2f800000, v166
	v_rsq_f32_e32 v156, v156
	v_ldexp_f32 v158, v172, v158
	v_fmamk_f32 v158, v158, 0x2f800000, v166
	v_mul_f32_e32 v172, 0x4f800000, v158
	v_cmp_gt_f32_e32 vcc, s48, v158
	v_cndmask_b32_e64 v154, v154, v162, s[0:1]
	v_mov_b32_e32 v232, v164
	v_pk_mul_f32 v[126:127], v[164:165], v[126:127] op_sel_hi:[0,1]
	v_cndmask_b32_e32 v174, v158, v172, vcc
	v_sqrt_f32_e32 v172, v174
	v_mul_f32_e32 v158, v145, v154
	v_mul_f32_e32 v145, 0x37b6087d, v156
	v_pk_mul_f32 v[124:125], v[164:165], v[124:125] op_sel_hi:[0,1]
	v_add_u32_e32 v154, -1, v172
	v_fma_f32 v156, -v154, v172, v174
	v_cmp_ge_f32_e64 s[0:1], 0, v156
	v_add_u32_e32 v156, 1, v172
	v_fma_f32 v162, -v156, v172, v174
	v_cndmask_b32_e64 v154, v172, v154, s[0:1]
	global_load_dwordx2 v[172:173], v[148:149], off offset:1280
	v_cmp_lt_f32_e64 s[0:1], 0, v162
	v_pk_mul_f32 v[116:117], v[164:165], v[116:117] op_sel_hi:[0,1]
	v_pk_mul_f32 v[118:119], v[164:165], v[118:119] op_sel_hi:[0,1]
	v_cndmask_b32_e64 v154, v154, v156, s[0:1]
	v_mul_f32_e32 v156, 0x37800000, v154
	v_cndmask_b32_e32 v154, v154, v156, vcc
	v_ffbh_u32_e32 v156, v153
	v_min_u32_e32 v156, 32, v156
	v_lshlrev_b64 v[152:153], v156, v[152:153]
	v_min_u32_e32 v152, 1, v152
	v_or_b32_e32 v162, v153, v152
	global_load_dwordx2 v[152:153], v[146:147], off offset:1280
	v_cvt_f32_u32_e32 v162, v162
	v_sub_u32_e32 v156, 32, v156
	global_load_dwordx2 v[146:147], v[146:147], off offset:1408
	v_cmp_class_f32_e32 vcc, v174, v167
	v_ldexp_f32 v156, v162, v156
	v_ffbh_u32_e32 v162, v151
	v_min_u32_e32 v162, 32, v162
	v_lshlrev_b64 v[150:151], v162, v[150:151]
	v_min_u32_e32 v150, 1, v150
	global_load_dwordx2 v[148:149], v[148:149], off offset:1408
	v_or_b32_e32 v150, v151, v150
	v_cvt_f32_u32_e32 v150, v150
	v_fmamk_f32 v151, v156, 0x2f800000, v166
	v_sub_u32_e32 v156, 32, v162
	v_cndmask_b32_e32 v154, v154, v174, vcc
	v_ldexp_f32 v150, v150, v156
	v_fmamk_f32 v150, v150, 0x2f800000, v166
	v_mul_f32_e32 v156, 0x4f800000, v150
	v_cmp_gt_f32_e32 vcc, s48, v150
	v_rsq_f32_e32 v151, v151
	v_mul_f32_e32 v162, v145, v154
	v_cndmask_b32_e32 v156, v150, v156, vcc
	v_sqrt_f32_e32 v150, v156
	v_mul_f32_e32 v145, 0x37b6087d, v151
	v_mov_b32_e32 v234, v160
	v_pk_mul_f32 v[110:111], v[160:161], v[110:111] op_sel_hi:[0,1]
	v_pk_mul_f32 v[108:109], v[160:161], v[108:109] op_sel_hi:[0,1]
	v_add_u32_e32 v151, -1, v150
	v_fma_f32 v154, -v151, v150, v156
	v_cmp_ge_f32_e64 s[0:1], 0, v154
	v_add_u32_e32 v154, 1, v150
	v_pk_mul_f32 v[100:101], v[160:161], v[100:101] op_sel_hi:[0,1]
	v_cndmask_b32_e64 v151, v150, v151, s[0:1]
	v_fma_f32 v150, -v154, v150, v156
	v_cmp_lt_f32_e64 s[0:1], 0, v150
	s_waitcnt vmcnt(5)
	v_ffbh_u32_e32 v150, v169
	v_min_u32_e32 v175, 32, v150
	v_cndmask_b32_e64 v154, v151, v154, s[0:1]
	v_lshlrev_b64 v[150:151], v175, v[168:169]
	v_min_u32_e32 v150, 1, v150
	v_or_b32_e32 v150, v151, v150
	v_cvt_f32_u32_e32 v150, v150
	v_mul_f32_e32 v151, 0x37800000, v154
	v_cndmask_b32_e32 v154, v154, v151, vcc
	v_sub_u32_e32 v151, 32, v175
	v_ldexp_f32 v168, v150, v151
	s_waitcnt vmcnt(4)
	v_ffbh_u32_e32 v150, v171
	v_min_u32_e32 v169, 32, v150
	v_lshlrev_b64 v[150:151], v169, v[170:171]
	v_min_u32_e32 v150, 1, v150
	v_or_b32_e32 v150, v151, v150
	v_cvt_f32_u32_e32 v150, v150
	v_fmamk_f32 v151, v168, 0x2f800000, v166
	v_sub_u32_e32 v168, 32, v169
	v_rsq_f32_e32 v151, v151
	v_ldexp_f32 v150, v150, v168
	v_fmamk_f32 v150, v150, 0x2f800000, v166
	v_mul_f32_e32 v168, 0x4f800000, v150
	v_cmp_gt_f32_e32 vcc, s48, v150
	v_cmp_class_f32_e64 s[0:1], v156, v167
	v_pk_mul_f32 v[102:103], v[160:161], v[102:103] op_sel_hi:[0,1]
	v_cndmask_b32_e32 v168, v150, v168, vcc
	v_sqrt_f32_e32 v150, v168
	v_cndmask_b32_e64 v154, v154, v156, s[0:1]
	v_mul_f32_e32 v156, v145, v154
	v_mul_f32_e32 v145, 0x37b6087d, v151
	v_add_u32_e32 v151, -1, v150
	v_fma_f32 v154, -v151, v150, v168
	v_cmp_ge_f32_e64 s[0:1], 0, v154
	v_add_u32_e32 v154, 1, v150
	v_mov_b32_e32 v236, v158
	v_pk_mul_f32 v[94:95], v[158:159], v[94:95] op_sel_hi:[0,1]
	v_cndmask_b32_e64 v151, v150, v151, s[0:1]
	v_fma_f32 v150, -v154, v150, v168
	v_cmp_lt_f32_e64 s[0:1], 0, v150
	s_waitcnt vmcnt(3)
	v_ffbh_u32_e32 v150, v173
	v_min_u32_e32 v169, 32, v150
	v_cndmask_b32_e64 v154, v151, v154, s[0:1]
	v_lshlrev_b64 v[150:151], v169, v[172:173]
	v_min_u32_e32 v150, 1, v150
	v_or_b32_e32 v150, v151, v150
	v_cvt_f32_u32_e32 v150, v150
	v_mul_f32_e32 v151, 0x37800000, v154
	v_cndmask_b32_e32 v154, v154, v151, vcc
	v_sub_u32_e32 v151, 32, v169
	v_ldexp_f32 v169, v150, v151
	s_waitcnt vmcnt(2)
	v_ffbh_u32_e32 v150, v153
	v_min_u32_e32 v170, 32, v150
	v_lshlrev_b64 v[150:151], v170, v[152:153]
	v_min_u32_e32 v150, 1, v150
	v_or_b32_e32 v150, v151, v150
	v_cvt_f32_u32_e32 v150, v150
	v_sub_u32_e32 v152, 32, v170
	v_fmamk_f32 v151, v169, 0x2f800000, v166
	v_rsq_f32_e32 v151, v151
	v_ldexp_f32 v150, v150, v152
	v_fmamk_f32 v150, v150, 0x2f800000, v166
	v_mul_f32_e32 v152, 0x4f800000, v150
	v_cmp_gt_f32_e32 vcc, s48, v150
	v_cmp_class_f32_e64 s[0:1], v168, v167
	v_pk_mul_f32 v[170:171], v[164:165], v[122:123] op_sel_hi:[0,1]
	v_cndmask_b32_e32 v150, v150, v152, vcc
	v_sqrt_f32_e32 v152, v150
	v_cndmask_b32_e64 v153, v154, v168, s[0:1]
	v_mul_f32_e32 v154, v145, v153
	v_mul_f32_e32 v145, 0x37b6087d, v151
	v_add_u32_e32 v151, -1, v152
	v_fma_f32 v153, -v151, v152, v150
	v_cmp_ge_f32_e64 s[0:1], 0, v153
	v_add_u32_e32 v153, 1, v152
	v_pk_mul_f32 v[122:123], v[164:165], v[120:121] op_sel_hi:[0,1]
	v_cndmask_b32_e64 v151, v152, v151, s[0:1]
	v_fma_f32 v152, -v153, v152, v150
	v_cmp_lt_f32_e64 s[0:1], 0, v152
	v_cvt_pk_bf16_f32 v120, v124, v125
	v_cvt_pk_bf16_f32 v121, v126, v127
	v_cvt_pk_bf16_f32 v122, v122, v123
	v_cvt_pk_bf16_f32 v123, v170, v171
	v_pk_mul_f32 v[92:93], v[158:159], v[92:93] op_sel_hi:[0,1]
	s_nop 0
	v_cndmask_b32_e64 v151, v151, v153, s[0:1]
	v_mul_f32_e32 v152, 0x37800000, v151
	v_cndmask_b32_e32 v151, v151, v152, vcc
	s_waitcnt vmcnt(0)
	v_ffbh_u32_e32 v152, v149
	v_min_u32_e32 v152, 32, v152
	v_lshlrev_b64 v[148:149], v152, v[148:149]
	v_min_u32_e32 v148, 1, v148
	v_or_b32_e32 v148, v149, v148
	v_cvt_f32_u32_e32 v148, v148
	v_cmp_class_f32_e32 vcc, v150, v167
	v_pk_mul_f32 v[84:85], v[158:159], v[84:85] op_sel_hi:[0,1]
	v_pk_mul_f32 v[86:87], v[158:159], v[86:87] op_sel_hi:[0,1]
	v_cndmask_b32_e32 v149, v151, v150, vcc
	v_sub_u32_e32 v150, 32, v152
	v_ldexp_f32 v148, v148, v150
	v_ffbh_u32_e32 v150, v147
	v_min_u32_e32 v150, 32, v150
	v_lshlrev_b64 v[146:147], v150, v[146:147]
	v_min_u32_e32 v146, 1, v146
	v_or_b32_e32 v146, v147, v146
	v_cvt_f32_u32_e32 v146, v146
	v_fmamk_f32 v147, v148, 0x2f800000, v166
	v_sub_u32_e32 v148, 32, v150
	v_lshl_or_b32 v152, s50, 8, v159
	v_ldexp_f32 v146, v146, v148
	v_fmamk_f32 v146, v146, 0x2f800000, v166
	v_mul_f32_e32 v148, 0x4f800000, v146
	v_cmp_gt_f32_e32 vcc, s48, v146
	v_ashrrev_i32_e32 v153, 31, v152
	v_lshlrev_b64 v[152:153], 1, v[152:153]
	v_cndmask_b32_e32 v146, v146, v148, vcc
	v_sqrt_f32_e32 v150, v146
	v_mul_f32_e32 v148, v145, v149
	v_cvt_f32_i32_e32 v56, v56
	v_mov_b32_e32 v238, v162
	v_pk_mul_f32 v[78:79], v[162:163], v[78:79] op_sel_hi:[0,1]
	v_add_u32_e32 v149, -1, v150
	v_fma_f32 v151, -v149, v150, v146
	v_cmp_ge_f32_e64 s[0:1], 0, v151
	v_add_u32_e32 v151, 1, v150
	v_pk_mul_f32 v[76:77], v[162:163], v[76:77] op_sel_hi:[0,1]
	v_cndmask_b32_e64 v149, v150, v149, s[0:1]
	v_fma_f32 v150, -v151, v150, v146
	v_cmp_lt_f32_e64 s[0:1], 0, v150
	v_cvt_f32_i32_e32 v53, v53
	v_cvt_f32_i32_e32 v52, v52
	v_cndmask_b32_e64 v149, v149, v151, s[0:1]
	v_mul_f32_e32 v150, 0x37800000, v149
	v_cndmask_b32_e32 v149, v149, v150, vcc
	v_mov_b64_e32 v[150:151], s[10:11]
	v_mad_i64_i32 v[168:169], s[0:1], v144, s49, v[150:151]
	v_lshl_add_u64 v[168:169], v[168:169], 0, v[152:153]
	global_store_dwordx4 v[168:169], v[120:123], off
	v_cvt_f32_i32_e32 v49, v49
	v_cvt_f32_i32_e32 v51, v51
	v_pk_mul_f32 v[120:121], v[164:165], v[114:115] op_sel_hi:[0,1]
	v_pk_mul_f32 v[114:115], v[164:165], v[112:113] op_sel_hi:[0,1]
	v_cvt_pk_bf16_f32 v112, v116, v117
	v_cvt_pk_bf16_f32 v113, v118, v119
	v_cvt_pk_bf16_f32 v114, v114, v115
	v_cvt_pk_bf16_f32 v115, v120, v121
	global_store_dwordx4 v[168:169], v[112:115], off offset:256
	v_cvt_f32_i32_e32 v50, v50
	v_cvt_f32_i32_e32 v48, v48
	v_or_b32_e32 v112, 16, v144
	v_mad_i64_i32 v[112:113], s[0:1], v112, s49, v[150:151]
	v_lshl_add_u64 v[112:113], v[112:113], 0, v[152:153]
	v_pk_mul_f32 v[114:115], v[160:161], v[106:107] op_sel_hi:[0,1]
	v_pk_mul_f32 v[106:107], v[160:161], v[104:105] op_sel_hi:[0,1]
	v_cvt_pk_bf16_f32 v104, v108, v109
	v_cvt_pk_bf16_f32 v105, v110, v111
	v_cvt_pk_bf16_f32 v106, v106, v107
	v_cvt_pk_bf16_f32 v107, v114, v115
	global_store_dwordx4 v[112:113], v[104:107], off
	v_add_u32_e32 v174, 0x80, v144
	v_pk_mul_f32 v[70:71], v[162:163], v[70:71] op_sel_hi:[0,1]
	v_pk_mul_f32 v[104:105], v[160:161], v[98:99] op_sel_hi:[0,1]
	v_pk_mul_f32 v[98:99], v[160:161], v[96:97] op_sel_hi:[0,1]
	v_cvt_pk_bf16_f32 v96, v100, v101
	v_cvt_pk_bf16_f32 v97, v102, v103
	v_cvt_pk_bf16_f32 v98, v98, v99
	v_cvt_pk_bf16_f32 v99, v104, v105
	global_store_dwordx4 v[112:113], v[96:99], off offset:256
	v_pk_mul_f32 v[68:69], v[162:163], v[68:69] op_sel_hi:[0,1]
	v_cvt_f32_i32_e32 v55, v55
	v_or_b32_e32 v96, 32, v144
	v_mad_i64_i32 v[96:97], s[0:1], v96, s49, v[150:151]
	v_lshl_add_u64 v[96:97], v[96:97], 0, v[152:153]
	v_pk_mul_f32 v[98:99], v[158:159], v[90:91] op_sel_hi:[0,1]
	v_pk_mul_f32 v[90:91], v[158:159], v[88:89] op_sel_hi:[0,1]
	v_cvt_pk_bf16_f32 v88, v92, v93
	v_cvt_pk_bf16_f32 v89, v94, v95
	v_cvt_pk_bf16_f32 v90, v90, v91
	v_cvt_pk_bf16_f32 v91, v98, v99
	global_store_dwordx4 v[96:97], v[88:91], off
	v_cvt_f32_i32_e32 v54, v54
	v_mov_b32_e32 v240, v156
	v_pk_mul_f32 v[62:63], v[156:157], v[62:63] op_sel_hi:[0,1]
	v_pk_mul_f32 v[88:89], v[158:159], v[82:83] op_sel_hi:[0,1]
	v_pk_mul_f32 v[82:83], v[158:159], v[80:81] op_sel_hi:[0,1]
	v_cvt_pk_bf16_f32 v80, v84, v85
	v_cvt_pk_bf16_f32 v81, v86, v87
	v_cvt_pk_bf16_f32 v82, v82, v83
	v_cvt_pk_bf16_f32 v83, v88, v89
	global_store_dwordx4 v[96:97], v[80:83], off offset:256
	v_pk_mul_f32 v[60:61], v[156:157], v[60:61] op_sel_hi:[0,1]
	v_cvt_f32_i32_e32 v45, v45
	v_or_b32_e32 v80, 48, v144
	v_mad_i64_i32 v[80:81], s[0:1], v80, s49, v[150:151]
	v_lshl_add_u64 v[80:81], v[80:81], 0, v[152:153]
	v_pk_mul_f32 v[82:83], v[162:163], v[74:75] op_sel_hi:[0,1]
	v_pk_mul_f32 v[74:75], v[162:163], v[72:73] op_sel_hi:[0,1]
	v_cvt_pk_bf16_f32 v72, v76, v77
	v_cvt_pk_bf16_f32 v73, v78, v79
	v_cvt_pk_bf16_f32 v74, v74, v75
	v_cvt_pk_bf16_f32 v75, v82, v83
	global_store_dwordx4 v[80:81], v[72:75], off
	v_cvt_f32_i32_e32 v44, v44
	v_cvt_f32_i32_e32 v47, v47
	v_pk_mul_f32 v[72:73], v[162:163], v[66:67] op_sel_hi:[0,1]
	v_pk_mul_f32 v[66:67], v[162:163], v[64:65] op_sel_hi:[0,1]
	v_cvt_pk_bf16_f32 v64, v68, v69
	v_cvt_pk_bf16_f32 v65, v70, v71
	v_cvt_pk_bf16_f32 v66, v66, v67
	v_cvt_pk_bf16_f32 v67, v72, v73
	global_store_dwordx4 v[80:81], v[64:67], off offset:256
	v_cvt_f32_i32_e32 v46, v46
	v_cvt_f32_i32_e32 v41, v41
	v_mad_i64_i32 v[64:65], s[0:1], v174, s49, v[150:151]
	v_lshl_add_u64 v[64:65], v[64:65], 0, v[152:153]
	v_pk_mul_f32 v[66:67], v[156:157], v[58:59] op_sel_hi:[0,1]
	v_pk_mul_f32 v[58:59], v[156:157], v[56:57] op_sel_hi:[0,1]
	v_cvt_pk_bf16_f32 v56, v60, v61
	v_cvt_pk_bf16_f32 v57, v62, v63
	v_cvt_f32_i32_e32 v43, v43
	v_cvt_f32_i32_e32 v42, v42
	v_cvt_f32_i32_e32 v40, v40
	v_cvt_pk_bf16_f32 v58, v58, v59
	v_cvt_pk_bf16_f32 v59, v66, v67
	global_store_dwordx4 v[64:65], v[56:59], off
	v_pk_mul_f32 v[52:53], v[156:157], v[52:53] op_sel_hi:[0,1]
	v_cvt_f32_i32_e32 v37, v37
	v_pk_mul_f32 v[56:57], v[156:157], v[50:51] op_sel_hi:[0,1]
	v_pk_mul_f32 v[50:51], v[156:157], v[48:49] op_sel_hi:[0,1]
	v_cvt_pk_bf16_f32 v48, v52, v53
	v_cvt_f32_i32_e32 v36, v36
	v_cvt_f32_i32_e32 v33, v33
	v_cvt_f32_i32_e32 v35, v35
	v_cvt_f32_i32_e32 v34, v34
	v_cvt_f32_i32_e32 v32, v32
	v_pk_mul_f32 v[54:55], v[156:157], v[54:55] op_sel_hi:[0,1]
	v_cvt_pk_bf16_f32 v49, v54, v55
	v_cvt_pk_bf16_f32 v50, v50, v51
	v_cvt_pk_bf16_f32 v51, v56, v57
	global_store_dwordx4 v[64:65], v[48:51], off offset:256
	v_cvt_f32_i32_e32 v39, v39
	v_cvt_f32_i32_e32 v38, v38
	v_add_u32_e32 v48, 0x90, v144
	v_mad_i64_i32 v[48:49], s[0:1], v48, s49, v[150:151]
	v_lshl_add_u64 v[48:49], v[48:49], 0, v[152:153]
	v_mov_b32_e32 v242, v154
	v_pk_mul_f32 v[46:47], v[154:155], v[46:47] op_sel_hi:[0,1]
	v_pk_mul_f32 v[44:45], v[154:155], v[44:45] op_sel_hi:[0,1]
	v_pk_mul_f32 v[50:51], v[154:155], v[42:43] op_sel_hi:[0,1]
	v_pk_mul_f32 v[42:43], v[154:155], v[40:41] op_sel_hi:[0,1]
	v_cvt_pk_bf16_f32 v40, v44, v45
	v_cvt_pk_bf16_f32 v41, v46, v47
	v_cvt_f32_i32_e32 v29, v29
	v_cvt_f32_i32_e32 v28, v28
	v_cvt_f32_i32_e32 v31, v31
	v_cvt_f32_i32_e32 v30, v30
	v_cvt_f32_i32_e32 v25, v25
	v_cvt_f32_i32_e32 v27, v27
	v_cvt_f32_i32_e32 v26, v26
	v_cvt_f32_i32_e32 v24, v24
	v_rsq_f32_e32 v147, v147
	v_cvt_pk_bf16_f32 v42, v42, v43
	v_cvt_pk_bf16_f32 v43, v50, v51
	global_store_dwordx4 v[48:49], v[40:43], off
	v_pk_mul_f32 v[36:37], v[154:155], v[36:37] op_sel_hi:[0,1]
	v_cvt_f32_i32_e32 v21, v21
	v_pk_mul_f32 v[40:41], v[154:155], v[34:35] op_sel_hi:[0,1]
	v_pk_mul_f32 v[34:35], v[154:155], v[32:33] op_sel_hi:[0,1]
	v_cvt_pk_bf16_f32 v32, v36, v37
	v_cvt_f32_i32_e32 v20, v20
	v_cvt_f32_i32_e32 v23, v23
	v_cvt_f32_i32_e32 v22, v22
	v_cvt_f32_i32_e32 v17, v17
	v_cvt_f32_i32_e32 v19, v19
	v_cvt_f32_i32_e32 v18, v18
	v_cvt_f32_i32_e32 v16, v16
	v_pk_mul_f32 v[38:39], v[154:155], v[38:39] op_sel_hi:[0,1]
	v_cvt_pk_bf16_f32 v33, v38, v39
	v_cvt_pk_bf16_f32 v34, v34, v35
	v_cvt_pk_bf16_f32 v35, v40, v41
	global_store_dwordx4 v[48:49], v[32:35], off offset:256
	v_cvt_f32_i32_e32 v13, v13
	v_cvt_f32_i32_e32 v12, v12
	v_add_u32_e32 v32, 0xa0, v144
	v_mad_i64_i32 v[32:33], s[0:1], v32, s49, v[150:151]
	v_cvt_f32_i32_e32 v15, v15
	v_cvt_f32_i32_e32 v14, v14
	v_cvt_f32_i32_e32 v9, v9
	v_cvt_f32_i32_e32 v11, v11
	v_cvt_f32_i32_e32 v10, v10
	v_cvt_f32_i32_e32 v8, v8
	v_cmp_class_f32_e32 vcc, v146, v167
	v_lshl_add_u64 v[32:33], v[32:33], 0, v[152:153]
	v_mov_b32_e32 v244, v148
	v_pk_mul_f32 v[30:31], v[148:149], v[30:31] op_sel_hi:[0,1]
	v_pk_mul_f32 v[28:29], v[148:149], v[28:29] op_sel_hi:[0,1]
	v_pk_mul_f32 v[34:35], v[148:149], v[26:27] op_sel_hi:[0,1]
	v_pk_mul_f32 v[26:27], v[148:149], v[24:25] op_sel_hi:[0,1]
	v_cvt_pk_bf16_f32 v24, v28, v29
	v_cvt_pk_bf16_f32 v25, v30, v31
	v_cvt_f32_i32_e32 v1, v1
	v_cvt_f32_i32_e32 v3, v3
	v_cvt_f32_i32_e32 v2, v2
	v_cvt_f32_i32_e32 v0, v0
	v_mul_f32_e32 v147, 0x37b6087d, v147
	v_add_u32_e32 v145, 0xb0, v144
	v_cndmask_b32_e32 v146, v149, v146, vcc
	v_cvt_pk_bf16_f32 v26, v26, v27
	v_cvt_pk_bf16_f32 v27, v34, v35
	global_store_dwordx4 v[32:33], v[24:27], off
	v_pk_mul_f32 v[22:23], v[148:149], v[22:23] op_sel_hi:[0,1]
	v_pk_mul_f32 v[20:21], v[148:149], v[20:21] op_sel_hi:[0,1]
	v_pk_mul_f32 v[24:25], v[148:149], v[18:19] op_sel_hi:[0,1]
	v_pk_mul_f32 v[18:19], v[148:149], v[16:17] op_sel_hi:[0,1]
	v_cvt_pk_bf16_f32 v16, v20, v21
	v_cvt_pk_bf16_f32 v17, v22, v23
	v_cvt_f32_i32_e32 v5, v5
	v_cvt_f32_i32_e32 v4, v4
	v_cvt_f32_i32_e32 v7, v7
	v_cvt_f32_i32_e32 v6, v6
	v_mul_f32_e32 v146, v147, v146
	v_cvt_pk_bf16_f32 v18, v18, v19
	v_cvt_pk_bf16_f32 v19, v24, v25
	global_store_dwordx4 v[32:33], v[16:19], off offset:256
	v_mov_b32_e32 v246, v146
	v_pk_mul_f32 v[14:15], v[146:147], v[14:15] op_sel_hi:[0,1]
	v_pk_mul_f32 v[12:13], v[146:147], v[12:13] op_sel_hi:[0,1]
	v_mad_i64_i32 v[16:17], s[0:1], v145, s49, v[150:151]
	v_lshl_add_u64 v[16:17], v[16:17], 0, v[152:153]
	v_pk_mul_f32 v[18:19], v[146:147], v[10:11] op_sel_hi:[0,1]
	v_pk_mul_f32 v[10:11], v[146:147], v[8:9] op_sel_hi:[0,1]
	v_cvt_pk_bf16_f32 v8, v12, v13
	v_cvt_pk_bf16_f32 v9, v14, v15
	v_cvt_pk_bf16_f32 v10, v10, v11
	v_cvt_pk_bf16_f32 v11, v18, v19
	global_store_dwordx4 v[16:17], v[8:11], off
	s_andn2_b64 vcc, exec, s[2:3]
	s_mov_b64 s[0:1], -1
	v_pk_mul_f32 v[8:9], v[146:147], v[2:3] op_sel_hi:[0,1]
	v_pk_mul_f32 v[2:3], v[146:147], v[0:1] op_sel_hi:[0,1]
	v_pk_mul_f32 v[6:7], v[146:147], v[6:7] op_sel_hi:[0,1]
	v_pk_mul_f32 v[4:5], v[146:147], v[4:5] op_sel_hi:[0,1]
	v_cvt_pk_bf16_f32 v0, v4, v5
	v_cvt_pk_bf16_f32 v1, v6, v7
	v_cvt_pk_bf16_f32 v2, v2, v3
	v_cvt_pk_bf16_f32 v3, v8, v9
	global_store_dwordx4 v[16:17], v[0:3], off offset:256
	s_cbranch_vccnz .LBB0_722

.Llean_p7:
	v_lshl_add_u32 v144, s0, 8, v155
	v_mov_b32_e32 v145, 0
	v_lshl_or_b32 v148, s50, 8, v159
	v_mov_b32_e32 v149, 0
	v_mov_b32_e32 v146, 0x5000
	v_mad_u64_u32 v[146:147], s[96:97], v144, v146, 0
	v_lshlrev_b64 v[148:149], 1, v[148:149]
	v_lshl_add_u64 v[146:147], s[10:11], 0, v[146:147]
	v_lshl_add_u64 v[150:151], v[146:147], 0, v[148:149]
	v_cvt_f32_i32_e32 v124, v124
	v_cvt_f32_i32_e32 v125, v125
	v_cvt_f32_i32_e32 v126, v126
	v_cvt_f32_i32_e32 v127, v127
	v_cvt_f32_i32_e32 v120, v120
	v_cvt_f32_i32_e32 v121, v121
	v_cvt_f32_i32_e32 v122, v122
	v_cvt_f32_i32_e32 v123, v123
	v_pk_mul_f32 v[124:125], v[232:233], v[124:125] op_sel_hi:[0,1]
	v_pk_mul_f32 v[126:127], v[232:233], v[126:127] op_sel_hi:[0,1]
	v_pk_mul_f32 v[120:121], v[232:233], v[120:121] op_sel_hi:[0,1]
	v_pk_mul_f32 v[122:123], v[232:233], v[122:123] op_sel_hi:[0,1]
	v_cvt_pk_bf16_f32 v170, v124, v125
	v_cvt_pk_bf16_f32 v171, v126, v127
	v_cvt_pk_bf16_f32 v172, v120, v121
	v_cvt_pk_bf16_f32 v173, v122, v123
	global_store_dwordx4 v[150:151], v[170:173], off
	v_cvt_f32_i32_e32 v116, v116
	v_cvt_f32_i32_e32 v117, v117
	v_cvt_f32_i32_e32 v118, v118
	v_cvt_f32_i32_e32 v119, v119
	v_cvt_f32_i32_e32 v112, v112
	v_cvt_f32_i32_e32 v113, v113
	v_cvt_f32_i32_e32 v114, v114
	v_cvt_f32_i32_e32 v115, v115
	v_pk_mul_f32 v[116:117], v[232:233], v[116:117] op_sel_hi:[0,1]
	v_pk_mul_f32 v[118:119], v[232:233], v[118:119] op_sel_hi:[0,1]
	v_pk_mul_f32 v[112:113], v[232:233], v[112:113] op_sel_hi:[0,1]
	v_pk_mul_f32 v[114:115], v[232:233], v[114:115] op_sel_hi:[0,1]
	v_cvt_pk_bf16_f32 v174, v116, v117
	v_cvt_pk_bf16_f32 v175, v118, v119
	v_cvt_pk_bf16_f32 v176, v112, v113
	v_cvt_pk_bf16_f32 v177, v114, v115
	global_store_dwordx4 v[150:151], v[174:177], off offset:256
	v_add_co_u32_e32 v152, vcc, 0x50000, v150
	s_nop 1
	v_addc_co_u32_e32 v153, vcc, 0, v151, vcc
	v_cvt_f32_i32_e32 v108, v108
	v_cvt_f32_i32_e32 v109, v109
	v_cvt_f32_i32_e32 v110, v110
	v_cvt_f32_i32_e32 v111, v111
	v_cvt_f32_i32_e32 v104, v104
	v_cvt_f32_i32_e32 v105, v105
	v_cvt_f32_i32_e32 v106, v106
	v_cvt_f32_i32_e32 v107, v107
	v_pk_mul_f32 v[108:109], v[234:235], v[108:109] op_sel_hi:[0,1]
	v_pk_mul_f32 v[110:111], v[234:235], v[110:111] op_sel_hi:[0,1]
	v_pk_mul_f32 v[104:105], v[234:235], v[104:105] op_sel_hi:[0,1]
	v_pk_mul_f32 v[106:107], v[234:235], v[106:107] op_sel_hi:[0,1]
	v_cvt_pk_bf16_f32 v178, v108, v109
	v_cvt_pk_bf16_f32 v179, v110, v111
	v_cvt_pk_bf16_f32 v180, v104, v105
	v_cvt_pk_bf16_f32 v181, v106, v107
	global_store_dwordx4 v[152:153], v[178:181], off
	v_cvt_f32_i32_e32 v100, v100
	v_cvt_f32_i32_e32 v101, v101
	v_cvt_f32_i32_e32 v102, v102
	v_cvt_f32_i32_e32 v103, v103
	v_cvt_f32_i32_e32 v96, v96
	v_cvt_f32_i32_e32 v97, v97
	v_cvt_f32_i32_e32 v98, v98
	v_cvt_f32_i32_e32 v99, v99
	v_pk_mul_f32 v[100:101], v[234:235], v[100:101] op_sel_hi:[0,1]
	v_pk_mul_f32 v[102:103], v[234:235], v[102:103] op_sel_hi:[0,1]
	v_pk_mul_f32 v[96:97], v[234:235], v[96:97] op_sel_hi:[0,1]
	v_pk_mul_f32 v[98:99], v[234:235], v[98:99] op_sel_hi:[0,1]
	v_cvt_pk_bf16_f32 v182, v100, v101
	v_cvt_pk_bf16_f32 v183, v102, v103
	v_cvt_pk_bf16_f32 v184, v96, v97
	v_cvt_pk_bf16_f32 v185, v98, v99
	global_store_dwordx4 v[152:153], v[182:185], off offset:256
	v_add_co_u32_e32 v152, vcc, 0xa0000, v150
	s_nop 1
	v_addc_co_u32_e32 v153, vcc, 0, v151, vcc
	v_cvt_f32_i32_e32 v92, v92
	v_cvt_f32_i32_e32 v93, v93
	v_cvt_f32_i32_e32 v94, v94
	v_cvt_f32_i32_e32 v95, v95
	v_cvt_f32_i32_e32 v88, v88
	v_cvt_f32_i32_e32 v89, v89
	v_cvt_f32_i32_e32 v90, v90
	v_cvt_f32_i32_e32 v91, v91
	v_pk_mul_f32 v[92:93], v[236:237], v[92:93] op_sel_hi:[0,1]
	v_pk_mul_f32 v[94:95], v[236:237], v[94:95] op_sel_hi:[0,1]
	v_pk_mul_f32 v[88:89], v[236:237], v[88:89] op_sel_hi:[0,1]
	v_pk_mul_f32 v[90:91], v[236:237], v[90:91] op_sel_hi:[0,1]
	v_cvt_pk_bf16_f32 v186, v92, v93
	v_cvt_pk_bf16_f32 v187, v94, v95
	v_cvt_pk_bf16_f32 v188, v88, v89
	v_cvt_pk_bf16_f32 v189, v90, v91
	global_store_dwordx4 v[152:153], v[186:189], off
	v_cvt_f32_i32_e32 v84, v84
	v_cvt_f32_i32_e32 v85, v85
	v_cvt_f32_i32_e32 v86, v86
	v_cvt_f32_i32_e32 v87, v87
	v_cvt_f32_i32_e32 v80, v80
	v_cvt_f32_i32_e32 v81, v81
	v_cvt_f32_i32_e32 v82, v82
	v_cvt_f32_i32_e32 v83, v83
	v_pk_mul_f32 v[84:85], v[236:237], v[84:85] op_sel_hi:[0,1]
	v_pk_mul_f32 v[86:87], v[236:237], v[86:87] op_sel_hi:[0,1]
	v_pk_mul_f32 v[80:81], v[236:237], v[80:81] op_sel_hi:[0,1]
	v_pk_mul_f32 v[82:83], v[236:237], v[82:83] op_sel_hi:[0,1]
	v_cvt_pk_bf16_f32 v190, v84, v85
	v_cvt_pk_bf16_f32 v191, v86, v87
	v_cvt_pk_bf16_f32 v192, v80, v81
	v_cvt_pk_bf16_f32 v193, v82, v83
	global_store_dwordx4 v[152:153], v[190:193], off offset:256
	v_add_co_u32_e32 v152, vcc, 0xf0000, v150
	s_nop 1
	v_addc_co_u32_e32 v153, vcc, 0, v151, vcc
	v_cvt_f32_i32_e32 v76, v76
	v_cvt_f32_i32_e32 v77, v77
	v_cvt_f32_i32_e32 v78, v78
	v_cvt_f32_i32_e32 v79, v79
	v_cvt_f32_i32_e32 v72, v72
	v_cvt_f32_i32_e32 v73, v73
	v_cvt_f32_i32_e32 v74, v74
	v_cvt_f32_i32_e32 v75, v75
	v_pk_mul_f32 v[76:77], v[238:239], v[76:77] op_sel_hi:[0,1]
	v_pk_mul_f32 v[78:79], v[238:239], v[78:79] op_sel_hi:[0,1]
	v_pk_mul_f32 v[72:73], v[238:239], v[72:73] op_sel_hi:[0,1]
	v_pk_mul_f32 v[74:75], v[238:239], v[74:75] op_sel_hi:[0,1]
	v_cvt_pk_bf16_f32 v194, v76, v77
	v_cvt_pk_bf16_f32 v195, v78, v79
	v_cvt_pk_bf16_f32 v196, v72, v73
	v_cvt_pk_bf16_f32 v197, v74, v75
	global_store_dwordx4 v[152:153], v[194:197], off
	v_cvt_f32_i32_e32 v68, v68
	v_cvt_f32_i32_e32 v69, v69
	v_cvt_f32_i32_e32 v70, v70
	v_cvt_f32_i32_e32 v71, v71
	v_cvt_f32_i32_e32 v64, v64
	v_cvt_f32_i32_e32 v65, v65
	v_cvt_f32_i32_e32 v66, v66
	v_cvt_f32_i32_e32 v67, v67
	v_pk_mul_f32 v[68:69], v[238:239], v[68:69] op_sel_hi:[0,1]
	v_pk_mul_f32 v[70:71], v[238:239], v[70:71] op_sel_hi:[0,1]
	v_pk_mul_f32 v[64:65], v[238:239], v[64:65] op_sel_hi:[0,1]
	v_pk_mul_f32 v[66:67], v[238:239], v[66:67] op_sel_hi:[0,1]
	v_cvt_pk_bf16_f32 v198, v68, v69
	v_cvt_pk_bf16_f32 v199, v70, v71
	v_cvt_pk_bf16_f32 v200, v64, v65
	v_cvt_pk_bf16_f32 v201, v66, v67
	global_store_dwordx4 v[152:153], v[198:201], off offset:256
	v_add_co_u32_e32 v152, vcc, 0x280000, v150
	s_nop 1
	v_addc_co_u32_e32 v153, vcc, 0, v151, vcc
	v_cvt_f32_i32_e32 v60, v60
	v_cvt_f32_i32_e32 v61, v61
	v_cvt_f32_i32_e32 v62, v62
	v_cvt_f32_i32_e32 v63, v63
	v_cvt_f32_i32_e32 v56, v56
	v_cvt_f32_i32_e32 v57, v57
	v_cvt_f32_i32_e32 v58, v58
	v_cvt_f32_i32_e32 v59, v59
	v_pk_mul_f32 v[60:61], v[240:241], v[60:61] op_sel_hi:[0,1]
	v_pk_mul_f32 v[62:63], v[240:241], v[62:63] op_sel_hi:[0,1]
	v_pk_mul_f32 v[56:57], v[240:241], v[56:57] op_sel_hi:[0,1]
	v_pk_mul_f32 v[58:59], v[240:241], v[58:59] op_sel_hi:[0,1]
	v_cvt_pk_bf16_f32 v170, v60, v61
	v_cvt_pk_bf16_f32 v171, v62, v63
	v_cvt_pk_bf16_f32 v172, v56, v57
	v_cvt_pk_bf16_f32 v173, v58, v59
	global_store_dwordx4 v[152:153], v[170:173], off
	v_cvt_f32_i32_e32 v52, v52
	v_cvt_f32_i32_e32 v53, v53
	v_cvt_f32_i32_e32 v54, v54
	v_cvt_f32_i32_e32 v55, v55
	v_cvt_f32_i32_e32 v48, v48
	v_cvt_f32_i32_e32 v49, v49
	v_cvt_f32_i32_e32 v50, v50
	v_cvt_f32_i32_e32 v51, v51
	v_pk_mul_f32 v[52:53], v[240:241], v[52:53] op_sel_hi:[0,1]
	v_pk_mul_f32 v[54:55], v[240:241], v[54:55] op_sel_hi:[0,1]
	v_pk_mul_f32 v[48:49], v[240:241], v[48:49] op_sel_hi:[0,1]
	v_pk_mul_f32 v[50:51], v[240:241], v[50:51] op_sel_hi:[0,1]
	v_cvt_pk_bf16_f32 v174, v52, v53
	v_cvt_pk_bf16_f32 v175, v54, v55
	v_cvt_pk_bf16_f32 v176, v48, v49
	v_cvt_pk_bf16_f32 v177, v50, v51
	global_store_dwordx4 v[152:153], v[174:177], off offset:256
	v_add_co_u32_e32 v152, vcc, 0x2d0000, v150
	s_nop 1
	v_addc_co_u32_e32 v153, vcc, 0, v151, vcc
	v_cvt_f32_i32_e32 v44, v44
	v_cvt_f32_i32_e32 v45, v45
	v_cvt_f32_i32_e32 v46, v46
	v_cvt_f32_i32_e32 v47, v47
	v_cvt_f32_i32_e32 v40, v40
	v_cvt_f32_i32_e32 v41, v41
	v_cvt_f32_i32_e32 v42, v42
	v_cvt_f32_i32_e32 v43, v43
	v_pk_mul_f32 v[44:45], v[242:243], v[44:45] op_sel_hi:[0,1]
	v_pk_mul_f32 v[46:47], v[242:243], v[46:47] op_sel_hi:[0,1]
	v_pk_mul_f32 v[40:41], v[242:243], v[40:41] op_sel_hi:[0,1]
	v_pk_mul_f32 v[42:43], v[242:243], v[42:43] op_sel_hi:[0,1]
	v_cvt_pk_bf16_f32 v178, v44, v45
	v_cvt_pk_bf16_f32 v179, v46, v47
	v_cvt_pk_bf16_f32 v180, v40, v41
	v_cvt_pk_bf16_f32 v181, v42, v43
	global_store_dwordx4 v[152:153], v[178:181], off
	v_cvt_f32_i32_e32 v36, v36
	v_cvt_f32_i32_e32 v37, v37
	v_cvt_f32_i32_e32 v38, v38
	v_cvt_f32_i32_e32 v39, v39
	v_cvt_f32_i32_e32 v32, v32
	v_cvt_f32_i32_e32 v33, v33
	v_cvt_f32_i32_e32 v34, v34
	v_cvt_f32_i32_e32 v35, v35
	v_pk_mul_f32 v[36:37], v[242:243], v[36:37] op_sel_hi:[0,1]
	v_pk_mul_f32 v[38:39], v[242:243], v[38:39] op_sel_hi:[0,1]
	v_pk_mul_f32 v[32:33], v[242:243], v[32:33] op_sel_hi:[0,1]
	v_pk_mul_f32 v[34:35], v[242:243], v[34:35] op_sel_hi:[0,1]
	v_cvt_pk_bf16_f32 v182, v36, v37
	v_cvt_pk_bf16_f32 v183, v38, v39
	v_cvt_pk_bf16_f32 v184, v32, v33
	v_cvt_pk_bf16_f32 v185, v34, v35
	global_store_dwordx4 v[152:153], v[182:185], off offset:256
	v_add_co_u32_e32 v152, vcc, 0x320000, v150
	s_nop 1
	v_addc_co_u32_e32 v153, vcc, 0, v151, vcc
	v_cvt_f32_i32_e32 v28, v28
	v_cvt_f32_i32_e32 v29, v29
	v_cvt_f32_i32_e32 v30, v30
	v_cvt_f32_i32_e32 v31, v31
	v_cvt_f32_i32_e32 v24, v24
	v_cvt_f32_i32_e32 v25, v25
	v_cvt_f32_i32_e32 v26, v26
	v_cvt_f32_i32_e32 v27, v27
	v_pk_mul_f32 v[28:29], v[244:245], v[28:29] op_sel_hi:[0,1]
	v_pk_mul_f32 v[30:31], v[244:245], v[30:31] op_sel_hi:[0,1]
	v_pk_mul_f32 v[24:25], v[244:245], v[24:25] op_sel_hi:[0,1]
	v_pk_mul_f32 v[26:27], v[244:245], v[26:27] op_sel_hi:[0,1]
	v_cvt_pk_bf16_f32 v186, v28, v29
	v_cvt_pk_bf16_f32 v187, v30, v31
	v_cvt_pk_bf16_f32 v188, v24, v25
	v_cvt_pk_bf16_f32 v189, v26, v27
	global_store_dwordx4 v[152:153], v[186:189], off
	v_cvt_f32_i32_e32 v20, v20
	v_cvt_f32_i32_e32 v21, v21
	v_cvt_f32_i32_e32 v22, v22
	v_cvt_f32_i32_e32 v23, v23
	v_cvt_f32_i32_e32 v16, v16
	v_cvt_f32_i32_e32 v17, v17
	v_cvt_f32_i32_e32 v18, v18
	v_cvt_f32_i32_e32 v19, v19
	v_pk_mul_f32 v[20:21], v[244:245], v[20:21] op_sel_hi:[0,1]
	v_pk_mul_f32 v[22:23], v[244:245], v[22:23] op_sel_hi:[0,1]
	v_pk_mul_f32 v[16:17], v[244:245], v[16:17] op_sel_hi:[0,1]
	v_pk_mul_f32 v[18:19], v[244:245], v[18:19] op_sel_hi:[0,1]
	v_cvt_pk_bf16_f32 v190, v20, v21
	v_cvt_pk_bf16_f32 v191, v22, v23
	v_cvt_pk_bf16_f32 v192, v16, v17
	v_cvt_pk_bf16_f32 v193, v18, v19
	global_store_dwordx4 v[152:153], v[190:193], off offset:256
	v_add_co_u32_e32 v152, vcc, 0x370000, v150
	s_nop 1
	v_addc_co_u32_e32 v153, vcc, 0, v151, vcc
	v_cvt_f32_i32_e32 v12, v12
	v_cvt_f32_i32_e32 v13, v13
	v_cvt_f32_i32_e32 v14, v14
	v_cvt_f32_i32_e32 v15, v15
	v_cvt_f32_i32_e32 v8, v8
	v_cvt_f32_i32_e32 v9, v9
	v_cvt_f32_i32_e32 v10, v10
	v_cvt_f32_i32_e32 v11, v11
	v_pk_mul_f32 v[12:13], v[246:247], v[12:13] op_sel_hi:[0,1]
	v_pk_mul_f32 v[14:15], v[246:247], v[14:15] op_sel_hi:[0,1]
	v_pk_mul_f32 v[8:9], v[246:247], v[8:9] op_sel_hi:[0,1]
	v_pk_mul_f32 v[10:11], v[246:247], v[10:11] op_sel_hi:[0,1]
	v_cvt_pk_bf16_f32 v194, v12, v13
	v_cvt_pk_bf16_f32 v195, v14, v15
	v_cvt_pk_bf16_f32 v196, v8, v9
	v_cvt_pk_bf16_f32 v197, v10, v11
	global_store_dwordx4 v[152:153], v[194:197], off
	v_cvt_f32_i32_e32 v4, v4
	v_cvt_f32_i32_e32 v5, v5
	v_cvt_f32_i32_e32 v6, v6
	v_cvt_f32_i32_e32 v7, v7
	v_cvt_f32_i32_e32 v0, v0
	v_cvt_f32_i32_e32 v1, v1
	v_cvt_f32_i32_e32 v2, v2
	v_cvt_f32_i32_e32 v3, v3
	v_pk_mul_f32 v[4:5], v[246:247], v[4:5] op_sel_hi:[0,1]
	v_pk_mul_f32 v[6:7], v[246:247], v[6:7] op_sel_hi:[0,1]
	v_pk_mul_f32 v[0:1], v[246:247], v[0:1] op_sel_hi:[0,1]
	v_pk_mul_f32 v[2:3], v[246:247], v[2:3] op_sel_hi:[0,1]
	v_cvt_pk_bf16_f32 v198, v4, v5
	v_cvt_pk_bf16_f32 v199, v6, v7
	v_cvt_pk_bf16_f32 v200, v0, v1
	v_cvt_pk_bf16_f32 v201, v2, v3
	global_store_dwordx4 v[152:153], v[198:201], off offset:256
	s_andn2_b64 vcc, exec, s[2:3]
	s_mov_b64 s[0:1], -1
	s_cbranch_vccnz .LBB0_722
	s_branch .Ljoin_p7

.LBB0_1258:
	v_lshl_add_u32 v30, s28, 8, v190
	v_lshl_or_b32 v24, s30, 8, v192
	v_ashrrev_i32_e32 v25, 31, v24
	v_ashrrev_i32_e32 v31, 31, v30
	s_nop 7
	s_nop 7
	s_nop 7
	v_lshl_add_u64 v[28:29], v[24:25], 1, s[6:7]
	v_lshlrev_b64 v[0:1], 13, v[30:31]
	v_lshl_add_u64 v[26:27], v[30:31], 3, s[12:13]
	v_lshl_add_u64 v[188:189], v[28:29], 0, v[0:1]
	global_load_dwordx2 v[208:209], v[26:27], off
	global_load_dwordx2 v[232:233], v[26:27], off offset:128
	global_load_dwordx2 v[234:235], v[26:27], off offset:256
	global_load_dwordx2 v[236:237], v[26:27], off offset:384
	global_load_dwordx2 v[238:239], v[26:27], off offset:1024
	global_load_dwordx2 v[240:241], v[26:27], off offset:1152
	global_load_dwordx2 v[242:243], v[26:27], off offset:1280
	global_load_dwordx2 v[244:245], v[26:27], off offset:1408
	global_load_dwordx4 v[200:203], v[188:189], off
	v_or_b32_e32 v184, 16, v30
	v_or_b32_e32 v180, 32, v30
	v_or_b32_e32 v176, 48, v30
	v_ashrrev_i32_e32 v185, 31, v184
	v_ashrrev_i32_e32 v181, 31, v180
	v_ashrrev_i32_e32 v177, 31, v176
	v_lshlrev_b64 v[0:1], 12, v[30:31]
	v_lshlrev_b64 v[2:3], 13, v[184:185]
	v_lshlrev_b64 v[4:5], 13, v[180:181]
	v_lshlrev_b64 v[6:7], 13, v[176:177]
	v_lshl_add_u64 v[0:1], v[0:1], 0, v[24:25]
	v_lshl_add_u64 v[186:187], v[28:29], 0, v[2:3]
	v_lshl_add_u64 v[182:183], v[28:29], 0, v[4:5]
	v_lshl_add_u64 v[178:179], v[28:29], 0, v[6:7]
	v_lshl_add_u64 v[210:211], s[10:11], 0, v[0:1]
	global_load_dwordx4 v[204:207], v[188:189], off offset:256
	global_load_dwordx4 v[20:23], v[186:187], off
	global_load_dwordx4 v[16:19], v[186:187], off offset:256
	global_load_dwordx4 v[12:15], v[182:183], off
	global_load_dwordx4 v[8:11], v[182:183], off offset:256
	global_load_dwordx4 v[4:7], v[178:179], off
	global_load_dwordx4 v[0:3], v[178:179], off offset:256
	s_mov_b64 s[96:97], 0x100000
	v_lshl_add_u64 v[220:221], v[188:189], 0, s[96:97]
	global_load_dwordx4 v[220:223], v[220:221], off
	v_lshl_add_u64 v[224:225], v[188:189], 0, s[96:97]
	global_load_dwordx4 v[224:227], v[224:225], off offset:256
	v_lshl_add_u64 v[228:229], v[186:187], 0, s[96:97]
	global_load_dwordx4 v[228:231], v[228:229], off
	v_lshl_add_u64 v[246:247], v[186:187], 0, s[96:97]
	global_load_dwordx4 v[246:249], v[246:247], off offset:256
	v_lshl_add_u64 v[250:251], v[182:183], 0, s[96:97]
	global_load_dwordx4 v[250:253], v[250:251], off
	s_waitcnt vmcnt(0)
	v_ffbh_u32_e32 v216, v209
	v_min_u32_e32 v216, 32, v216
	v_lshlrev_b64 v[208:209], v216, v[208:209]
	v_min_u32_e32 v208, 1, v208
	v_or_b32_e32 v208, v209, v208
	v_cvt_f32_u32_e32 v208, v208
	v_lshlrev_b32_e32 v212, 16, v200
	v_and_b32_e32 v213, 0xffff0000, v200
	v_lshlrev_b32_e32 v200, 16, v201
	v_and_b32_e32 v201, 0xffff0000, v201
	v_lshlrev_b32_e32 v214, 16, v202
	v_and_b32_e32 v215, 0xffff0000, v202
	v_lshlrev_b32_e32 v202, 16, v203
	v_and_b32_e32 v203, 0xffff0000, v203
	v_pk_fma_f32 v[158:159], v[158:159], s[18:19], v[200:201] op_sel_hi:[1,0,1]
	v_pk_fma_f32 v[156:157], v[156:157], s[18:19], v[212:213] op_sel_hi:[1,0,1]
	v_pk_fma_f32 v[200:201], v[154:155], s[18:19], v[202:203] op_sel_hi:[1,0,1]
	v_pk_fma_f32 v[202:203], v[152:153], s[18:19], v[214:215] op_sel_hi:[1,0,1]
	v_sub_u32_e32 v212, 32, v216
	v_cvt_pk_bf16_f32 v152, v156, v157
	v_cvt_pk_bf16_f32 v153, v158, v159
	v_cvt_pk_bf16_f32 v154, v202, v203
	v_cvt_pk_bf16_f32 v155, v200, v201
	global_store_dwordx4 v[188:189], v[152:155], off
	v_mul_f32_e32 v213, v157, v157
	v_mul_f32_e32 v214, v159, v159
	v_ldexp_f32 v152, v208, v212
	v_fmamk_f32 v152, v152, 0x2f800000, v197
	v_rsq_f32_e32 v152, v152
	v_mul_f32_e32 v209, v203, v203
	v_fmac_f32_e32 v213, v156, v156
	v_fmac_f32_e32 v214, v158, v158
	v_mul_f32_e32 v208, 0x41fe0000, v152
	v_mul_f32_e32 v152, v208, v156
	v_mul_f32_e32 v153, v208, v157
	v_mul_f32_e32 v155, v208, v158
	v_mul_f32_e32 v156, v208, v159
	v_mul_f32_e32 v158, v208, v203
	v_fmac_f32_e32 v209, v202, v202
	v_mul_f32_e32 v157, v208, v202
	v_mul_f32_e32 v159, v208, v200
	v_mul_f32_e32 v202, v208, v201
	v_med3_f32 v152, v152, s53, v199
	v_med3_f32 v153, v153, s53, v199
	v_med3_f32 v156, v156, s53, v199
	v_med3_f32 v158, v158, s53, v199
	v_med3_f32 v155, v155, s53, v199
	v_med3_f32 v157, v157, s53, v199
	v_med3_f32 v159, v159, s53, v199
	v_med3_f32 v202, v202, s53, v199
	v_rndne_f32_e32 v152, v152
	v_rndne_f32_e32 v153, v153
	v_rndne_f32_e32 v156, v156
	v_rndne_f32_e32 v158, v158
	v_rndne_f32_e32 v155, v155
	v_rndne_f32_e32 v157, v157
	v_rndne_f32_e32 v159, v159
	v_rndne_f32_e32 v202, v202
	v_cvt_i32_f32_e32 v152, v152
	v_cvt_i32_f32_e32 v153, v153
	v_cvt_i32_f32_e32 v156, v156
	v_cvt_i32_f32_e32 v158, v158
	v_cvt_i32_f32_sdwa v155, v155 dst_sel:WORD_1 dst_unused:UNUSED_PAD src0_sel:DWORD
	v_cvt_i32_f32_e32 v157, v157
	v_cvt_i32_f32_sdwa v159, v159 dst_sel:WORD_1 dst_unused:UNUSED_PAD src0_sel:DWORD
	v_cvt_i32_f32_e32 v202, v202
	v_lshlrev_b32_e32 v153, 8, v153
	v_perm_b32 v152, v156, v152, s54
	v_lshlrev_b32_e32 v156, 8, v158
	v_and_b32_e32 v155, 0xff0000, v155
	v_and_b32_e32 v158, 0xff0000, v159
	v_perm_b32 v157, v202, v157, s54
	v_and_b32_e32 v153, 0xff00, v153
	v_and_b32_e32 v156, 0xff00, v156
	v_or3_b32 v152, v152, v153, v155
	v_or3_b32 v153, v157, v156, v158
	v_add_f32_e32 v154, v213, v214
	global_store_dwordx2 v[210:211], v[152:153], off
	v_mul_f32_e32 v153, v201, v201
	v_add_f32_e32 v152, v209, v154
	v_fmac_f32_e32 v153, v200, v200
	v_add_f32_e32 v200, v153, v152
	v_lshlrev_b32_e32 v152, 16, v204
	v_and_b32_e32 v153, 0xffff0000, v204
	v_lshlrev_b32_e32 v154, 16, v205
	v_and_b32_e32 v155, 0xffff0000, v205
	v_lshlrev_b32_e32 v156, 16, v206
	v_and_b32_e32 v157, 0xffff0000, v206
	v_lshlrev_b32_e32 v158, 16, v207
	v_and_b32_e32 v159, 0xffff0000, v207
	v_pk_fma_f32 v[150:151], v[150:151], s[18:19], v[154:155] op_sel_hi:[1,0,1]
	v_pk_fma_f32 v[148:149], v[148:149], s[18:19], v[152:153] op_sel_hi:[1,0,1]
	v_pk_fma_f32 v[154:155], v[144:145], s[18:19], v[156:157] op_sel_hi:[1,0,1]
	v_cvt_pk_bf16_f32 v144, v148, v149
	v_cvt_pk_bf16_f32 v145, v150, v151
	v_pk_fma_f32 v[152:153], v[146:147], s[18:19], v[158:159] op_sel_hi:[1,0,1]
	v_cvt_pk_bf16_f32 v146, v154, v155
	s_nop 0
	v_cvt_pk_bf16_f32 v147, v152, v153
	global_store_dwordx4 v[188:189], v[144:147], off offset:256
	s_nop 1
	v_mul_f32_e32 v145, v208, v149
	v_mul_f32_e32 v144, v208, v148
	v_mul_f32_e32 v146, v208, v150
	v_mul_f32_e32 v147, v208, v151
	v_med3_f32 v145, v145, s53, v199
	v_med3_f32 v144, v144, s53, v199
	v_rndne_f32_e32 v145, v145
	v_med3_f32 v146, v146, s53, v199
	v_med3_f32 v147, v147, s53, v199
	v_rndne_f32_e32 v144, v144
	v_cvt_i32_f32_e32 v145, v145
	v_rndne_f32_e32 v146, v146
	v_rndne_f32_e32 v147, v147
	v_cvt_i32_f32_e32 v144, v144
	v_cvt_i32_f32_sdwa v146, v146 dst_sel:WORD_1 dst_unused:UNUSED_PAD src0_sel:DWORD
	v_cvt_i32_f32_e32 v147, v147
	v_lshlrev_b32_e32 v145, 8, v145
	v_and_b32_e32 v145, 0xff00, v145
	v_and_b32_e32 v146, 0xff0000, v146
	v_perm_b32 v144, v147, v144, s54
	v_or3_b32 v156, v144, v145, v146
	v_mul_f32_e32 v145, v208, v155
	v_med3_f32 v145, v145, s53, v199
	v_rndne_f32_e32 v145, v145
	v_cvt_i32_f32_e32 v145, v145
	v_mul_f32_e32 v144, v208, v154
	v_med3_f32 v144, v144, s53, v199
	v_rndne_f32_e32 v144, v144
	v_mul_f32_e32 v146, v208, v152
	v_cvt_i32_f32_e32 v157, v144
	v_lshlrev_b32_e32 v144, 8, v145
	v_and_b32_e32 v158, 0xff00, v144
	v_med3_f32 v144, v146, s53, v199
	v_rndne_f32_e32 v145, v144
	v_mul_f32_e32 v144, v149, v149
	v_mul_f32_e32 v146, v151, v151
	v_fmac_f32_e32 v144, v148, v148
	v_fmac_f32_e32 v146, v150, v150
	v_add_f32_e32 v144, v144, v146
	v_mul_f32_e32 v146, v155, v155
	v_fmac_f32_e32 v146, v154, v154
	v_add_f32_e32 v144, v146, v144
	v_mul_f32_e32 v146, v153, v153
	v_fmac_f32_e32 v146, v152, v152
	v_add_f32_e32 v144, v146, v144
	v_and_b32_e32 v148, 64, v198
	v_add_f32_e32 v146, v200, v144
	v_xor_b32_e32 v144, 16, v198
	v_add_u32_e32 v148, 64, v148
	v_cmp_lt_i32_e32 vcc, v144, v148
	v_mul_f32_e32 v147, v208, v153
	v_cvt_i32_f32_sdwa v150, v145 dst_sel:WORD_1 dst_unused:UNUSED_PAD src0_sel:DWORD
	v_cndmask_b32_e32 v144, v198, v144, vcc
	v_lshlrev_b32_e32 v144, 2, v144
	ds_bpermute_b32 v149, v144, v146
	v_med3_f32 v145, v147, s53, v199
	v_rndne_f32_e32 v145, v145
	v_cvt_i32_f32_e32 v151, v145
	v_xor_b32_e32 v145, 32, v198
	v_cmp_lt_i32_e32 vcc, v145, v148
	s_waitcnt lgkmcnt(0)
	v_add_f32_e32 v146, v146, v149
	v_and_b32_e32 v148, 0xff0000, v150
	v_cndmask_b32_e32 v145, v198, v145, vcc
	v_lshlrev_b32_e32 v145, 2, v145
	ds_bpermute_b32 v147, v145, v146
	v_perm_b32 v149, v151, v157, s54
	v_or3_b32 v157, v149, v158, v148
	global_store_dwordx2 v[210:211], v[156:157], off offset:128
	s_and_saveexec_b64 s[28:29], s[2:3]
	s_cbranch_execz .LBB0_1260
	s_waitcnt lgkmcnt(0)
	v_add_f32_e32 v146, v146, v147
	v_fma_f32 v146, v146, s55, 0.5
	v_trunc_f32_e32 v146, v146
	v_mul_f32_e32 v147, 0x2f800000, v146
	v_floor_f32_e32 v147, v147
	v_fmac_f32_e32 v146, 0xcf800000, v147
	v_cvt_u32_f32_e32 v146, v146
	v_cvt_u32_f32_e32 v147, v147
	v_lshl_add_u64 v[148:149], v[30:31], 3, s[8:9]
	global_atomic_add_x2 v[148:149], v[146:147], off
.LBB0_1260:
	s_or_b64 exec, exec, s[28:29]
	s_waitcnt lgkmcnt(0)
	v_lshl_add_u64 v[146:147], v[184:185], 3, s[12:13]
	v_mov_b32_e32 v146, v232
	v_mov_b32_e32 v147, v233
	v_lshlrev_b32_e32 v150, 16, v20
	v_and_b32_e32 v151, 0xffff0000, v20
	v_lshlrev_b32_e32 v154, 16, v16
	v_and_b32_e32 v155, 0xffff0000, v16
	v_lshlrev_b32_e32 v16, 16, v17
	v_and_b32_e32 v17, 0xffff0000, v17
	v_lshlrev_b32_e32 v20, 16, v21
	v_and_b32_e32 v21, 0xffff0000, v21
	v_lshlrev_b32_e32 v152, 16, v22
	v_and_b32_e32 v153, 0xffff0000, v22
	v_lshlrev_b32_e32 v22, 16, v23
	v_and_b32_e32 v23, 0xffff0000, v23
	v_lshlrev_b32_e32 v156, 16, v18
	v_and_b32_e32 v157, 0xffff0000, v18
	v_lshlrev_b32_e32 v18, 16, v19
	v_and_b32_e32 v19, 0xffff0000, v19
	v_pk_fma_f32 v[140:141], v[140:141], s[18:19], v[150:151] op_sel_hi:[1,0,1]
	v_pk_fma_f32 v[134:135], v[134:135], s[18:19], v[16:17] op_sel_hi:[1,0,1]
	v_cvt_pk_bf16_f32 v16, v140, v141
	v_pk_fma_f32 v[20:21], v[142:143], s[18:19], v[20:21] op_sel_hi:[1,0,1]
	v_pk_fma_f32 v[22:23], v[138:139], s[18:19], v[22:23] op_sel_hi:[1,0,1]
	v_pk_fma_f32 v[136:137], v[136:137], s[18:19], v[152:153] op_sel_hi:[1,0,1]
	v_pk_fma_f32 v[130:131], v[130:131], s[18:19], v[18:19] op_sel_hi:[1,0,1]
	v_cvt_pk_bf16_f32 v17, v20, v21
	v_cvt_pk_bf16_f32 v18, v136, v137
	v_cvt_pk_bf16_f32 v19, v22, v23
	global_store_dwordx4 v[186:187], v[16:19], off
	v_lshlrev_b64 v[148:149], 12, v[184:185]
	v_mul_f32_e32 v31, v141, v141
	v_mul_f32_e32 v142, v21, v21
	v_lshl_add_u64 v[148:149], v[148:149], 0, v[24:25]
	v_mul_f32_e32 v143, v137, v137
	v_fmac_f32_e32 v31, v140, v140
	v_fmac_f32_e32 v142, v20, v20
	v_lshl_add_u64 v[138:139], s[10:11], 0, v[148:149]
	v_mul_f32_e32 v148, v23, v23
	v_fmac_f32_e32 v143, v136, v136
	v_fmac_f32_e32 v148, v22, v22
	v_pk_fma_f32 v[132:133], v[132:133], s[18:19], v[154:155] op_sel_hi:[1,0,1]
	v_pk_fma_f32 v[128:129], v[128:129], s[18:19], v[156:157] op_sel_hi:[1,0,1]
	v_ffbh_u32_e32 v16, v147
	v_min_u32_e32 v18, 32, v16
	v_lshlrev_b64 v[16:17], v18, v[146:147]
	v_min_u32_e32 v16, 1, v16
	v_or_b32_e32 v16, v17, v16
	v_cvt_f32_u32_e32 v16, v16
	v_sub_u32_e32 v17, 32, v18
	v_ldexp_f32 v16, v16, v17
	v_fmamk_f32 v16, v16, 0x2f800000, v197
	v_rsq_f32_e32 v16, v16
	v_add_f32_e32 v17, v31, v142
	v_add_f32_e32 v17, v143, v17
	v_add_f32_e32 v31, v148, v17
	v_mul_f32_e32 v142, 0x41fe0000, v16
	v_mul_f32_e32 v16, v140, v142
	v_mul_f32_e32 v17, v141, v142
	v_mul_f32_e32 v19, v21, v142
	v_mul_f32_e32 v21, v137, v142
	v_mul_f32_e32 v18, v20, v142
	v_mul_f32_e32 v20, v136, v142
	v_mul_f32_e32 v22, v22, v142
	v_mul_f32_e32 v23, v23, v142
	v_med3_f32 v16, v16, s53, v199
	v_med3_f32 v17, v17, s53, v199
	v_med3_f32 v19, v19, s53, v199
	v_med3_f32 v21, v21, s53, v199
	v_med3_f32 v18, v18, s53, v199
	v_med3_f32 v20, v20, s53, v199
	v_med3_f32 v22, v22, s53, v199
	v_med3_f32 v23, v23, s53, v199
	v_rndne_f32_e32 v16, v16
	v_rndne_f32_e32 v17, v17
	v_rndne_f32_e32 v19, v19
	v_rndne_f32_e32 v21, v21
	v_rndne_f32_e32 v18, v18
	v_rndne_f32_e32 v20, v20
	v_rndne_f32_e32 v22, v22
	v_rndne_f32_e32 v23, v23
	v_cvt_i32_f32_e32 v16, v16
	v_cvt_i32_f32_e32 v17, v17
	v_cvt_i32_f32_e32 v19, v19
	v_cvt_i32_f32_e32 v21, v21
	v_cvt_i32_f32_sdwa v18, v18 dst_sel:WORD_1 dst_unused:UNUSED_PAD src0_sel:DWORD
	v_cvt_i32_f32_e32 v20, v20
	v_cvt_i32_f32_sdwa v22, v22 dst_sel:WORD_1 dst_unused:UNUSED_PAD src0_sel:DWORD
	v_cvt_i32_f32_e32 v23, v23
	v_lshlrev_b32_e32 v17, 8, v17
	v_perm_b32 v16, v19, v16, s54
	v_lshlrev_b32_e32 v19, 8, v21
	v_and_b32_e32 v18, 0xff0000, v18
	v_and_b32_e32 v21, 0xff0000, v22
	v_perm_b32 v20, v23, v20, s54
	v_and_b32_e32 v17, 0xff00, v17
	v_and_b32_e32 v19, 0xff00, v19
	v_or3_b32 v16, v16, v17, v18
	v_or3_b32 v17, v20, v19, v21
	v_mul_f32_e32 v137, v133, v142
	global_store_dwordx2 v[138:139], v[16:17], off
	v_cvt_pk_bf16_f32 v16, v132, v133
	v_cvt_pk_bf16_f32 v17, v134, v135
	v_mul_f32_e32 v136, v132, v142
	v_mul_f32_e32 v140, v134, v142
	v_mul_f32_e32 v141, v135, v142
	v_cvt_pk_bf16_f32 v18, v128, v129
	v_cvt_pk_bf16_f32 v19, v130, v131
	global_store_dwordx4 v[186:187], v[16:19], off offset:256
	v_med3_f32 v136, v136, s53, v199
	v_mul_f32_e32 v20, v131, v142
	v_med3_f32 v17, v137, s53, v199
	v_rndne_f32_e32 v17, v17
	v_med3_f32 v18, v140, s53, v199
	v_med3_f32 v19, v141, s53, v199
	v_rndne_f32_e32 v16, v136
	v_cvt_i32_f32_e32 v17, v17
	v_rndne_f32_e32 v18, v18
	v_rndne_f32_e32 v19, v19
	v_cvt_i32_f32_e32 v16, v16
	v_cvt_i32_f32_sdwa v18, v18 dst_sel:WORD_1 dst_unused:UNUSED_PAD src0_sel:DWORD
	v_cvt_i32_f32_e32 v19, v19
	v_lshlrev_b32_e32 v17, 8, v17
	v_and_b32_e32 v17, 0xff00, v17
	v_and_b32_e32 v18, 0xff0000, v18
	v_perm_b32 v16, v19, v16, s54
	v_or3_b32 v18, v16, v17, v18
	v_mul_f32_e32 v17, v129, v142
	v_med3_f32 v17, v17, s53, v199
	v_rndne_f32_e32 v17, v17
	v_cvt_i32_f32_e32 v17, v17
	v_mul_f32_e32 v16, v128, v142
	v_med3_f32 v16, v16, s53, v199
	v_rndne_f32_e32 v16, v16
	v_mul_f32_e32 v19, v130, v142
	v_cvt_i32_f32_e32 v21, v16
	v_lshlrev_b32_e32 v16, 8, v17
	v_and_b32_e32 v22, 0xff00, v16
	v_med3_f32 v16, v19, s53, v199
	v_mul_f32_e32 v17, v133, v133
	v_mul_f32_e32 v19, v135, v135
	v_fmac_f32_e32 v17, v132, v132
	v_fmac_f32_e32 v19, v134, v134
	v_add_f32_e32 v17, v17, v19
	v_mul_f32_e32 v19, v129, v129
	v_fmac_f32_e32 v19, v128, v128
	v_add_f32_e32 v17, v19, v17
	v_mul_f32_e32 v19, v131, v131
	v_fmac_f32_e32 v19, v130, v130
	v_add_f32_e32 v17, v19, v17
	v_add_f32_e32 v17, v31, v17
	ds_bpermute_b32 v19, v144, v17
	v_rndne_f32_e32 v16, v16
	v_cvt_i32_f32_sdwa v23, v16 dst_sel:WORD_1 dst_unused:UNUSED_PAD src0_sel:DWORD
	v_med3_f32 v16, v20, s53, v199
	v_rndne_f32_e32 v16, v16
	v_cvt_i32_f32_e32 v20, v16
	s_waitcnt lgkmcnt(0)
	v_add_f32_e32 v16, v17, v19
	ds_bpermute_b32 v17, v145, v16
	v_and_b32_e32 v19, 0xff0000, v23
	v_perm_b32 v20, v20, v21, s54
	v_or3_b32 v19, v20, v22, v19
	global_store_dwordx2 v[138:139], v[18:19], off offset:128
	s_and_saveexec_b64 s[28:29], s[2:3]
	s_cbranch_execz .LBB0_1262
	s_waitcnt lgkmcnt(0)
	v_add_f32_e32 v16, v16, v17
	v_fma_f32 v16, v16, s55, 0.5
	v_trunc_f32_e32 v16, v16
	v_mul_f32_e32 v17, 0x2f800000, v16
	v_floor_f32_e32 v17, v17
	v_fmac_f32_e32 v16, 0xcf800000, v17
	v_cvt_u32_f32_e32 v16, v16
	v_cvt_u32_f32_e32 v17, v17
	v_lshl_add_u64 v[18:19], v[184:185], 3, s[8:9]
	global_atomic_add_x2 v[18:19], v[16:17], off
.LBB0_1262:
	s_or_b64 exec, exec, s[28:29]
	s_waitcnt lgkmcnt(0)
	v_lshl_add_u64 v[16:17], v[180:181], 3, s[12:13]
	v_mov_b32_e32 v16, v234
	v_mov_b32_e32 v17, v235
	v_lshlrev_b32_e32 v20, 16, v12
	v_and_b32_e32 v21, 0xffff0000, v12
	v_lshlrev_b32_e32 v128, 16, v8
	v_and_b32_e32 v129, 0xffff0000, v8
	v_lshlrev_b32_e32 v8, 16, v9
	v_and_b32_e32 v9, 0xffff0000, v9
	v_lshlrev_b32_e32 v12, 16, v13
	v_and_b32_e32 v13, 0xffff0000, v13
	v_lshlrev_b32_e32 v22, 16, v14
	v_and_b32_e32 v23, 0xffff0000, v14
	v_lshlrev_b32_e32 v14, 16, v15
	v_and_b32_e32 v15, 0xffff0000, v15
	v_lshlrev_b32_e32 v130, 16, v10
	v_and_b32_e32 v131, 0xffff0000, v10
	v_lshlrev_b32_e32 v10, 16, v11
	v_and_b32_e32 v11, 0xffff0000, v11
	v_pk_fma_f32 v[20:21], v[124:125], s[18:19], v[20:21] op_sel_hi:[1,0,1]
	v_pk_fma_f32 v[118:119], v[118:119], s[18:19], v[8:9] op_sel_hi:[1,0,1]
	v_cvt_pk_bf16_f32 v8, v20, v21
	v_pk_fma_f32 v[12:13], v[126:127], s[18:19], v[12:13] op_sel_hi:[1,0,1]
	v_pk_fma_f32 v[14:15], v[122:123], s[18:19], v[14:15] op_sel_hi:[1,0,1]
	v_pk_fma_f32 v[22:23], v[120:121], s[18:19], v[22:23] op_sel_hi:[1,0,1]
	v_pk_fma_f32 v[114:115], v[114:115], s[18:19], v[10:11] op_sel_hi:[1,0,1]
	v_cvt_pk_bf16_f32 v9, v12, v13
	v_cvt_pk_bf16_f32 v10, v22, v23
	v_cvt_pk_bf16_f32 v11, v14, v15
	global_store_dwordx4 v[182:183], v[8:11], off
	v_mul_f32_e32 v31, v21, v21
	v_mul_f32_e32 v120, v13, v13
	v_mul_f32_e32 v121, v23, v23
	v_fmac_f32_e32 v31, v20, v20
	v_fmac_f32_e32 v120, v12, v12
	v_mul_f32_e32 v122, v15, v15
	v_fmac_f32_e32 v121, v22, v22
	v_fmac_f32_e32 v122, v14, v14
	v_lshlrev_b64 v[18:19], 12, v[180:181]
	v_lshl_add_u64 v[18:19], v[18:19], 0, v[24:25]
	v_pk_fma_f32 v[116:117], v[116:117], s[18:19], v[128:129] op_sel_hi:[1,0,1]
	v_lshl_add_u64 v[18:19], s[10:11], 0, v[18:19]
	v_pk_fma_f32 v[112:113], v[112:113], s[18:19], v[130:131] op_sel_hi:[1,0,1]
	v_ffbh_u32_e32 v8, v17
	v_min_u32_e32 v10, 32, v8
	v_lshlrev_b64 v[8:9], v10, v[16:17]
	v_min_u32_e32 v8, 1, v8
	v_or_b32_e32 v8, v9, v8
	v_cvt_f32_u32_e32 v8, v8
	v_sub_u32_e32 v9, 32, v10
	v_ldexp_f32 v8, v8, v9
	v_fmamk_f32 v8, v8, 0x2f800000, v197
	v_rsq_f32_e32 v8, v8
	v_add_f32_e32 v9, v31, v120
	v_add_f32_e32 v9, v121, v9
	v_add_f32_e32 v16, v122, v9
	v_mul_f32_e32 v17, 0x41fe0000, v8
	v_mul_f32_e32 v8, v20, v17
	v_mul_f32_e32 v9, v21, v17
	v_mul_f32_e32 v11, v13, v17
	v_mul_f32_e32 v13, v23, v17
	v_mul_f32_e32 v10, v12, v17
	v_mul_f32_e32 v12, v22, v17
	v_mul_f32_e32 v14, v14, v17
	v_mul_f32_e32 v15, v15, v17
	v_med3_f32 v8, v8, s53, v199
	v_med3_f32 v9, v9, s53, v199
	v_med3_f32 v11, v11, s53, v199
	v_med3_f32 v13, v13, s53, v199
	v_med3_f32 v10, v10, s53, v199
	v_med3_f32 v12, v12, s53, v199
	v_med3_f32 v14, v14, s53, v199
	v_med3_f32 v15, v15, s53, v199
	v_rndne_f32_e32 v8, v8
	v_rndne_f32_e32 v9, v9
	v_rndne_f32_e32 v11, v11
	v_rndne_f32_e32 v13, v13
	v_rndne_f32_e32 v10, v10
	v_rndne_f32_e32 v12, v12
	v_rndne_f32_e32 v14, v14
	v_rndne_f32_e32 v15, v15
	v_cvt_i32_f32_e32 v8, v8
	v_cvt_i32_f32_e32 v9, v9
	v_cvt_i32_f32_e32 v11, v11
	v_cvt_i32_f32_e32 v13, v13
	v_cvt_i32_f32_sdwa v10, v10 dst_sel:WORD_1 dst_unused:UNUSED_PAD src0_sel:DWORD
	v_cvt_i32_f32_e32 v12, v12
	v_cvt_i32_f32_sdwa v14, v14 dst_sel:WORD_1 dst_unused:UNUSED_PAD src0_sel:DWORD
	v_cvt_i32_f32_e32 v15, v15
	v_lshlrev_b32_e32 v9, 8, v9
	v_perm_b32 v8, v11, v8, s54
	v_lshlrev_b32_e32 v11, 8, v13
	v_and_b32_e32 v10, 0xff0000, v10
	v_and_b32_e32 v13, 0xff0000, v14
	v_perm_b32 v12, v15, v12, s54
	v_and_b32_e32 v9, 0xff00, v9
	v_and_b32_e32 v11, 0xff00, v11
	v_or3_b32 v8, v8, v9, v10
	v_or3_b32 v9, v12, v11, v13
	v_mul_f32_e32 v21, v117, v17
	global_store_dwordx2 v[18:19], v[8:9], off
	v_cvt_pk_bf16_f32 v8, v116, v117
	v_cvt_pk_bf16_f32 v9, v118, v119
	v_mul_f32_e32 v20, v116, v17
	v_mul_f32_e32 v22, v118, v17
	v_mul_f32_e32 v23, v119, v17
	v_cvt_pk_bf16_f32 v10, v112, v113
	v_cvt_pk_bf16_f32 v11, v114, v115
	global_store_dwordx4 v[182:183], v[8:11], off offset:256
	v_med3_f32 v20, v20, s53, v199
	v_mul_f32_e32 v12, v115, v17
	v_med3_f32 v9, v21, s53, v199
	v_rndne_f32_e32 v9, v9
	v_med3_f32 v10, v22, s53, v199
	v_med3_f32 v11, v23, s53, v199
	v_rndne_f32_e32 v8, v20
	v_cvt_i32_f32_e32 v9, v9
	v_rndne_f32_e32 v10, v10
	v_rndne_f32_e32 v11, v11
	v_cvt_i32_f32_e32 v8, v8
	v_cvt_i32_f32_sdwa v10, v10 dst_sel:WORD_1 dst_unused:UNUSED_PAD src0_sel:DWORD
	v_cvt_i32_f32_e32 v11, v11
	v_lshlrev_b32_e32 v9, 8, v9
	v_and_b32_e32 v9, 0xff00, v9
	v_and_b32_e32 v10, 0xff0000, v10
	v_perm_b32 v8, v11, v8, s54
	v_or3_b32 v10, v8, v9, v10
	v_mul_f32_e32 v9, v113, v17
	v_med3_f32 v9, v9, s53, v199
	v_rndne_f32_e32 v9, v9
	v_cvt_i32_f32_e32 v9, v9
	v_mul_f32_e32 v8, v112, v17
	v_med3_f32 v8, v8, s53, v199
	v_rndne_f32_e32 v8, v8
	v_mul_f32_e32 v11, v114, v17
	v_cvt_i32_f32_e32 v13, v8
	v_lshlrev_b32_e32 v8, 8, v9
	v_and_b32_e32 v14, 0xff00, v8
	v_med3_f32 v8, v11, s53, v199
	v_mul_f32_e32 v9, v117, v117
	v_mul_f32_e32 v11, v119, v119
	v_fmac_f32_e32 v9, v116, v116
	v_fmac_f32_e32 v11, v118, v118
	v_add_f32_e32 v9, v9, v11
	v_mul_f32_e32 v11, v113, v113
	v_fmac_f32_e32 v11, v112, v112
	v_add_f32_e32 v9, v11, v9
	v_mul_f32_e32 v11, v115, v115
	v_fmac_f32_e32 v11, v114, v114
	v_add_f32_e32 v9, v11, v9
	v_add_f32_e32 v9, v16, v9
	ds_bpermute_b32 v11, v144, v9
	v_rndne_f32_e32 v8, v8
	v_cvt_i32_f32_sdwa v15, v8 dst_sel:WORD_1 dst_unused:UNUSED_PAD src0_sel:DWORD
	v_med3_f32 v8, v12, s53, v199
	v_rndne_f32_e32 v8, v8
	v_cvt_i32_f32_e32 v12, v8
	s_waitcnt lgkmcnt(0)
	v_add_f32_e32 v8, v9, v11
	ds_bpermute_b32 v9, v145, v8
	v_and_b32_e32 v11, 0xff0000, v15
	v_perm_b32 v12, v12, v13, s54
	v_or3_b32 v11, v12, v14, v11
	global_store_dwordx2 v[18:19], v[10:11], off offset:128
	s_and_saveexec_b64 s[28:29], s[2:3]
	s_cbranch_execz .LBB0_1264
	s_waitcnt lgkmcnt(0)
	v_add_f32_e32 v8, v8, v9
	v_fma_f32 v8, v8, s55, 0.5
	v_trunc_f32_e32 v8, v8
	v_mul_f32_e32 v9, 0x2f800000, v8
	v_floor_f32_e32 v9, v9
	v_fmac_f32_e32 v8, 0xcf800000, v9
	v_cvt_u32_f32_e32 v8, v8
	v_cvt_u32_f32_e32 v9, v9
	v_lshl_add_u64 v[10:11], v[180:181], 3, s[8:9]
	global_atomic_add_x2 v[10:11], v[8:9], off
.LBB0_1264:
	s_or_b64 exec, exec, s[28:29]
	s_waitcnt lgkmcnt(0)
	v_lshl_add_u64 v[8:9], v[176:177], 3, s[12:13]
	v_mov_b32_e32 v8, v236
	v_mov_b32_e32 v9, v237
	v_lshlrev_b32_e32 v12, 16, v4
	v_and_b32_e32 v13, 0xffff0000, v4
	v_lshlrev_b32_e32 v16, 16, v0
	v_and_b32_e32 v17, 0xffff0000, v0
	v_lshlrev_b32_e32 v0, 16, v1
	v_and_b32_e32 v1, 0xffff0000, v1
	v_lshlrev_b32_e32 v4, 16, v5
	v_and_b32_e32 v5, 0xffff0000, v5
	v_lshlrev_b32_e32 v14, 16, v6
	v_and_b32_e32 v15, 0xffff0000, v6
	v_lshlrev_b32_e32 v6, 16, v7
	v_and_b32_e32 v7, 0xffff0000, v7
	v_lshlrev_b32_e32 v18, 16, v2
	v_and_b32_e32 v19, 0xffff0000, v2
	v_lshlrev_b32_e32 v2, 16, v3
	v_and_b32_e32 v3, 0xffff0000, v3
	v_pk_fma_f32 v[12:13], v[108:109], s[18:19], v[12:13] op_sel_hi:[1,0,1]
	v_pk_fma_f32 v[20:21], v[102:103], s[18:19], v[0:1] op_sel_hi:[1,0,1]
	v_cvt_pk_bf16_f32 v0, v12, v13
	v_pk_fma_f32 v[4:5], v[110:111], s[18:19], v[4:5] op_sel_hi:[1,0,1]
	v_pk_fma_f32 v[6:7], v[106:107], s[18:19], v[6:7] op_sel_hi:[1,0,1]
	v_pk_fma_f32 v[14:15], v[104:105], s[18:19], v[14:15] op_sel_hi:[1,0,1]
	v_pk_fma_f32 v[22:23], v[98:99], s[18:19], v[2:3] op_sel_hi:[1,0,1]
	v_cvt_pk_bf16_f32 v1, v4, v5
	v_cvt_pk_bf16_f32 v2, v14, v15
	v_cvt_pk_bf16_f32 v3, v6, v7
	global_store_dwordx4 v[178:179], v[0:3], off
	v_pk_fma_f32 v[18:19], v[96:97], s[18:19], v[18:19] op_sel_hi:[1,0,1]
	v_mul_f32_e32 v31, v13, v13
	v_mul_f32_e32 v96, v5, v5
	v_mul_f32_e32 v97, v15, v15
	v_fmac_f32_e32 v31, v12, v12
	v_fmac_f32_e32 v96, v4, v4
	v_mul_f32_e32 v98, v7, v7
	v_fmac_f32_e32 v97, v14, v14
	v_fmac_f32_e32 v98, v6, v6
	v_lshlrev_b64 v[10:11], 12, v[176:177]
	v_lshl_add_u64 v[10:11], v[10:11], 0, v[24:25]
	v_pk_fma_f32 v[16:17], v[100:101], s[18:19], v[16:17] op_sel_hi:[1,0,1]
	v_lshl_add_u64 v[10:11], s[10:11], 0, v[10:11]
	v_ffbh_u32_e32 v0, v9
	v_min_u32_e32 v2, 32, v0
	v_lshlrev_b64 v[0:1], v2, v[8:9]
	v_min_u32_e32 v0, 1, v0
	v_or_b32_e32 v0, v1, v0
	v_cvt_f32_u32_e32 v0, v0
	v_sub_u32_e32 v1, 32, v2
	v_ldexp_f32 v0, v0, v1
	v_fmamk_f32 v0, v0, 0x2f800000, v197
	v_rsq_f32_e32 v0, v0
	v_add_f32_e32 v1, v31, v96
	v_add_f32_e32 v1, v97, v1
	v_add_f32_e32 v8, v98, v1
	v_mul_f32_e32 v9, 0x41fe0000, v0
	v_mul_f32_e32 v0, v12, v9
	v_mul_f32_e32 v1, v13, v9
	v_mul_f32_e32 v3, v5, v9
	v_mul_f32_e32 v5, v15, v9
	v_mul_f32_e32 v2, v4, v9
	v_mul_f32_e32 v4, v14, v9
	v_mul_f32_e32 v6, v6, v9
	v_mul_f32_e32 v7, v7, v9
	v_med3_f32 v0, v0, s53, v199
	v_med3_f32 v1, v1, s53, v199
	v_med3_f32 v3, v3, s53, v199
	v_med3_f32 v5, v5, s53, v199
	v_med3_f32 v2, v2, s53, v199
	v_med3_f32 v4, v4, s53, v199
	v_med3_f32 v6, v6, s53, v199
	v_med3_f32 v7, v7, s53, v199
	v_rndne_f32_e32 v0, v0
	v_rndne_f32_e32 v1, v1
	v_rndne_f32_e32 v3, v3
	v_rndne_f32_e32 v5, v5
	v_rndne_f32_e32 v2, v2
	v_rndne_f32_e32 v4, v4
	v_rndne_f32_e32 v6, v6
	v_rndne_f32_e32 v7, v7
	v_cvt_i32_f32_e32 v0, v0
	v_cvt_i32_f32_e32 v1, v1
	v_cvt_i32_f32_e32 v3, v3
	v_cvt_i32_f32_e32 v5, v5
	v_cvt_i32_f32_sdwa v2, v2 dst_sel:WORD_1 dst_unused:UNUSED_PAD src0_sel:DWORD
	v_cvt_i32_f32_e32 v4, v4
	v_cvt_i32_f32_sdwa v6, v6 dst_sel:WORD_1 dst_unused:UNUSED_PAD src0_sel:DWORD
	v_cvt_i32_f32_e32 v7, v7
	v_lshlrev_b32_e32 v1, 8, v1
	v_perm_b32 v0, v3, v0, s54
	v_lshlrev_b32_e32 v3, 8, v5
	v_and_b32_e32 v2, 0xff0000, v2
	v_and_b32_e32 v5, 0xff0000, v6
	v_perm_b32 v4, v7, v4, s54
	v_and_b32_e32 v1, 0xff00, v1
	v_and_b32_e32 v3, 0xff00, v3
	v_or3_b32 v0, v0, v1, v2
	v_or3_b32 v1, v4, v3, v5
	v_mul_f32_e32 v13, v17, v9
	global_store_dwordx2 v[10:11], v[0:1], off
	v_cvt_pk_bf16_f32 v0, v16, v17
	v_cvt_pk_bf16_f32 v1, v20, v21
	v_mul_f32_e32 v12, v16, v9
	v_mul_f32_e32 v14, v20, v9
	v_mul_f32_e32 v15, v21, v9
	v_cvt_pk_bf16_f32 v2, v18, v19
	v_cvt_pk_bf16_f32 v3, v22, v23
	global_store_dwordx4 v[178:179], v[0:3], off offset:256
	v_med3_f32 v12, v12, s53, v199
	v_mul_f32_e32 v4, v23, v9
	v_med3_f32 v1, v13, s53, v199
	v_rndne_f32_e32 v1, v1
	v_med3_f32 v2, v14, s53, v199
	v_med3_f32 v3, v15, s53, v199
	v_rndne_f32_e32 v0, v12
	v_cvt_i32_f32_e32 v1, v1
	v_rndne_f32_e32 v2, v2
	v_rndne_f32_e32 v3, v3
	v_cvt_i32_f32_e32 v0, v0
	v_cvt_i32_f32_sdwa v2, v2 dst_sel:WORD_1 dst_unused:UNUSED_PAD src0_sel:DWORD
	v_cvt_i32_f32_e32 v3, v3
	v_lshlrev_b32_e32 v1, 8, v1
	v_and_b32_e32 v1, 0xff00, v1
	v_and_b32_e32 v2, 0xff0000, v2
	v_perm_b32 v0, v3, v0, s54
	v_or3_b32 v2, v0, v1, v2
	v_mul_f32_e32 v1, v19, v9
	v_med3_f32 v1, v1, s53, v199
	v_rndne_f32_e32 v1, v1
	v_cvt_i32_f32_e32 v1, v1
	v_mul_f32_e32 v0, v18, v9
	v_med3_f32 v0, v0, s53, v199
	v_rndne_f32_e32 v0, v0
	v_mul_f32_e32 v3, v22, v9
	v_cvt_i32_f32_e32 v5, v0
	v_lshlrev_b32_e32 v0, 8, v1
	v_and_b32_e32 v6, 0xff00, v0
	v_med3_f32 v0, v3, s53, v199
	v_mul_f32_e32 v1, v17, v17
	v_mul_f32_e32 v3, v21, v21
	v_fmac_f32_e32 v1, v16, v16
	v_fmac_f32_e32 v3, v20, v20
	v_add_f32_e32 v1, v1, v3
	v_mul_f32_e32 v3, v19, v19
	v_fmac_f32_e32 v3, v18, v18
	v_add_f32_e32 v1, v3, v1
	v_mul_f32_e32 v3, v23, v23
	v_fmac_f32_e32 v3, v22, v22
	v_add_f32_e32 v1, v3, v1
	v_add_f32_e32 v1, v8, v1
	ds_bpermute_b32 v3, v144, v1
	v_rndne_f32_e32 v0, v0
	v_cvt_i32_f32_sdwa v7, v0 dst_sel:WORD_1 dst_unused:UNUSED_PAD src0_sel:DWORD
	v_med3_f32 v0, v4, s53, v199
	v_rndne_f32_e32 v0, v0
	v_cvt_i32_f32_e32 v4, v0
	s_waitcnt lgkmcnt(0)
	v_add_f32_e32 v0, v1, v3
	ds_bpermute_b32 v1, v145, v0
	v_and_b32_e32 v3, 0xff0000, v7
	v_perm_b32 v4, v4, v5, s54
	v_or3_b32 v3, v4, v6, v3
	global_store_dwordx2 v[10:11], v[2:3], off offset:128
	s_and_saveexec_b64 s[28:29], s[2:3]
	s_cbranch_execz .LBB0_1266
	s_waitcnt lgkmcnt(0)
	v_add_f32_e32 v0, v0, v1
	v_fma_f32 v0, v0, s55, 0.5
	v_trunc_f32_e32 v0, v0
	v_mul_f32_e32 v1, 0x2f800000, v0
	v_floor_f32_e32 v1, v1
	v_fmac_f32_e32 v0, 0xcf800000, v1
	v_cvt_u32_f32_e32 v0, v0
	v_cvt_u32_f32_e32 v1, v1
	v_lshl_add_u64 v[2:3], v[176:177], 3, s[8:9]
	global_atomic_add_x2 v[2:3], v[0:1], off
.LBB0_1266:
	s_or_b64 exec, exec, s[28:29]
	v_add_u32_e32 v104, 0x80, v30
	v_ashrrev_i32_e32 v105, 31, v104
	s_waitcnt lgkmcnt(0)
	v_lshlrev_b64 v[0:1], 13, v[104:105]
	v_lshl_add_u64 v[106:107], v[28:29], 0, v[0:1]
	v_mov_b32_e32 v116, v238
	v_mov_b32_e32 v117, v239
	v_mov_b32_e32 v108, v220
	v_mov_b32_e32 v109, v221
	v_mov_b32_e32 v110, v222
	v_mov_b32_e32 v111, v223
	v_add_u32_e32 v100, 0x90, v30
	v_add_u32_e32 v96, 0xa0, v30
	v_add_u32_e32 v30, 0xb0, v30
	v_ashrrev_i32_e32 v101, 31, v100
	v_ashrrev_i32_e32 v97, 31, v96
	v_ashrrev_i32_e32 v31, 31, v30
	v_lshlrev_b64 v[0:1], 13, v[100:101]
	v_lshlrev_b64 v[2:3], 13, v[96:97]
	v_lshlrev_b64 v[4:5], 13, v[30:31]
	v_lshlrev_b64 v[6:7], 12, v[104:105]
	v_lshl_add_u64 v[102:103], v[28:29], 0, v[0:1]
	v_lshl_add_u64 v[98:99], v[28:29], 0, v[2:3]
	v_lshl_add_u64 v[28:29], v[28:29], 0, v[4:5]
	v_lshl_add_u64 v[118:119], v[6:7], 0, v[24:25]
	v_mov_b32_e32 v112, v224
	v_mov_b32_e32 v113, v225
	v_mov_b32_e32 v114, v226
	v_mov_b32_e32 v115, v227
	v_mov_b32_e32 v20, v228
	v_mov_b32_e32 v21, v229
	v_mov_b32_e32 v22, v230
	v_mov_b32_e32 v23, v231
	v_mov_b32_e32 v16, v246
	v_mov_b32_e32 v17, v247
	v_mov_b32_e32 v18, v248
	v_mov_b32_e32 v19, v249
	v_mov_b32_e32 v12, v250
	v_mov_b32_e32 v13, v251
	v_mov_b32_e32 v14, v252
	v_mov_b32_e32 v15, v253
	global_load_dwordx4 v[8:11], v[98:99], off offset:256
	global_load_dwordx4 v[4:7], v[28:29], off
	global_load_dwordx4 v[0:3], v[28:29], off offset:256
	v_lshl_add_u64 v[118:119], s[10:11], 0, v[118:119]
	v_ffbh_u32_e32 v124, v117
	v_min_u32_e32 v124, 32, v124
	v_lshlrev_b32_e32 v120, 16, v108
	v_and_b32_e32 v121, 0xffff0000, v108
	v_lshlrev_b32_e32 v108, 16, v109
	v_and_b32_e32 v109, 0xffff0000, v109
	v_lshlrev_b32_e32 v122, 16, v110
	v_and_b32_e32 v123, 0xffff0000, v110
	v_lshlrev_b32_e32 v110, 16, v111
	v_and_b32_e32 v111, 0xffff0000, v111
	v_lshlrev_b64 v[116:117], v124, v[116:117]
	v_pk_fma_f32 v[94:95], v[94:95], s[18:19], v[108:109] op_sel_hi:[1,0,1]
	v_pk_fma_f32 v[92:93], v[92:93], s[18:19], v[120:121] op_sel_hi:[1,0,1]
	v_pk_fma_f32 v[108:109], v[90:91], s[18:19], v[110:111] op_sel_hi:[1,0,1]
	v_pk_fma_f32 v[110:111], v[88:89], s[18:19], v[122:123] op_sel_hi:[1,0,1]
	v_cvt_pk_bf16_f32 v88, v92, v93
	v_min_u32_e32 v116, 1, v116
	v_cvt_pk_bf16_f32 v89, v94, v95
	v_cvt_pk_bf16_f32 v90, v110, v111
	v_cvt_pk_bf16_f32 v91, v108, v109
	global_store_dwordx4 v[106:107], v[88:91], off
	v_sub_u32_e32 v120, 32, v124
	v_mul_f32_e32 v121, v93, v93
	v_or_b32_e32 v88, v117, v116
	v_cvt_f32_u32_e32 v88, v88
	v_mul_f32_e32 v122, v95, v95
	v_mul_f32_e32 v123, v111, v111
	v_fmac_f32_e32 v121, v92, v92
	v_ldexp_f32 v88, v88, v120
	v_fmamk_f32 v88, v88, 0x2f800000, v197
	v_rsq_f32_e32 v88, v88
	v_fmac_f32_e32 v122, v94, v94
	v_mul_f32_e32 v124, v109, v109
	v_fmac_f32_e32 v123, v110, v110
	v_add_f32_e32 v89, v121, v122
	v_fmac_f32_e32 v124, v108, v108
	v_add_f32_e32 v89, v123, v89
	v_mul_f32_e32 v117, 0x41fe0000, v88
	v_add_f32_e32 v116, v124, v89
	v_mul_f32_e32 v88, v117, v92
	v_mul_f32_e32 v89, v117, v93
	v_mul_f32_e32 v91, v117, v95
	v_mul_f32_e32 v93, v117, v111
	v_mul_f32_e32 v90, v117, v94
	v_mul_f32_e32 v92, v117, v110
	v_mul_f32_e32 v94, v117, v108
	v_mul_f32_e32 v95, v117, v109
	v_med3_f32 v88, v88, s53, v199
	v_med3_f32 v89, v89, s53, v199
	v_med3_f32 v91, v91, s53, v199
	v_med3_f32 v93, v93, s53, v199
	v_med3_f32 v90, v90, s53, v199
	v_med3_f32 v92, v92, s53, v199
	v_med3_f32 v94, v94, s53, v199
	v_med3_f32 v95, v95, s53, v199
	v_rndne_f32_e32 v88, v88
	v_rndne_f32_e32 v89, v89
	v_rndne_f32_e32 v91, v91
	v_rndne_f32_e32 v93, v93
	v_rndne_f32_e32 v90, v90
	v_rndne_f32_e32 v92, v92
	v_rndne_f32_e32 v94, v94
	v_rndne_f32_e32 v95, v95
	v_cvt_i32_f32_e32 v88, v88
	v_cvt_i32_f32_e32 v89, v89
	v_cvt_i32_f32_e32 v91, v91
	v_cvt_i32_f32_e32 v93, v93
	v_cvt_i32_f32_sdwa v90, v90 dst_sel:WORD_1 dst_unused:UNUSED_PAD src0_sel:DWORD
	v_cvt_i32_f32_e32 v92, v92
	v_cvt_i32_f32_sdwa v94, v94 dst_sel:WORD_1 dst_unused:UNUSED_PAD src0_sel:DWORD
	v_cvt_i32_f32_e32 v95, v95
	v_lshlrev_b32_e32 v89, 8, v89
	v_perm_b32 v88, v91, v88, s54
	v_lshlrev_b32_e32 v91, 8, v93
	v_and_b32_e32 v90, 0xff0000, v90
	v_and_b32_e32 v93, 0xff0000, v94
	v_perm_b32 v92, v95, v92, s54
	v_and_b32_e32 v89, 0xff00, v89
	v_and_b32_e32 v91, 0xff00, v91
	v_or3_b32 v88, v88, v89, v90
	v_or3_b32 v89, v92, v91, v93
	global_store_dwordx2 v[118:119], v[88:89], off
	v_lshlrev_b32_e32 v88, 16, v112
	v_and_b32_e32 v89, 0xffff0000, v112
	v_lshlrev_b32_e32 v90, 16, v113
	v_and_b32_e32 v91, 0xffff0000, v113
	v_lshlrev_b32_e32 v92, 16, v114
	v_and_b32_e32 v93, 0xffff0000, v114
	v_lshlrev_b32_e32 v94, 16, v115
	v_and_b32_e32 v95, 0xffff0000, v115
	v_pk_fma_f32 v[86:87], v[86:87], s[18:19], v[90:91] op_sel_hi:[1,0,1]
	v_pk_fma_f32 v[84:85], v[84:85], s[18:19], v[88:89] op_sel_hi:[1,0,1]
	v_pk_fma_f32 v[90:91], v[80:81], s[18:19], v[92:93] op_sel_hi:[1,0,1]
	v_cvt_pk_bf16_f32 v80, v84, v85
	v_cvt_pk_bf16_f32 v81, v86, v87
	v_pk_fma_f32 v[88:89], v[82:83], s[18:19], v[94:95] op_sel_hi:[1,0,1]
	v_cvt_pk_bf16_f32 v82, v90, v91
	s_nop 0
	v_cvt_pk_bf16_f32 v83, v88, v89
	global_store_dwordx4 v[106:107], v[80:83], off offset:256
	v_mul_f32_e32 v92, v117, v89
	s_nop 0
	v_mul_f32_e32 v81, v117, v85
	v_mul_f32_e32 v80, v117, v84
	v_mul_f32_e32 v82, v117, v86
	v_mul_f32_e32 v83, v117, v87
	v_med3_f32 v81, v81, s53, v199
	v_med3_f32 v80, v80, s53, v199
	v_rndne_f32_e32 v81, v81
	v_med3_f32 v82, v82, s53, v199
	v_med3_f32 v83, v83, s53, v199
	v_rndne_f32_e32 v80, v80
	v_cvt_i32_f32_e32 v81, v81
	v_rndne_f32_e32 v82, v82
	v_rndne_f32_e32 v83, v83
	v_cvt_i32_f32_e32 v80, v80
	v_cvt_i32_f32_sdwa v82, v82 dst_sel:WORD_1 dst_unused:UNUSED_PAD src0_sel:DWORD
	v_cvt_i32_f32_e32 v83, v83
	v_lshlrev_b32_e32 v81, 8, v81
	v_and_b32_e32 v81, 0xff00, v81
	v_and_b32_e32 v82, 0xff0000, v82
	v_perm_b32 v80, v83, v80, s54
	v_or3_b32 v82, v80, v81, v82
	v_mul_f32_e32 v81, v117, v91
	v_med3_f32 v81, v81, s53, v199
	v_rndne_f32_e32 v81, v81
	v_cvt_i32_f32_e32 v81, v81
	v_mul_f32_e32 v80, v117, v90
	v_med3_f32 v80, v80, s53, v199
	v_rndne_f32_e32 v80, v80
	v_mul_f32_e32 v83, v117, v88
	v_cvt_i32_f32_e32 v93, v80
	v_lshlrev_b32_e32 v80, 8, v81
	v_and_b32_e32 v94, 0xff00, v80
	v_med3_f32 v80, v83, s53, v199
	v_mul_f32_e32 v81, v85, v85
	v_mul_f32_e32 v83, v87, v87
	v_fmac_f32_e32 v81, v84, v84
	v_fmac_f32_e32 v83, v86, v86
	v_add_f32_e32 v81, v81, v83
	v_mul_f32_e32 v83, v91, v91
	v_fmac_f32_e32 v83, v90, v90
	v_add_f32_e32 v81, v83, v81
	v_mul_f32_e32 v83, v89, v89
	v_fmac_f32_e32 v83, v88, v88
	v_add_f32_e32 v81, v83, v81
	v_add_f32_e32 v81, v116, v81
	ds_bpermute_b32 v83, v144, v81
	v_rndne_f32_e32 v80, v80
	v_cvt_i32_f32_sdwa v84, v80 dst_sel:WORD_1 dst_unused:UNUSED_PAD src0_sel:DWORD
	v_med3_f32 v80, v92, s53, v199
	v_rndne_f32_e32 v80, v80
	v_cvt_i32_f32_e32 v85, v80
	s_waitcnt lgkmcnt(0)
	v_add_f32_e32 v80, v81, v83
	ds_bpermute_b32 v81, v145, v80
	v_and_b32_e32 v83, 0xff0000, v84
	v_perm_b32 v84, v85, v93, s54
	v_or3_b32 v83, v84, v94, v83
	global_store_dwordx2 v[118:119], v[82:83], off offset:128
	s_and_saveexec_b64 s[28:29], s[2:3]
	s_cbranch_execz .LBB0_1268
	s_waitcnt lgkmcnt(0)
	v_add_f32_e32 v80, v80, v81
	v_fma_f32 v80, v80, s55, 0.5
	v_trunc_f32_e32 v80, v80
	v_mul_f32_e32 v81, 0x2f800000, v80
	v_floor_f32_e32 v81, v81
	v_fmac_f32_e32 v80, 0xcf800000, v81
	v_cvt_u32_f32_e32 v80, v80
	v_cvt_u32_f32_e32 v81, v81
	v_lshl_add_u64 v[82:83], v[104:105], 3, s[8:9]
	global_atomic_add_x2 v[82:83], v[80:81], off
.LBB0_1268:
	s_or_b64 exec, exec, s[28:29]
	s_waitcnt lgkmcnt(0)
	v_mov_b32_e32 v80, v240
	v_mov_b32_e32 v81, v241
	v_lshlrev_b32_e32 v84, 16, v20
	v_and_b32_e32 v85, 0xffff0000, v20
	v_lshlrev_b32_e32 v88, 16, v16
	v_and_b32_e32 v89, 0xffff0000, v16
	v_lshlrev_b32_e32 v16, 16, v17
	v_and_b32_e32 v17, 0xffff0000, v17
	v_lshlrev_b32_e32 v20, 16, v21
	v_and_b32_e32 v21, 0xffff0000, v21
	v_lshlrev_b32_e32 v86, 16, v22
	v_and_b32_e32 v87, 0xffff0000, v22
	v_lshlrev_b32_e32 v22, 16, v23
	v_and_b32_e32 v23, 0xffff0000, v23
	v_lshlrev_b32_e32 v90, 16, v18
	v_and_b32_e32 v91, 0xffff0000, v18
	v_lshlrev_b32_e32 v18, 16, v19
	v_and_b32_e32 v19, 0xffff0000, v19
	v_pk_fma_f32 v[76:77], v[76:77], s[18:19], v[84:85] op_sel_hi:[1,0,1]
	v_pk_fma_f32 v[70:71], v[70:71], s[18:19], v[16:17] op_sel_hi:[1,0,1]
	v_cvt_pk_bf16_f32 v16, v76, v77
	v_pk_fma_f32 v[20:21], v[78:79], s[18:19], v[20:21] op_sel_hi:[1,0,1]
	v_pk_fma_f32 v[22:23], v[74:75], s[18:19], v[22:23] op_sel_hi:[1,0,1]
	v_pk_fma_f32 v[72:73], v[72:73], s[18:19], v[86:87] op_sel_hi:[1,0,1]
	v_pk_fma_f32 v[66:67], v[66:67], s[18:19], v[18:19] op_sel_hi:[1,0,1]
	v_cvt_pk_bf16_f32 v17, v20, v21
	v_cvt_pk_bf16_f32 v18, v72, v73
	v_cvt_pk_bf16_f32 v19, v22, v23
	global_store_dwordx4 v[102:103], v[16:19], off
	v_lshlrev_b64 v[82:83], 12, v[100:101]
	v_lshl_add_u64 v[82:83], v[82:83], 0, v[24:25]
	v_mul_f32_e32 v78, v77, v77
	v_mul_f32_e32 v79, v21, v21
	v_lshl_add_u64 v[74:75], s[10:11], 0, v[82:83]
	v_mul_f32_e32 v82, v73, v73
	v_fmac_f32_e32 v78, v76, v76
	v_fmac_f32_e32 v79, v20, v20
	v_mul_f32_e32 v83, v23, v23
	v_fmac_f32_e32 v82, v72, v72
	v_fmac_f32_e32 v83, v22, v22
	v_pk_fma_f32 v[68:69], v[68:69], s[18:19], v[88:89] op_sel_hi:[1,0,1]
	v_pk_fma_f32 v[64:65], v[64:65], s[18:19], v[90:91] op_sel_hi:[1,0,1]
	s_waitcnt vmcnt(6)
	v_ffbh_u32_e32 v16, v81
	v_min_u32_e32 v18, 32, v16
	v_lshlrev_b64 v[16:17], v18, v[80:81]
	v_min_u32_e32 v16, 1, v16
	v_or_b32_e32 v16, v17, v16
	v_cvt_f32_u32_e32 v16, v16
	v_sub_u32_e32 v17, 32, v18
	v_ldexp_f32 v16, v16, v17
	v_fmamk_f32 v16, v16, 0x2f800000, v197
	v_rsq_f32_e32 v16, v16
	v_add_f32_e32 v17, v78, v79
	v_add_f32_e32 v17, v82, v17
	v_add_f32_e32 v78, v83, v17
	v_mul_f32_e32 v79, 0x41fe0000, v16
	v_mul_f32_e32 v16, v76, v79
	v_mul_f32_e32 v17, v77, v79
	v_mul_f32_e32 v19, v21, v79
	v_mul_f32_e32 v21, v73, v79
	v_mul_f32_e32 v18, v20, v79
	v_mul_f32_e32 v20, v72, v79
	v_mul_f32_e32 v22, v22, v79
	v_mul_f32_e32 v23, v23, v79
	v_med3_f32 v16, v16, s53, v199
	v_med3_f32 v17, v17, s53, v199
	v_med3_f32 v19, v19, s53, v199
	v_med3_f32 v21, v21, s53, v199
	v_med3_f32 v18, v18, s53, v199
	v_med3_f32 v20, v20, s53, v199
	v_med3_f32 v22, v22, s53, v199
	v_med3_f32 v23, v23, s53, v199
	v_rndne_f32_e32 v16, v16
	v_rndne_f32_e32 v17, v17
	v_rndne_f32_e32 v19, v19
	v_rndne_f32_e32 v21, v21
	v_rndne_f32_e32 v18, v18
	v_rndne_f32_e32 v20, v20
	v_rndne_f32_e32 v22, v22
	v_rndne_f32_e32 v23, v23
	v_cvt_i32_f32_e32 v16, v16
	v_cvt_i32_f32_e32 v17, v17
	v_cvt_i32_f32_e32 v19, v19
	v_cvt_i32_f32_e32 v21, v21
	v_cvt_i32_f32_sdwa v18, v18 dst_sel:WORD_1 dst_unused:UNUSED_PAD src0_sel:DWORD
	v_cvt_i32_f32_e32 v20, v20
	v_cvt_i32_f32_sdwa v22, v22 dst_sel:WORD_1 dst_unused:UNUSED_PAD src0_sel:DWORD
	v_cvt_i32_f32_e32 v23, v23
	v_lshlrev_b32_e32 v17, 8, v17
	v_perm_b32 v16, v19, v16, s54
	v_lshlrev_b32_e32 v19, 8, v21
	v_and_b32_e32 v18, 0xff0000, v18
	v_and_b32_e32 v21, 0xff0000, v22
	v_perm_b32 v20, v23, v20, s54
	v_and_b32_e32 v17, 0xff00, v17
	v_and_b32_e32 v19, 0xff00, v19
	v_or3_b32 v16, v16, v17, v18
	v_or3_b32 v17, v20, v19, v21
	v_mul_f32_e32 v73, v69, v79
	global_store_dwordx2 v[74:75], v[16:17], off
	v_cvt_pk_bf16_f32 v16, v68, v69
	v_cvt_pk_bf16_f32 v17, v70, v71
	v_mul_f32_e32 v72, v68, v79
	v_mul_f32_e32 v76, v70, v79
	v_mul_f32_e32 v77, v71, v79
	v_cvt_pk_bf16_f32 v18, v64, v65
	v_cvt_pk_bf16_f32 v19, v66, v67
	global_store_dwordx4 v[102:103], v[16:19], off offset:256
	v_med3_f32 v72, v72, s53, v199
	v_mul_f32_e32 v20, v67, v79
	v_med3_f32 v17, v73, s53, v199
	v_rndne_f32_e32 v17, v17
	v_med3_f32 v18, v76, s53, v199
	v_med3_f32 v19, v77, s53, v199
	v_rndne_f32_e32 v16, v72
	v_cvt_i32_f32_e32 v17, v17
	v_rndne_f32_e32 v18, v18
	v_rndne_f32_e32 v19, v19
	v_cvt_i32_f32_e32 v16, v16
	v_cvt_i32_f32_sdwa v18, v18 dst_sel:WORD_1 dst_unused:UNUSED_PAD src0_sel:DWORD
	v_cvt_i32_f32_e32 v19, v19
	v_lshlrev_b32_e32 v17, 8, v17
	v_and_b32_e32 v17, 0xff00, v17
	v_and_b32_e32 v18, 0xff0000, v18
	v_perm_b32 v16, v19, v16, s54
	v_or3_b32 v18, v16, v17, v18
	v_mul_f32_e32 v17, v65, v79
	v_med3_f32 v17, v17, s53, v199
	v_rndne_f32_e32 v17, v17
	v_cvt_i32_f32_e32 v17, v17
	v_mul_f32_e32 v16, v64, v79
	v_med3_f32 v16, v16, s53, v199
	v_rndne_f32_e32 v16, v16
	v_mul_f32_e32 v19, v66, v79
	v_cvt_i32_f32_e32 v21, v16
	v_lshlrev_b32_e32 v16, 8, v17
	v_and_b32_e32 v22, 0xff00, v16
	v_med3_f32 v16, v19, s53, v199
	v_mul_f32_e32 v17, v69, v69
	v_mul_f32_e32 v19, v71, v71
	v_fmac_f32_e32 v17, v68, v68
	v_fmac_f32_e32 v19, v70, v70
	v_add_f32_e32 v17, v17, v19
	v_mul_f32_e32 v19, v65, v65
	v_fmac_f32_e32 v19, v64, v64
	v_add_f32_e32 v17, v19, v17
	v_mul_f32_e32 v19, v67, v67
	v_fmac_f32_e32 v19, v66, v66
	v_add_f32_e32 v17, v19, v17
	v_add_f32_e32 v17, v78, v17
	ds_bpermute_b32 v19, v144, v17
	v_rndne_f32_e32 v16, v16
	v_cvt_i32_f32_sdwa v23, v16 dst_sel:WORD_1 dst_unused:UNUSED_PAD src0_sel:DWORD
	v_med3_f32 v16, v20, s53, v199
	v_rndne_f32_e32 v16, v16
	v_cvt_i32_f32_e32 v20, v16
	s_waitcnt lgkmcnt(0)
	v_add_f32_e32 v16, v17, v19
	ds_bpermute_b32 v17, v145, v16
	v_and_b32_e32 v19, 0xff0000, v23
	v_perm_b32 v20, v20, v21, s54
	v_or3_b32 v19, v20, v22, v19
	global_store_dwordx2 v[74:75], v[18:19], off offset:128
	s_and_saveexec_b64 s[28:29], s[2:3]
	s_cbranch_execz .LBB0_1270
	s_waitcnt lgkmcnt(0)
	v_add_f32_e32 v16, v16, v17
	v_fma_f32 v16, v16, s55, 0.5
	v_trunc_f32_e32 v16, v16
	v_mul_f32_e32 v17, 0x2f800000, v16
	v_floor_f32_e32 v17, v17
	v_fmac_f32_e32 v16, 0xcf800000, v17
	v_cvt_u32_f32_e32 v16, v16
	v_cvt_u32_f32_e32 v17, v17
	v_lshl_add_u64 v[18:19], v[100:101], 3, s[8:9]
	global_atomic_add_x2 v[18:19], v[16:17], off
.LBB0_1270:
	s_or_b64 exec, exec, s[28:29]
	s_waitcnt lgkmcnt(0)
	v_mov_b32_e32 v16, v242
	v_mov_b32_e32 v17, v243
	v_lshlrev_b32_e32 v20, 16, v12
	v_and_b32_e32 v21, 0xffff0000, v12
	v_lshlrev_b32_e32 v64, 16, v8
	v_and_b32_e32 v65, 0xffff0000, v8
	v_lshlrev_b32_e32 v8, 16, v9
	v_and_b32_e32 v9, 0xffff0000, v9
	v_lshlrev_b32_e32 v12, 16, v13
	v_and_b32_e32 v13, 0xffff0000, v13
	v_lshlrev_b32_e32 v22, 16, v14
	v_and_b32_e32 v23, 0xffff0000, v14
	v_lshlrev_b32_e32 v14, 16, v15
	v_and_b32_e32 v15, 0xffff0000, v15
	v_lshlrev_b32_e32 v66, 16, v10
	v_and_b32_e32 v67, 0xffff0000, v10
	v_lshlrev_b32_e32 v10, 16, v11
	v_and_b32_e32 v11, 0xffff0000, v11
	v_pk_fma_f32 v[20:21], v[60:61], s[18:19], v[20:21] op_sel_hi:[1,0,1]
	v_pk_fma_f32 v[54:55], v[54:55], s[18:19], v[8:9] op_sel_hi:[1,0,1]
	v_cvt_pk_bf16_f32 v8, v20, v21
	v_pk_fma_f32 v[12:13], v[62:63], s[18:19], v[12:13] op_sel_hi:[1,0,1]
	v_pk_fma_f32 v[14:15], v[58:59], s[18:19], v[14:15] op_sel_hi:[1,0,1]
	v_pk_fma_f32 v[22:23], v[56:57], s[18:19], v[22:23] op_sel_hi:[1,0,1]
	v_pk_fma_f32 v[50:51], v[50:51], s[18:19], v[10:11] op_sel_hi:[1,0,1]
	v_cvt_pk_bf16_f32 v9, v12, v13
	v_cvt_pk_bf16_f32 v10, v22, v23
	v_cvt_pk_bf16_f32 v11, v14, v15
	global_store_dwordx4 v[98:99], v[8:11], off
	v_mul_f32_e32 v56, v21, v21
	v_mul_f32_e32 v57, v13, v13
	v_mul_f32_e32 v58, v23, v23
	v_fmac_f32_e32 v56, v20, v20
	v_fmac_f32_e32 v57, v12, v12
	v_mul_f32_e32 v59, v15, v15
	v_fmac_f32_e32 v58, v22, v22
	v_fmac_f32_e32 v59, v14, v14
	v_lshlrev_b64 v[18:19], 12, v[96:97]
	v_lshl_add_u64 v[18:19], v[18:19], 0, v[24:25]
	v_pk_fma_f32 v[52:53], v[52:53], s[18:19], v[64:65] op_sel_hi:[1,0,1]
	v_lshl_add_u64 v[18:19], s[10:11], 0, v[18:19]
	v_pk_fma_f32 v[48:49], v[48:49], s[18:19], v[66:67] op_sel_hi:[1,0,1]
	s_waitcnt vmcnt(11)
	v_ffbh_u32_e32 v8, v17
	v_min_u32_e32 v10, 32, v8
	v_lshlrev_b64 v[8:9], v10, v[16:17]
	v_min_u32_e32 v8, 1, v8
	v_or_b32_e32 v8, v9, v8
	v_cvt_f32_u32_e32 v8, v8
	v_sub_u32_e32 v9, 32, v10
	v_ldexp_f32 v8, v8, v9
	v_fmamk_f32 v8, v8, 0x2f800000, v197
	v_rsq_f32_e32 v8, v8
	v_add_f32_e32 v9, v56, v57
	v_add_f32_e32 v9, v58, v9
	v_add_f32_e32 v16, v59, v9
	v_mul_f32_e32 v17, 0x41fe0000, v8
	v_mul_f32_e32 v8, v20, v17
	v_mul_f32_e32 v9, v21, v17
	v_mul_f32_e32 v11, v13, v17
	v_mul_f32_e32 v13, v23, v17
	v_mul_f32_e32 v10, v12, v17
	v_mul_f32_e32 v12, v22, v17
	v_mul_f32_e32 v14, v14, v17
	v_mul_f32_e32 v15, v15, v17
	v_med3_f32 v8, v8, s53, v199
	v_med3_f32 v9, v9, s53, v199
	v_med3_f32 v11, v11, s53, v199
	v_med3_f32 v13, v13, s53, v199
	v_med3_f32 v10, v10, s53, v199
	v_med3_f32 v12, v12, s53, v199
	v_med3_f32 v14, v14, s53, v199
	v_med3_f32 v15, v15, s53, v199
	v_rndne_f32_e32 v8, v8
	v_rndne_f32_e32 v9, v9
	v_rndne_f32_e32 v11, v11
	v_rndne_f32_e32 v13, v13
	v_rndne_f32_e32 v10, v10
	v_rndne_f32_e32 v12, v12
	v_rndne_f32_e32 v14, v14
	v_rndne_f32_e32 v15, v15
	v_cvt_i32_f32_e32 v8, v8
	v_cvt_i32_f32_e32 v9, v9
	v_cvt_i32_f32_e32 v11, v11
	v_cvt_i32_f32_e32 v13, v13
	v_cvt_i32_f32_sdwa v10, v10 dst_sel:WORD_1 dst_unused:UNUSED_PAD src0_sel:DWORD
	v_cvt_i32_f32_e32 v12, v12
	v_cvt_i32_f32_sdwa v14, v14 dst_sel:WORD_1 dst_unused:UNUSED_PAD src0_sel:DWORD
	v_cvt_i32_f32_e32 v15, v15
	v_lshlrev_b32_e32 v9, 8, v9
	v_perm_b32 v8, v11, v8, s54
	v_lshlrev_b32_e32 v11, 8, v13
	v_and_b32_e32 v10, 0xff0000, v10
	v_and_b32_e32 v13, 0xff0000, v14
	v_perm_b32 v12, v15, v12, s54
	v_and_b32_e32 v9, 0xff00, v9
	v_and_b32_e32 v11, 0xff00, v11
	v_or3_b32 v8, v8, v9, v10
	v_or3_b32 v9, v12, v11, v13
	v_mul_f32_e32 v21, v53, v17
	global_store_dwordx2 v[18:19], v[8:9], off
	v_cvt_pk_bf16_f32 v8, v52, v53
	v_cvt_pk_bf16_f32 v9, v54, v55
	v_mul_f32_e32 v20, v52, v17
	v_mul_f32_e32 v22, v54, v17
	v_mul_f32_e32 v23, v55, v17
	v_cvt_pk_bf16_f32 v10, v48, v49
	v_cvt_pk_bf16_f32 v11, v50, v51
	global_store_dwordx4 v[98:99], v[8:11], off offset:256
	v_med3_f32 v20, v20, s53, v199
	v_mul_f32_e32 v12, v51, v17
	v_med3_f32 v9, v21, s53, v199
	v_rndne_f32_e32 v9, v9
	v_med3_f32 v10, v22, s53, v199
	v_med3_f32 v11, v23, s53, v199
	v_rndne_f32_e32 v8, v20
	v_cvt_i32_f32_e32 v9, v9
	v_rndne_f32_e32 v10, v10
	v_rndne_f32_e32 v11, v11
	v_cvt_i32_f32_e32 v8, v8
	v_cvt_i32_f32_sdwa v10, v10 dst_sel:WORD_1 dst_unused:UNUSED_PAD src0_sel:DWORD
	v_cvt_i32_f32_e32 v11, v11
	v_lshlrev_b32_e32 v9, 8, v9
	v_and_b32_e32 v9, 0xff00, v9
	v_and_b32_e32 v10, 0xff0000, v10
	v_perm_b32 v8, v11, v8, s54
	v_or3_b32 v10, v8, v9, v10
	v_mul_f32_e32 v9, v49, v17
	v_med3_f32 v9, v9, s53, v199
	v_rndne_f32_e32 v9, v9
	v_cvt_i32_f32_e32 v9, v9
	v_mul_f32_e32 v8, v48, v17
	v_med3_f32 v8, v8, s53, v199
	v_rndne_f32_e32 v8, v8
	v_mul_f32_e32 v11, v50, v17
	v_cvt_i32_f32_e32 v13, v8
	v_lshlrev_b32_e32 v8, 8, v9
	v_and_b32_e32 v14, 0xff00, v8
	v_med3_f32 v8, v11, s53, v199
	v_mul_f32_e32 v9, v53, v53
	v_mul_f32_e32 v11, v55, v55
	v_fmac_f32_e32 v9, v52, v52
	v_fmac_f32_e32 v11, v54, v54
	v_add_f32_e32 v9, v9, v11
	v_mul_f32_e32 v11, v49, v49
	v_fmac_f32_e32 v11, v48, v48
	v_add_f32_e32 v9, v11, v9
	v_mul_f32_e32 v11, v51, v51
	v_fmac_f32_e32 v11, v50, v50
	v_add_f32_e32 v9, v11, v9
	v_add_f32_e32 v9, v16, v9
	ds_bpermute_b32 v11, v144, v9
	v_rndne_f32_e32 v8, v8
	v_cvt_i32_f32_sdwa v15, v8 dst_sel:WORD_1 dst_unused:UNUSED_PAD src0_sel:DWORD
	v_med3_f32 v8, v12, s53, v199
	v_rndne_f32_e32 v8, v8
	v_cvt_i32_f32_e32 v12, v8
	s_waitcnt lgkmcnt(0)
	v_add_f32_e32 v8, v9, v11
	ds_bpermute_b32 v9, v145, v8
	v_and_b32_e32 v11, 0xff0000, v15
	v_perm_b32 v12, v12, v13, s54
	v_or3_b32 v11, v12, v14, v11
	global_store_dwordx2 v[18:19], v[10:11], off offset:128
	s_and_saveexec_b64 s[28:29], s[2:3]
	s_cbranch_execz .LBB0_1272
	s_waitcnt lgkmcnt(0)
	v_add_f32_e32 v8, v8, v9
	v_fma_f32 v8, v8, s55, 0.5
	v_trunc_f32_e32 v8, v8
	v_mul_f32_e32 v9, 0x2f800000, v8
	v_floor_f32_e32 v9, v9
	v_fmac_f32_e32 v8, 0xcf800000, v9
	v_cvt_u32_f32_e32 v8, v8
	v_cvt_u32_f32_e32 v9, v9
	v_lshl_add_u64 v[10:11], v[96:97], 3, s[8:9]
	global_atomic_add_x2 v[10:11], v[8:9], off
.LBB0_1272:
	s_or_b64 exec, exec, s[28:29]
	s_waitcnt lgkmcnt(0)
	v_mov_b32_e32 v8, v244
	v_mov_b32_e32 v9, v245
	v_lshlrev_b32_e32 v12, 16, v4
	v_and_b32_e32 v13, 0xffff0000, v4
	v_lshlrev_b32_e32 v16, 16, v0
	v_and_b32_e32 v17, 0xffff0000, v0
	v_lshlrev_b32_e32 v0, 16, v1
	v_and_b32_e32 v1, 0xffff0000, v1
	v_lshlrev_b32_e32 v4, 16, v5
	v_and_b32_e32 v5, 0xffff0000, v5
	v_lshlrev_b32_e32 v14, 16, v6
	v_and_b32_e32 v15, 0xffff0000, v6
	v_lshlrev_b32_e32 v6, 16, v7
	v_and_b32_e32 v7, 0xffff0000, v7
	v_lshlrev_b32_e32 v18, 16, v2
	v_and_b32_e32 v19, 0xffff0000, v2
	v_lshlrev_b32_e32 v2, 16, v3
	v_and_b32_e32 v3, 0xffff0000, v3
	v_pk_fma_f32 v[12:13], v[44:45], s[18:19], v[12:13] op_sel_hi:[1,0,1]
	v_pk_fma_f32 v[20:21], v[38:39], s[18:19], v[0:1] op_sel_hi:[1,0,1]
	v_cvt_pk_bf16_f32 v0, v12, v13
	v_pk_fma_f32 v[4:5], v[46:47], s[18:19], v[4:5] op_sel_hi:[1,0,1]
	v_pk_fma_f32 v[6:7], v[42:43], s[18:19], v[6:7] op_sel_hi:[1,0,1]
	v_pk_fma_f32 v[14:15], v[40:41], s[18:19], v[14:15] op_sel_hi:[1,0,1]
	v_pk_fma_f32 v[22:23], v[34:35], s[18:19], v[2:3] op_sel_hi:[1,0,1]
	v_cvt_pk_bf16_f32 v1, v4, v5
	v_cvt_pk_bf16_f32 v2, v14, v15
	v_cvt_pk_bf16_f32 v3, v6, v7
	global_store_dwordx4 v[28:29], v[0:3], off
	v_lshlrev_b64 v[10:11], 12, v[30:31]
	v_lshl_add_u64 v[10:11], v[10:11], 0, v[24:25]
	v_mul_f32_e32 v24, v13, v13
	v_mul_f32_e32 v25, v5, v5
	v_mul_f32_e32 v26, v15, v15
	v_fmac_f32_e32 v24, v12, v12
	v_fmac_f32_e32 v25, v4, v4
	v_mul_f32_e32 v27, v7, v7
	v_fmac_f32_e32 v26, v14, v14
	v_fmac_f32_e32 v27, v6, v6
	v_pk_fma_f32 v[16:17], v[36:37], s[18:19], v[16:17] op_sel_hi:[1,0,1]
	v_lshl_add_u64 v[10:11], s[10:11], 0, v[10:11]
	v_pk_fma_f32 v[18:19], v[32:33], s[18:19], v[18:19] op_sel_hi:[1,0,1]
	s_waitcnt vmcnt(16)
	v_ffbh_u32_e32 v0, v9
	v_min_u32_e32 v2, 32, v0
	v_lshlrev_b64 v[0:1], v2, v[8:9]
	v_min_u32_e32 v0, 1, v0
	v_or_b32_e32 v0, v1, v0
	v_cvt_f32_u32_e32 v0, v0
	v_sub_u32_e32 v1, 32, v2
	v_ldexp_f32 v0, v0, v1
	v_fmamk_f32 v0, v0, 0x2f800000, v197
	v_rsq_f32_e32 v0, v0
	v_add_f32_e32 v1, v24, v25
	v_add_f32_e32 v1, v26, v1
	v_add_f32_e32 v8, v27, v1
	v_mul_f32_e32 v9, 0x41fe0000, v0
	v_mul_f32_e32 v0, v12, v9
	v_mul_f32_e32 v1, v13, v9
	v_mul_f32_e32 v3, v5, v9
	v_mul_f32_e32 v5, v15, v9
	v_mul_f32_e32 v2, v4, v9
	v_mul_f32_e32 v4, v14, v9
	v_mul_f32_e32 v6, v6, v9
	v_mul_f32_e32 v7, v7, v9
	v_med3_f32 v0, v0, s53, v199
	v_med3_f32 v1, v1, s53, v199
	v_med3_f32 v3, v3, s53, v199
	v_med3_f32 v5, v5, s53, v199
	v_med3_f32 v2, v2, s53, v199
	v_med3_f32 v4, v4, s53, v199
	v_med3_f32 v6, v6, s53, v199
	v_med3_f32 v7, v7, s53, v199
	v_rndne_f32_e32 v0, v0
	v_rndne_f32_e32 v1, v1
	v_rndne_f32_e32 v3, v3
	v_rndne_f32_e32 v5, v5
	v_rndne_f32_e32 v2, v2
	v_rndne_f32_e32 v4, v4
	v_rndne_f32_e32 v6, v6
	v_rndne_f32_e32 v7, v7
	v_cvt_i32_f32_e32 v0, v0
	v_cvt_i32_f32_e32 v1, v1
	v_cvt_i32_f32_e32 v3, v3
	v_cvt_i32_f32_e32 v5, v5
	v_cvt_i32_f32_sdwa v2, v2 dst_sel:WORD_1 dst_unused:UNUSED_PAD src0_sel:DWORD
	v_cvt_i32_f32_e32 v4, v4
	v_cvt_i32_f32_sdwa v6, v6 dst_sel:WORD_1 dst_unused:UNUSED_PAD src0_sel:DWORD
	v_cvt_i32_f32_e32 v7, v7
	v_lshlrev_b32_e32 v1, 8, v1
	v_perm_b32 v0, v3, v0, s54
	v_lshlrev_b32_e32 v3, 8, v5
	v_and_b32_e32 v2, 0xff0000, v2
	v_and_b32_e32 v5, 0xff0000, v6
	v_perm_b32 v4, v7, v4, s54
	v_and_b32_e32 v1, 0xff00, v1
	v_and_b32_e32 v3, 0xff00, v3
	v_or3_b32 v0, v0, v1, v2
	v_or3_b32 v1, v4, v3, v5
	v_mul_f32_e32 v13, v17, v9
	global_store_dwordx2 v[10:11], v[0:1], off
	v_cvt_pk_bf16_f32 v0, v16, v17
	v_cvt_pk_bf16_f32 v1, v20, v21
	v_mul_f32_e32 v12, v16, v9
	v_mul_f32_e32 v14, v20, v9
	v_mul_f32_e32 v15, v21, v9
	v_cvt_pk_bf16_f32 v2, v18, v19
	v_cvt_pk_bf16_f32 v3, v22, v23
	global_store_dwordx4 v[28:29], v[0:3], off offset:256
	v_med3_f32 v12, v12, s53, v199
	v_mul_f32_e32 v4, v23, v9
	v_med3_f32 v1, v13, s53, v199
	v_rndne_f32_e32 v1, v1
	v_med3_f32 v2, v14, s53, v199
	v_med3_f32 v3, v15, s53, v199
	v_rndne_f32_e32 v0, v12
	v_cvt_i32_f32_e32 v1, v1
	v_rndne_f32_e32 v2, v2
	v_rndne_f32_e32 v3, v3
	v_cvt_i32_f32_e32 v0, v0
	v_cvt_i32_f32_sdwa v2, v2 dst_sel:WORD_1 dst_unused:UNUSED_PAD src0_sel:DWORD
	v_cvt_i32_f32_e32 v3, v3
	v_lshlrev_b32_e32 v1, 8, v1
	v_and_b32_e32 v1, 0xff00, v1
	v_and_b32_e32 v2, 0xff0000, v2
	v_perm_b32 v0, v3, v0, s54
	v_or3_b32 v2, v0, v1, v2
	v_mul_f32_e32 v1, v19, v9
	v_med3_f32 v1, v1, s53, v199
	v_rndne_f32_e32 v1, v1
	v_cvt_i32_f32_e32 v1, v1
	v_mul_f32_e32 v0, v18, v9
	v_med3_f32 v0, v0, s53, v199
	v_rndne_f32_e32 v0, v0
	v_mul_f32_e32 v3, v22, v9
	v_cvt_i32_f32_e32 v5, v0
	v_lshlrev_b32_e32 v0, 8, v1
	v_and_b32_e32 v6, 0xff00, v0
	v_med3_f32 v0, v3, s53, v199
	v_mul_f32_e32 v1, v17, v17
	v_mul_f32_e32 v3, v21, v21
	v_fmac_f32_e32 v1, v16, v16
	v_fmac_f32_e32 v3, v20, v20
	v_add_f32_e32 v1, v1, v3
	v_mul_f32_e32 v3, v19, v19
	v_fmac_f32_e32 v3, v18, v18
	v_add_f32_e32 v1, v3, v1
	v_mul_f32_e32 v3, v23, v23
	v_fmac_f32_e32 v3, v22, v22
	v_add_f32_e32 v1, v3, v1
	v_add_f32_e32 v1, v8, v1
	ds_bpermute_b32 v3, v144, v1
	v_rndne_f32_e32 v0, v0
	v_cvt_i32_f32_sdwa v7, v0 dst_sel:WORD_1 dst_unused:UNUSED_PAD src0_sel:DWORD
	v_med3_f32 v0, v4, s53, v199
	v_rndne_f32_e32 v0, v0
	v_cvt_i32_f32_e32 v4, v0
	s_waitcnt lgkmcnt(0)
	v_add_f32_e32 v0, v1, v3
	ds_bpermute_b32 v1, v145, v0
	v_and_b32_e32 v3, 0xff0000, v7
	v_perm_b32 v4, v4, v5, s54
	v_or3_b32 v3, v4, v6, v3
	global_store_dwordx2 v[10:11], v[2:3], off offset:128
	s_and_saveexec_b64 s[28:29], s[2:3]
	s_cbranch_execz .LBB0_1274
	s_waitcnt lgkmcnt(0)
	v_add_f32_e32 v0, v0, v1
	v_fma_f32 v0, v0, s55, 0.5
	v_trunc_f32_e32 v0, v0
	v_mul_f32_e32 v1, 0x2f800000, v0
	v_floor_f32_e32 v1, v1
	v_fmac_f32_e32 v0, 0xcf800000, v1
	v_cvt_u32_f32_e32 v0, v0
	v_cvt_u32_f32_e32 v1, v1
	v_lshl_add_u64 v[2:3], v[30:31], 3, s[8:9]
	global_atomic_add_x2 v[2:3], v[0:1], off
